# v9 plus GEMM main loops: redundant post-barrier lgkmcnt(0) removed, adjacent s_setprio 0/1 pairs removed, vmcnt(8)+lgkmcnt(0) merged into one wait
# speedup vs baseline: 1.0156x; 1.0115x over previous
; #define PG8_STAGE(bufoff, gbase, voff) do { _Pragma("unroll") for (int _i = 0; _i < 2; ++_i) \
;         __builtin_amdgcn_global_load_lds((const unsigned*)((const char*)(gbase) + (voff)[_i]), (LAS unsigned*)(lds + (bufoff) + ldsw + _i * 8192), 16, 0, 0); } while (0)
; #define PG8_LDA(dst, b, h) do { _Pragma("unroll") for (int m = 0; m < 4; ++m) _Pragma("unroll") for (int k = 0; k < 2; ++k) dst[m][k] = *(const LAS bf16x8*)(lds + PG8_SA(b, h) + aoff + m * 2048 + k * 1024); } while (0)
; #define PG8_LDB(dst, b, h) do { _Pragma("unroll") for (int n = 0; n < 2; ++n) _Pragma("unroll") for (int k = 0; k < 2; ++k) dst[n][k] = *(const LAS bf16x8*)(lds + PG8_SB(b, h) + boff + n * 2048 + k * 1024); } while (0)
; #define PG8_MMA(ai, bj, At, Bt) do { __builtin_amdgcn_s_setprio(1); _Pragma("unroll") for (int m = 0; m < 4; ++m) _Pragma("unroll") for (int n = 0; n < 2; ++n) _Pragma("unroll") for (int k = 0; k < 2; ++k) \
;         acc[ai][bj][m][n] = __builtin_amdgcn_mfma_f32_16x16x32_bf16(Bt[n][k], At[m][k], acc[ai][bj][m][n], 0, 0, 0); __builtin_amdgcn_s_setprio(0); } while (0)
; #define PG8_WAIT_V(n) asm volatile("s_waitcnt vmcnt(" #n ")" ::: "memory")
; #define PG8_WAIT_L(n) asm volatile("s_waitcnt lgkmcnt(" #n ")" ::: "memory")
; #define PG8_BAR __builtin_amdgcn_s_barrier()
; #define PG8_SCHED __builtin_amdgcn_sched_barrier(0)
; template <class Epi, bool ALIGN_EPI = true>
; __device__ __forceinline__ void gemm_phase(LAS unsigned char* lds, const Gemm g, const StaticOrder& S, const Epi& E, int wave_k) {
;     ...
;             const char* a1 = cA + (size_t)(t + 1) * kstep;
;             const char* a2 = last ? nA : cA + (size_t)(t + 2) * kstep; const char* b2 = last ? nB : cB + (size_t)(t + 2) * kstep;
;             const char* a3 = a2 + kstep; const char* b3 = b2 + kstep;
;             PG8_LDB(B0, 0, 0); PG8_LDB(B1, 0, 1); PG8_SCHED; PG8_LDA(At, 0, 0); PG8_STAGE(PG8_SA(1, 1), a1 + hstepA, voffA);
;             PG8_WAIT_V(8); PG8_WAIT_L(0); PG8_BAR; PG8_MMA(0, 0, At, B0); PG8_MMA(0, 1, At, B1); PG8_BAR; PG8_SCHED;
;             PG8_LDA(At, 0, 1); PG8_STAGE(PG8_SB(0, 0), b2, voffB); PG8_STAGE(PG8_SB(0, 1), b2 + hstepB, voffB); PG8_STAGE(PG8_SA(0, 0), a2, voffA);
;             PG8_WAIT_V(8); PG8_WAIT_L(0); PG8_BAR; PG8_MMA(1, 0, At, B0); PG8_MMA(1, 1, At, B1); PG8_BAR; PG8_SCHED;
.LBB0_81:
	s_add_u32 s16, s2, 0xfffc0080
	s_addc_u32 s17, s3, -1
	s_add_i32 s65, 0, 0x10000
	s_cmp_eq_u32 s64, 12
	s_cselect_b32 s19, s42, s17
	s_cselect_b32 s18, s43, s16
	s_cselect_b32 s17, s49, s63
	s_cselect_b32 s16, s51, s62
	s_add_i32 s68, 0, 0x14000
	v_add_u32_e32 v150, s65, v157
	v_add_u32_e32 v154, s68, v157
	ds_read_b128 v[138:141], v150
	ds_read_b128 v[142:145], v150 offset:1024
	ds_read_b128 v[146:149], v150 offset:2048
	ds_read_b128 v[150:153], v150 offset:3072
	ds_read_b128 v[162:165], v154
	ds_read_b128 v[166:169], v154 offset:1024
	ds_read_b128 v[170:173], v154 offset:2048
	ds_read_b128 v[174:177], v154 offset:3072
	s_add_i32 m0, s35, 0xc000
	ds_read_b128 v[178:181], v159
	ds_read_b128 v[182:185], v159 offset:1024
	ds_read_b128 v[186:189], v159 offset:2048
	ds_read_b128 v[190:193], v159 offset:3072
	ds_read_b128 v[194:197], v159 offset:4096
	ds_read_b128 v[198:201], v159 offset:5120
	ds_read_b128 v[202:205], v159 offset:6144
	ds_read_b128 v[206:209], v159 offset:7168
	global_load_lds_dwordx4 v134, s[2:3]
	s_add_i32 m0, s35, 0xe000
	s_nop 0
	global_load_lds_dwordx4 v136, s[2:3]
	s_waitcnt vmcnt(8) lgkmcnt(0)
	s_barrier
	s_setprio 1
	v_mfma_f32_16x16x32_bf16 v[124:127], v[138:141], v[178:181], v[124:127]
	v_mfma_f32_16x16x32_bf16 v[120:123], v[146:149], v[178:181], v[120:123]
	v_mfma_f32_16x16x32_bf16 v[108:111], v[138:141], v[186:189], v[108:111]
	v_mfma_f32_16x16x32_bf16 v[100:103], v[146:149], v[186:189], v[100:103]
	v_mfma_f32_16x16x32_bf16 v[92:95], v[138:141], v[194:197], v[92:95]
	v_mfma_f32_16x16x32_bf16 v[84:87], v[146:149], v[194:197], v[84:87]
	v_mfma_f32_16x16x32_bf16 v[76:79], v[138:141], v[202:205], v[76:79]
	v_mfma_f32_16x16x32_bf16 v[68:71], v[146:149], v[202:205], v[68:71]
	v_mfma_f32_16x16x32_bf16 v[124:127], v[142:145], v[182:185], v[124:127]
	v_mfma_f32_16x16x32_bf16 v[120:123], v[150:153], v[182:185], v[120:123]
	v_mfma_f32_16x16x32_bf16 v[108:111], v[142:145], v[190:193], v[108:111]
	v_mfma_f32_16x16x32_bf16 v[100:103], v[150:153], v[190:193], v[100:103]
	v_mfma_f32_16x16x32_bf16 v[92:95], v[142:145], v[198:201], v[92:95]
	v_mfma_f32_16x16x32_bf16 v[84:87], v[150:153], v[198:201], v[84:87]
	v_mfma_f32_16x16x32_bf16 v[76:79], v[142:145], v[206:209], v[76:79]
	v_mfma_f32_16x16x32_bf16 v[68:71], v[150:153], v[206:209], v[68:71]
	v_mfma_f32_16x16x32_bf16 v[116:119], v[162:165], v[178:181], v[116:119]
	v_mfma_f32_16x16x32_bf16 v[112:115], v[170:173], v[178:181], v[112:115]
	v_mfma_f32_16x16x32_bf16 v[104:107], v[162:165], v[186:189], v[104:107]
	v_mfma_f32_16x16x32_bf16 v[96:99], v[170:173], v[186:189], v[96:99]
	v_mfma_f32_16x16x32_bf16 v[88:91], v[162:165], v[194:197], v[88:91]
	v_mfma_f32_16x16x32_bf16 v[80:83], v[170:173], v[194:197], v[80:83]
	v_mfma_f32_16x16x32_bf16 v[72:75], v[162:165], v[202:205], v[72:75]
	v_mfma_f32_16x16x32_bf16 v[64:67], v[170:173], v[202:205], v[64:67]
	v_mfma_f32_16x16x32_bf16 v[116:119], v[166:169], v[182:185], v[116:119]
	v_mfma_f32_16x16x32_bf16 v[112:115], v[174:177], v[182:185], v[112:115]
	v_mfma_f32_16x16x32_bf16 v[104:107], v[166:169], v[190:193], v[104:107]
	v_mfma_f32_16x16x32_bf16 v[96:99], v[174:177], v[190:193], v[96:99]
	v_mfma_f32_16x16x32_bf16 v[88:91], v[166:169], v[198:201], v[88:91]
	v_mfma_f32_16x16x32_bf16 v[80:83], v[174:177], v[198:201], v[80:83]
	v_mfma_f32_16x16x32_bf16 v[72:75], v[166:169], v[206:209], v[72:75]
	v_mfma_f32_16x16x32_bf16 v[64:67], v[174:177], v[206:209], v[64:67]
	s_setprio 0
	s_barrier
	s_add_i32 s65, s65, s29
	v_lshl_add_u64 v[154:155], s[16:17], 0, v[160:161]
	s_mov_b32 m0, s65
	ds_read_b128 v[178:181], v159 offset:16384
	ds_read_b128 v[182:185], v159 offset:17408
	ds_read_b128 v[186:189], v159 offset:18432
	ds_read_b128 v[190:193], v159 offset:19456
	ds_read_b128 v[194:197], v159 offset:20480
	ds_read_b128 v[198:201], v159 offset:21504
	ds_read_b128 v[202:205], v159 offset:22528
	ds_read_b128 v[206:209], v159 offset:23552
	global_load_lds_dwordx4 v[154:155], off
	s_add_i32 m0, s65, 0x2000
	s_add_u32 s66, s16, 0x40000
	v_lshl_add_u64 v[210:211], s[16:17], 0, v[128:129]
	s_addc_u32 s67, s17, 0
	s_add_i32 s65, s68, s29
	global_load_lds_dwordx4 v[210:211], off
	s_mov_b32 m0, s65
	v_lshl_add_u64 v[218:219], s[18:19], 0, v[130:131]
	global_load_lds_dwordx4 v160, s[66:67]
	s_add_i32 m0, s65, 0x2000
	s_nop 0
	global_load_lds_dwordx4 v128, s[66:67]
	v_lshl_add_u64 v[212:213], s[18:19], 0, v[132:133]
	s_mov_b32 m0, s35
	s_nop 0
	global_load_lds_dwordx4 v[212:213], off
	s_mov_b32 m0, s56
	s_nop 0
	global_load_lds_dwordx4 v[218:219], off
	s_waitcnt vmcnt(8) lgkmcnt(0)
	s_barrier
; #define PG8_STAGE(bufoff, gbase, voff) do { _Pragma("unroll") for (int _i = 0; _i < 2; ++_i) \
;         __builtin_amdgcn_global_load_lds((const unsigned*)((const char*)(gbase) + (voff)[_i]), (LAS unsigned*)(lds + (bufoff) + ldsw + _i * 8192), 16, 0, 0); } while (0)
; #define PG8_LDA(dst, b, h) do { _Pragma("unroll") for (int m = 0; m < 4; ++m) _Pragma("unroll") for (int k = 0; k < 2; ++k) dst[m][k] = *(const LAS bf16x8*)(lds + PG8_SA(b, h) + aoff + m * 2048 + k * 1024); } while (0)
; #define PG8_LDB(dst, b, h) do { _Pragma("unroll") for (int n = 0; n < 2; ++n) _Pragma("unroll") for (int k = 0; k < 2; ++k) dst[n][k] = *(const LAS bf16x8*)(lds + PG8_SB(b, h) + boff + n * 2048 + k * 1024); } while (0)
; #define PG8_MMA(ai, bj, At, Bt) do { __builtin_amdgcn_s_setprio(1); _Pragma("unroll") for (int m = 0; m < 4; ++m) _Pragma("unroll") for (int n = 0; n < 2; ++n) _Pragma("unroll") for (int k = 0; k < 2; ++k) \
;         acc[ai][bj][m][n] = __builtin_amdgcn_mfma_f32_16x16x32_bf16(Bt[n][k], At[m][k], acc[ai][bj][m][n], 0, 0, 0); __builtin_amdgcn_s_setprio(0); } while (0)
; #define PG8_WAIT_V(n) asm volatile("s_waitcnt vmcnt(" #n ")" ::: "memory")
; #define PG8_WAIT_L(n) asm volatile("s_waitcnt lgkmcnt(" #n ")" ::: "memory")
; #define PG8_BAR __builtin_amdgcn_s_barrier()
; #define PG8_SCHED __builtin_amdgcn_sched_barrier(0)
; template <class Epi, bool ALIGN_EPI = true>
; __device__ __forceinline__ void gemm_phase(LAS unsigned char* lds, const Gemm g, const StaticOrder& S, const Epi& E, int wave_k) {
;     ...
;             PG8_WAIT_V(8); PG8_WAIT_L(0); PG8_BAR; PG8_MMA(1, 0, At, B0); PG8_MMA(1, 1, At, B1); PG8_BAR; PG8_SCHED;
;             PG8_LDB(B0, 1, 0); PG8_LDB(B1, 1, 1); PG8_SCHED; PG8_LDA(At, 1, 0); PG8_STAGE(PG8_SA(0, 1), a2 + hstepA, voffA);
;             PG8_WAIT_V(8); PG8_WAIT_L(0); PG8_BAR; PG8_MMA(0, 0, At, B0); PG8_MMA(0, 1, At, B1); PG8_BAR; PG8_SCHED;
	s_setprio 1
	v_mfma_f32_16x16x32_bf16 v[60:63], v[138:141], v[178:181], v[60:63]
	v_mfma_f32_16x16x32_bf16 v[52:55], v[146:149], v[178:181], v[52:55]
	v_mfma_f32_16x16x32_bf16 v[44:47], v[138:141], v[186:189], v[44:47]
	v_mfma_f32_16x16x32_bf16 v[36:39], v[146:149], v[186:189], v[36:39]
	v_mfma_f32_16x16x32_bf16 v[28:31], v[138:141], v[194:197], v[28:31]
	v_mfma_f32_16x16x32_bf16 v[20:23], v[146:149], v[194:197], v[20:23]
	v_mfma_f32_16x16x32_bf16 v[12:15], v[138:141], v[202:205], v[12:15]
	v_mfma_f32_16x16x32_bf16 v[4:7], v[146:149], v[202:205], v[4:7]
	v_mfma_f32_16x16x32_bf16 v[60:63], v[142:145], v[182:185], v[60:63]
	v_mfma_f32_16x16x32_bf16 v[52:55], v[150:153], v[182:185], v[52:55]
	v_mfma_f32_16x16x32_bf16 v[44:47], v[142:145], v[190:193], v[44:47]
	v_mfma_f32_16x16x32_bf16 v[36:39], v[150:153], v[190:193], v[36:39]
	v_mfma_f32_16x16x32_bf16 v[28:31], v[142:145], v[198:201], v[28:31]
	v_mfma_f32_16x16x32_bf16 v[20:23], v[150:153], v[198:201], v[20:23]
	v_mfma_f32_16x16x32_bf16 v[12:15], v[142:145], v[206:209], v[12:15]
	v_mfma_f32_16x16x32_bf16 v[4:7], v[150:153], v[206:209], v[4:7]
	v_mfma_f32_16x16x32_bf16 v[56:59], v[162:165], v[178:181], v[56:59]
	v_mfma_f32_16x16x32_bf16 v[48:51], v[170:173], v[178:181], v[48:51]
	v_mfma_f32_16x16x32_bf16 v[40:43], v[162:165], v[186:189], v[40:43]
	v_mfma_f32_16x16x32_bf16 v[32:35], v[170:173], v[186:189], v[32:35]
	v_mfma_f32_16x16x32_bf16 v[24:27], v[162:165], v[194:197], v[24:27]
	v_mfma_f32_16x16x32_bf16 v[16:19], v[170:173], v[194:197], v[16:19]
	v_mfma_f32_16x16x32_bf16 v[8:11], v[162:165], v[202:205], v[8:11]
	v_mfma_f32_16x16x32_bf16 v[0:3], v[170:173], v[202:205], v[0:3]
	v_mfma_f32_16x16x32_bf16 v[56:59], v[166:169], v[182:185], v[56:59]
	v_mfma_f32_16x16x32_bf16 v[48:51], v[174:177], v[182:185], v[48:51]
	v_mfma_f32_16x16x32_bf16 v[40:43], v[166:169], v[190:193], v[40:43]
	v_mfma_f32_16x16x32_bf16 v[32:35], v[174:177], v[190:193], v[32:35]
	v_mfma_f32_16x16x32_bf16 v[24:27], v[166:169], v[198:201], v[24:27]
	v_mfma_f32_16x16x32_bf16 v[16:19], v[174:177], v[198:201], v[16:19]
	v_mfma_f32_16x16x32_bf16 v[8:11], v[166:169], v[206:209], v[8:11]
	v_mfma_f32_16x16x32_bf16 v[0:3], v[174:177], v[206:209], v[0:3]
	s_setprio 0
	s_barrier
	s_add_i32 s65, 0, 0x18000
	s_add_i32 s66, 0, 0x1c000
	v_add_u32_e32 v150, s65, v157
	v_add_u32_e32 v174, s66, v157
	ds_read_b128 v[138:141], v150
	ds_read_b128 v[142:145], v150 offset:1024
	ds_read_b128 v[146:149], v150 offset:2048
	ds_read_b128 v[150:153], v150 offset:3072
	ds_read_b128 v[162:165], v174
	ds_read_b128 v[166:169], v174 offset:1024
	ds_read_b128 v[170:173], v174 offset:2048
	ds_read_b128 v[174:177], v174 offset:3072
	s_add_u32 s18, s18, 0x40000
	s_addc_u32 s19, s19, 0
	s_mov_b32 m0, s57
	ds_read_b128 v[178:181], v159 offset:32768
	ds_read_b128 v[182:185], v159 offset:33792
	ds_read_b128 v[186:189], v159 offset:34816
	ds_read_b128 v[190:193], v159 offset:35840
	ds_read_b128 v[194:197], v159 offset:36864
	ds_read_b128 v[198:201], v159 offset:37888
	ds_read_b128 v[202:205], v159 offset:38912
	ds_read_b128 v[206:209], v159 offset:39936
	global_load_lds_dwordx4 v132, s[18:19]
	s_mov_b32 m0, s58
	s_nop 0
	global_load_lds_dwordx4 v130, s[18:19]
	s_waitcnt vmcnt(8) lgkmcnt(0)
	s_barrier
	s_setprio 1
	v_mfma_f32_16x16x32_bf16 v[124:127], v[138:141], v[178:181], v[124:127]
	v_mfma_f32_16x16x32_bf16 v[120:123], v[146:149], v[178:181], v[120:123]
	v_mfma_f32_16x16x32_bf16 v[108:111], v[138:141], v[186:189], v[108:111]
	v_mfma_f32_16x16x32_bf16 v[100:103], v[146:149], v[186:189], v[100:103]
	v_mfma_f32_16x16x32_bf16 v[92:95], v[138:141], v[194:197], v[92:95]
	v_mfma_f32_16x16x32_bf16 v[84:87], v[146:149], v[194:197], v[84:87]
	v_mfma_f32_16x16x32_bf16 v[76:79], v[138:141], v[202:205], v[76:79]
	v_mfma_f32_16x16x32_bf16 v[68:71], v[146:149], v[202:205], v[68:71]
	v_mfma_f32_16x16x32_bf16 v[124:127], v[142:145], v[182:185], v[124:127]
	v_mfma_f32_16x16x32_bf16 v[120:123], v[150:153], v[182:185], v[120:123]
	v_mfma_f32_16x16x32_bf16 v[108:111], v[142:145], v[190:193], v[108:111]
	v_mfma_f32_16x16x32_bf16 v[100:103], v[150:153], v[190:193], v[100:103]
	v_mfma_f32_16x16x32_bf16 v[92:95], v[142:145], v[198:201], v[92:95]
	v_mfma_f32_16x16x32_bf16 v[84:87], v[150:153], v[198:201], v[84:87]
	v_mfma_f32_16x16x32_bf16 v[76:79], v[142:145], v[206:209], v[76:79]
	v_mfma_f32_16x16x32_bf16 v[68:71], v[150:153], v[206:209], v[68:71]
	v_mfma_f32_16x16x32_bf16 v[116:119], v[162:165], v[178:181], v[116:119]
	v_mfma_f32_16x16x32_bf16 v[112:115], v[170:173], v[178:181], v[112:115]
	v_mfma_f32_16x16x32_bf16 v[104:107], v[162:165], v[186:189], v[104:107]
	v_mfma_f32_16x16x32_bf16 v[96:99], v[170:173], v[186:189], v[96:99]
	v_mfma_f32_16x16x32_bf16 v[88:91], v[162:165], v[194:197], v[88:91]
	v_mfma_f32_16x16x32_bf16 v[80:83], v[170:173], v[194:197], v[80:83]
	v_mfma_f32_16x16x32_bf16 v[72:75], v[162:165], v[202:205], v[72:75]
	v_mfma_f32_16x16x32_bf16 v[64:67], v[170:173], v[202:205], v[64:67]
	v_mfma_f32_16x16x32_bf16 v[116:119], v[166:169], v[182:185], v[116:119]
	v_mfma_f32_16x16x32_bf16 v[112:115], v[174:177], v[182:185], v[112:115]
	v_mfma_f32_16x16x32_bf16 v[104:107], v[166:169], v[190:193], v[104:107]
	v_mfma_f32_16x16x32_bf16 v[96:99], v[174:177], v[190:193], v[96:99]
	v_mfma_f32_16x16x32_bf16 v[88:91], v[166:169], v[198:201], v[88:91]
	v_mfma_f32_16x16x32_bf16 v[80:83], v[174:177], v[198:201], v[80:83]
	v_mfma_f32_16x16x32_bf16 v[72:75], v[166:169], v[206:209], v[72:75]
	v_mfma_f32_16x16x32_bf16 v[64:67], v[174:177], v[206:209], v[64:67]
	s_setprio 0
	s_barrier
; #define PG8_STAGE(bufoff, gbase, voff) do { _Pragma("unroll") for (int _i = 0; _i < 2; ++_i) \
;         __builtin_amdgcn_global_load_lds((const unsigned*)((const char*)(gbase) + (voff)[_i]), (LAS unsigned*)(lds + (bufoff) + ldsw + _i * 8192), 16, 0, 0); } while (0)
; #define PG8_LDA(dst, b, h) do { _Pragma("unroll") for (int m = 0; m < 4; ++m) _Pragma("unroll") for (int k = 0; k < 2; ++k) dst[m][k] = *(const LAS bf16x8*)(lds + PG8_SA(b, h) + aoff + m * 2048 + k * 1024); } while (0)
; #define PG8_MMA(ai, bj, At, Bt) do { __builtin_amdgcn_s_setprio(1); _Pragma("unroll") for (int m = 0; m < 4; ++m) _Pragma("unroll") for (int n = 0; n < 2; ++n) _Pragma("unroll") for (int k = 0; k < 2; ++k) \
;         acc[ai][bj][m][n] = __builtin_amdgcn_mfma_f32_16x16x32_bf16(Bt[n][k], At[m][k], acc[ai][bj][m][n], 0, 0, 0); __builtin_amdgcn_s_setprio(0); } while (0)
; #define PG8_WAIT_V(n) asm volatile("s_waitcnt vmcnt(" #n ")" ::: "memory")
; #define PG8_WAIT_L(n) asm volatile("s_waitcnt lgkmcnt(" #n ")" ::: "memory")
; #define PG8_BAR __builtin_amdgcn_s_barrier()
; #define PG8_SCHED __builtin_amdgcn_sched_barrier(0)
; template <class Epi, bool ALIGN_EPI = true>
; __device__ __forceinline__ void gemm_phase(LAS unsigned char* lds, const Gemm g, const StaticOrder& S, const Epi& E, int wave_k) {
;     ...
;             PG8_LDA(At, 1, 1); PG8_STAGE(PG8_SB(1, 0), b3, voffB); PG8_STAGE(PG8_SB(1, 1), b3 + hstepB, voffB); PG8_STAGE(PG8_SA(1, 0), a3, voffA);
;             PG8_WAIT_V(8); PG8_WAIT_L(0); PG8_BAR; PG8_MMA(1, 0, At, B0); PG8_MMA(1, 1, At, B1); PG8_BAR; PG8_SCHED;
;         }
	s_add_i32 s18, s65, s29
	v_lshl_add_u64 v[154:155], v[154:155], 0, s[22:23]
	s_mov_b32 m0, s18
	ds_read_b128 v[178:181], v159 offset:49152
	ds_read_b128 v[182:185], v159 offset:50176
	ds_read_b128 v[186:189], v159 offset:51200
	ds_read_b128 v[190:193], v159 offset:52224
	ds_read_b128 v[194:197], v159 offset:53248
	ds_read_b128 v[198:201], v159 offset:54272
	ds_read_b128 v[202:205], v159 offset:55296
	ds_read_b128 v[206:209], v159 offset:56320
	global_load_lds_dwordx4 v[154:155], off
	s_add_i32 m0, s18, 0x2000
	s_add_u32 s16, s16, 0x40080
	v_lshl_add_u64 v[154:155], v[210:211], 0, s[22:23]
	s_addc_u32 s17, s17, 0
	s_add_i32 s18, s66, s29
	global_load_lds_dwordx4 v[154:155], off
	s_mov_b32 m0, s18
	s_nop 0
	global_load_lds_dwordx4 v160, s[16:17]
	s_add_i32 m0, s18, 0x2000
	s_nop 0
	global_load_lds_dwordx4 v128, s[16:17]
	v_lshl_add_u64 v[154:155], v[212:213], 0, s[22:23]
	s_mov_b32 m0, s59
	s_nop 0
	global_load_lds_dwordx4 v[154:155], off
	v_lshl_add_u64 v[154:155], v[218:219], 0, s[22:23]
	s_mov_b32 m0, s60
	s_nop 0
	global_load_lds_dwordx4 v[154:155], off
	s_waitcnt vmcnt(8) lgkmcnt(0)
	s_barrier
	s_setprio 1
	v_mfma_f32_16x16x32_bf16 v[60:63], v[138:141], v[178:181], v[60:63]
	v_mfma_f32_16x16x32_bf16 v[52:55], v[146:149], v[178:181], v[52:55]
	v_mfma_f32_16x16x32_bf16 v[44:47], v[138:141], v[186:189], v[44:47]
	v_mfma_f32_16x16x32_bf16 v[36:39], v[146:149], v[186:189], v[36:39]
	v_mfma_f32_16x16x32_bf16 v[28:31], v[138:141], v[194:197], v[28:31]
	v_mfma_f32_16x16x32_bf16 v[20:23], v[146:149], v[194:197], v[20:23]
	v_mfma_f32_16x16x32_bf16 v[12:15], v[138:141], v[202:205], v[12:15]
	v_mfma_f32_16x16x32_bf16 v[4:7], v[146:149], v[202:205], v[4:7]
	v_mfma_f32_16x16x32_bf16 v[60:63], v[142:145], v[182:185], v[60:63]
	v_mfma_f32_16x16x32_bf16 v[52:55], v[150:153], v[182:185], v[52:55]
	v_mfma_f32_16x16x32_bf16 v[44:47], v[142:145], v[190:193], v[44:47]
	v_mfma_f32_16x16x32_bf16 v[36:39], v[150:153], v[190:193], v[36:39]
	v_mfma_f32_16x16x32_bf16 v[28:31], v[142:145], v[198:201], v[28:31]
	v_mfma_f32_16x16x32_bf16 v[20:23], v[150:153], v[198:201], v[20:23]
	v_mfma_f32_16x16x32_bf16 v[12:15], v[142:145], v[206:209], v[12:15]
	v_mfma_f32_16x16x32_bf16 v[4:7], v[150:153], v[206:209], v[4:7]
	v_mfma_f32_16x16x32_bf16 v[56:59], v[162:165], v[178:181], v[56:59]
	v_mfma_f32_16x16x32_bf16 v[48:51], v[170:173], v[178:181], v[48:51]
	v_mfma_f32_16x16x32_bf16 v[40:43], v[162:165], v[186:189], v[40:43]
	v_mfma_f32_16x16x32_bf16 v[32:35], v[170:173], v[186:189], v[32:35]
	v_mfma_f32_16x16x32_bf16 v[24:27], v[162:165], v[194:197], v[24:27]
	v_mfma_f32_16x16x32_bf16 v[16:19], v[170:173], v[194:197], v[16:19]
	v_mfma_f32_16x16x32_bf16 v[8:11], v[162:165], v[202:205], v[8:11]
	v_mfma_f32_16x16x32_bf16 v[0:3], v[170:173], v[202:205], v[0:3]
	v_mfma_f32_16x16x32_bf16 v[56:59], v[166:169], v[182:185], v[56:59]
	v_mfma_f32_16x16x32_bf16 v[48:51], v[174:177], v[182:185], v[48:51]
	v_mfma_f32_16x16x32_bf16 v[40:43], v[166:169], v[190:193], v[40:43]
	v_mfma_f32_16x16x32_bf16 v[32:35], v[174:177], v[190:193], v[32:35]
	v_mfma_f32_16x16x32_bf16 v[24:27], v[166:169], v[198:201], v[24:27]
	v_mfma_f32_16x16x32_bf16 v[16:19], v[174:177], v[198:201], v[16:19]
	v_mfma_f32_16x16x32_bf16 v[8:11], v[166:169], v[206:209], v[8:11]
	v_mfma_f32_16x16x32_bf16 v[0:3], v[174:177], v[206:209], v[0:3]
	s_setprio 0
	s_barrier
	s_add_i32 s64, s64, 2
	s_add_u32 s2, s2, 0x100
	s_addc_u32 s3, s3, 0
	s_add_u32 s62, s62, 0x100
	s_addc_u32 s63, s63, 0
	s_cmp_gt_u32 s64, 13
	s_cbranch_scc0 .LBB0_81
	s_and_b64 vcc, exec, s[46:47]
	s_cbranch_vccz .LBB0_84
	s_barrier

; #define PG8_STAGE(bufoff, gbase, voff) do { _Pragma("unroll") for (int _i = 0; _i < 2; ++_i) \
;         __builtin_amdgcn_global_load_lds((const unsigned*)((const char*)(gbase) + (voff)[_i]), (LAS unsigned*)(lds + (bufoff) + ldsw + _i * 8192), 16, 0, 0); } while (0)
; #define PG8_LDA(dst, b, h) do { _Pragma("unroll") for (int m = 0; m < 4; ++m) _Pragma("unroll") for (int k = 0; k < 2; ++k) dst[m][k] = *(const LAS bf16x8*)(lds + PG8_SA(b, h) + aoff + m * 2048 + k * 1024); } while (0)
; #define PG8_LDB(dst, b, h) do { _Pragma("unroll") for (int n = 0; n < 2; ++n) _Pragma("unroll") for (int k = 0; k < 2; ++k) dst[n][k] = *(const LAS bf16x8*)(lds + PG8_SB(b, h) + boff + n * 2048 + k * 1024); } while (0)
; #define PG8_MMA(ai, bj, At, Bt) do { __builtin_amdgcn_s_setprio(1); _Pragma("unroll") for (int m = 0; m < 4; ++m) _Pragma("unroll") for (int n = 0; n < 2; ++n) _Pragma("unroll") for (int k = 0; k < 2; ++k) \
;         acc[ai][bj][m][n] = __builtin_amdgcn_mfma_f32_16x16x32_bf16(Bt[n][k], At[m][k], acc[ai][bj][m][n], 0, 0, 0); __builtin_amdgcn_s_setprio(0); } while (0)
; #define PG8_WAIT_V(n) asm volatile("s_waitcnt vmcnt(" #n ")" ::: "memory")
; #define PG8_WAIT_L(n) asm volatile("s_waitcnt lgkmcnt(" #n ")" ::: "memory")
; #define PG8_BAR __builtin_amdgcn_s_barrier()
; #define PG8_SCHED __builtin_amdgcn_sched_barrier(0)
; template <class Epi, bool ALIGN_EPI = true>
; __device__ __forceinline__ void gemm_phase(LAS unsigned char* lds, const Gemm g, const StaticOrder& S, const Epi& E, int wave_k) {
;     ...
;             const char* a1 = cA + (size_t)(t + 1) * kstep;
;             const char* a2 = last ? nA : cA + (size_t)(t + 2) * kstep; const char* b2 = last ? nB : cB + (size_t)(t + 2) * kstep;
;             const char* a3 = a2 + kstep; const char* b3 = b2 + kstep;
;             PG8_LDB(B0, 0, 0); PG8_LDB(B1, 0, 1); PG8_SCHED; PG8_LDA(At, 0, 0); PG8_STAGE(PG8_SA(1, 1), a1 + hstepA, voffA);
;             PG8_WAIT_V(8); PG8_WAIT_L(0); PG8_BAR; PG8_MMA(0, 0, At, B0); PG8_MMA(0, 1, At, B1); PG8_BAR; PG8_SCHED;
;             PG8_LDA(At, 0, 1); PG8_STAGE(PG8_SB(0, 0), b2, voffB); PG8_STAGE(PG8_SB(0, 1), b2 + hstepB, voffB); PG8_STAGE(PG8_SA(0, 0), a2, voffA);
;             PG8_WAIT_V(8); PG8_WAIT_L(0); PG8_BAR; PG8_MMA(1, 0, At, B0); PG8_MMA(1, 1, At, B1); PG8_BAR; PG8_SCHED;
.LBB0_170:
	s_add_u32 s16, s24, 0x100
	s_addc_u32 s17, s25, 0
	s_add_i32 s71, 0, 0x10000
	s_cmp_eq_u32 s70, 40
	s_cselect_b32 s29, s1, s17
	s_cselect_b32 s28, s0, s16
	v_add_u32_e32 v142, s71, v145
	s_cselect_b32 s27, s37, s47
	s_cselect_b32 s26, s36, s46
	s_add_i32 s72, 0, 0x14000
	ds_read_b128 v[138:141], v142
	ds_read_b128 v[148:151], v142 offset:1024
	ds_read_b128 v[152:155], v142 offset:2048
	ds_read_b128 v[156:159], v142 offset:3072
	v_add_u32_e32 v142, s72, v145
	ds_read_b128 v[162:165], v142
	ds_read_b128 v[166:169], v142 offset:1024
	ds_read_b128 v[170:173], v142 offset:2048
	ds_read_b128 v[174:177], v142 offset:3072
	v_lshl_add_u64 v[142:143], s[24:25], 0, v[134:135]
	s_add_i32 m0, s57, 0xc000
	ds_read_b128 v[178:181], v147
	ds_read_b128 v[182:185], v147 offset:1024
	ds_read_b128 v[186:189], v147 offset:2048
	ds_read_b128 v[190:193], v147 offset:3072
	ds_read_b128 v[194:197], v147 offset:4096
	ds_read_b128 v[198:201], v147 offset:5120
	ds_read_b128 v[202:205], v147 offset:6144
	ds_read_b128 v[206:209], v147 offset:7168
	global_load_lds_dwordx4 v[142:143], off
	v_lshl_add_u64 v[142:143], s[24:25], 0, v[136:137]
	s_add_i32 m0, s57, 0xe000
	s_nop 0
	global_load_lds_dwordx4 v[142:143], off
	s_waitcnt vmcnt(8) lgkmcnt(0)
	s_barrier
	s_setprio 1
	v_mfma_f32_16x16x32_bf16 v[124:127], v[138:141], v[178:181], v[124:127]
	v_mfma_f32_16x16x32_bf16 v[120:123], v[152:155], v[178:181], v[120:123]
	v_mfma_f32_16x16x32_bf16 v[108:111], v[138:141], v[186:189], v[108:111]
	v_mfma_f32_16x16x32_bf16 v[104:107], v[152:155], v[186:189], v[104:107]
	v_mfma_f32_16x16x32_bf16 v[92:95], v[138:141], v[194:197], v[92:95]
	v_mfma_f32_16x16x32_bf16 v[88:91], v[152:155], v[194:197], v[88:91]
	v_mfma_f32_16x16x32_bf16 v[76:79], v[138:141], v[202:205], v[76:79]
	v_mfma_f32_16x16x32_bf16 v[72:75], v[152:155], v[202:205], v[72:75]
	v_mfma_f32_16x16x32_bf16 v[124:127], v[148:151], v[182:185], v[124:127]
	v_mfma_f32_16x16x32_bf16 v[120:123], v[156:159], v[182:185], v[120:123]
	v_mfma_f32_16x16x32_bf16 v[108:111], v[148:151], v[190:193], v[108:111]
	v_mfma_f32_16x16x32_bf16 v[104:107], v[156:159], v[190:193], v[104:107]
	v_mfma_f32_16x16x32_bf16 v[92:95], v[148:151], v[198:201], v[92:95]
	v_mfma_f32_16x16x32_bf16 v[88:91], v[156:159], v[198:201], v[88:91]
	v_mfma_f32_16x16x32_bf16 v[76:79], v[148:151], v[206:209], v[76:79]
	v_mfma_f32_16x16x32_bf16 v[72:75], v[156:159], v[206:209], v[72:75]
	v_mfma_f32_16x16x32_bf16 v[116:119], v[162:165], v[178:181], v[116:119]
	v_mfma_f32_16x16x32_bf16 v[112:115], v[170:173], v[178:181], v[112:115]
	v_mfma_f32_16x16x32_bf16 v[100:103], v[162:165], v[186:189], v[100:103]
	v_mfma_f32_16x16x32_bf16 v[96:99], v[170:173], v[186:189], v[96:99]
	v_mfma_f32_16x16x32_bf16 v[84:87], v[162:165], v[194:197], v[84:87]
	v_mfma_f32_16x16x32_bf16 v[80:83], v[170:173], v[194:197], v[80:83]
	v_mfma_f32_16x16x32_bf16 v[68:71], v[162:165], v[202:205], v[68:71]
	v_mfma_f32_16x16x32_bf16 v[64:67], v[170:173], v[202:205], v[64:67]
	v_mfma_f32_16x16x32_bf16 v[116:119], v[166:169], v[182:185], v[116:119]
	v_mfma_f32_16x16x32_bf16 v[112:115], v[174:177], v[182:185], v[112:115]
	v_mfma_f32_16x16x32_bf16 v[100:103], v[166:169], v[190:193], v[100:103]
	v_mfma_f32_16x16x32_bf16 v[96:99], v[174:177], v[190:193], v[96:99]
	v_mfma_f32_16x16x32_bf16 v[84:87], v[166:169], v[198:201], v[84:87]
	v_mfma_f32_16x16x32_bf16 v[80:83], v[174:177], v[198:201], v[80:83]
	v_mfma_f32_16x16x32_bf16 v[68:71], v[166:169], v[206:209], v[68:71]
	v_mfma_f32_16x16x32_bf16 v[64:67], v[174:177], v[206:209], v[64:67]
	s_setprio 0
	s_barrier
	s_add_i32 s24, s71, s52
	v_lshl_add_u64 v[142:143], s[26:27], 0, v[160:161]
	s_mov_b32 m0, s24
	ds_read_b128 v[178:181], v147 offset:16384
	ds_read_b128 v[182:185], v147 offset:17408
	ds_read_b128 v[186:189], v147 offset:18432
	ds_read_b128 v[190:193], v147 offset:19456
	ds_read_b128 v[194:197], v147 offset:20480
	ds_read_b128 v[198:201], v147 offset:21504
	ds_read_b128 v[202:205], v147 offset:22528
	ds_read_b128 v[206:209], v147 offset:23552
	global_load_lds_dwordx4 v[142:143], off
	s_add_i32 m0, s24, 0x2000
	s_add_u32 s24, s26, 0xb0000
	v_lshl_add_u64 v[210:211], s[26:27], 0, v[132:133]
	s_addc_u32 s25, s27, 0
	s_add_i32 s71, s72, s52
	global_load_lds_dwordx4 v[210:211], off
	s_mov_b32 m0, s71
	v_lshl_add_u64 v[218:219], s[28:29], 0, v[130:131]
	global_load_lds_dwordx4 v160, s[24:25]
	s_add_i32 m0, s71, 0x2000
	s_nop 0
	global_load_lds_dwordx4 v132, s[24:25]
	v_lshl_add_u64 v[212:213], s[28:29], 0, v[128:129]
	s_mov_b32 m0, s57
	s_nop 0
	global_load_lds_dwordx4 v[212:213], off
	s_mov_b32 m0, s58
	s_nop 0
	global_load_lds_dwordx4 v[218:219], off
	s_waitcnt vmcnt(8) lgkmcnt(0)
	s_barrier
; #define PG8_STAGE(bufoff, gbase, voff) do { _Pragma("unroll") for (int _i = 0; _i < 2; ++_i) \
;         __builtin_amdgcn_global_load_lds((const unsigned*)((const char*)(gbase) + (voff)[_i]), (LAS unsigned*)(lds + (bufoff) + ldsw + _i * 8192), 16, 0, 0); } while (0)
; #define PG8_LDA(dst, b, h) do { _Pragma("unroll") for (int m = 0; m < 4; ++m) _Pragma("unroll") for (int k = 0; k < 2; ++k) dst[m][k] = *(const LAS bf16x8*)(lds + PG8_SA(b, h) + aoff + m * 2048 + k * 1024); } while (0)
; #define PG8_LDB(dst, b, h) do { _Pragma("unroll") for (int n = 0; n < 2; ++n) _Pragma("unroll") for (int k = 0; k < 2; ++k) dst[n][k] = *(const LAS bf16x8*)(lds + PG8_SB(b, h) + boff + n * 2048 + k * 1024); } while (0)
; #define PG8_MMA(ai, bj, At, Bt) do { __builtin_amdgcn_s_setprio(1); _Pragma("unroll") for (int m = 0; m < 4; ++m) _Pragma("unroll") for (int n = 0; n < 2; ++n) _Pragma("unroll") for (int k = 0; k < 2; ++k) \
;         acc[ai][bj][m][n] = __builtin_amdgcn_mfma_f32_16x16x32_bf16(Bt[n][k], At[m][k], acc[ai][bj][m][n], 0, 0, 0); __builtin_amdgcn_s_setprio(0); } while (0)
; #define PG8_WAIT_V(n) asm volatile("s_waitcnt vmcnt(" #n ")" ::: "memory")
; #define PG8_WAIT_L(n) asm volatile("s_waitcnt lgkmcnt(" #n ")" ::: "memory")
; #define PG8_BAR __builtin_amdgcn_s_barrier()
; #define PG8_SCHED __builtin_amdgcn_sched_barrier(0)
; template <class Epi, bool ALIGN_EPI = true>
; __device__ __forceinline__ void gemm_phase(LAS unsigned char* lds, const Gemm g, const StaticOrder& S, const Epi& E, int wave_k) {
;     ...
;             PG8_WAIT_V(8); PG8_WAIT_L(0); PG8_BAR; PG8_MMA(1, 0, At, B0); PG8_MMA(1, 1, At, B1); PG8_BAR; PG8_SCHED;
;             PG8_LDB(B0, 1, 0); PG8_LDB(B1, 1, 1); PG8_SCHED; PG8_LDA(At, 1, 0); PG8_STAGE(PG8_SA(0, 1), a2 + hstepA, voffA);
;             PG8_WAIT_V(8); PG8_WAIT_L(0); PG8_BAR; PG8_MMA(0, 0, At, B0); PG8_MMA(0, 1, At, B1); PG8_BAR; PG8_SCHED;
	s_setprio 1
	v_mfma_f32_16x16x32_bf16 v[60:63], v[138:141], v[178:181], v[60:63]
	v_mfma_f32_16x16x32_bf16 v[56:59], v[152:155], v[178:181], v[56:59]
	v_mfma_f32_16x16x32_bf16 v[44:47], v[138:141], v[186:189], v[44:47]
	v_mfma_f32_16x16x32_bf16 v[40:43], v[152:155], v[186:189], v[40:43]
	v_mfma_f32_16x16x32_bf16 v[28:31], v[138:141], v[194:197], v[28:31]
	v_mfma_f32_16x16x32_bf16 v[24:27], v[152:155], v[194:197], v[24:27]
	v_mfma_f32_16x16x32_bf16 v[12:15], v[138:141], v[202:205], v[12:15]
	v_mfma_f32_16x16x32_bf16 v[8:11], v[152:155], v[202:205], v[8:11]
	v_mfma_f32_16x16x32_bf16 v[60:63], v[148:151], v[182:185], v[60:63]
	v_mfma_f32_16x16x32_bf16 v[56:59], v[156:159], v[182:185], v[56:59]
	v_mfma_f32_16x16x32_bf16 v[44:47], v[148:151], v[190:193], v[44:47]
	v_mfma_f32_16x16x32_bf16 v[40:43], v[156:159], v[190:193], v[40:43]
	v_mfma_f32_16x16x32_bf16 v[28:31], v[148:151], v[198:201], v[28:31]
	v_mfma_f32_16x16x32_bf16 v[24:27], v[156:159], v[198:201], v[24:27]
	v_mfma_f32_16x16x32_bf16 v[12:15], v[148:151], v[206:209], v[12:15]
	v_mfma_f32_16x16x32_bf16 v[8:11], v[156:159], v[206:209], v[8:11]
	v_mfma_f32_16x16x32_bf16 v[52:55], v[162:165], v[178:181], v[52:55]
	v_mfma_f32_16x16x32_bf16 v[48:51], v[170:173], v[178:181], v[48:51]
	v_mfma_f32_16x16x32_bf16 v[36:39], v[162:165], v[186:189], v[36:39]
	v_mfma_f32_16x16x32_bf16 v[32:35], v[170:173], v[186:189], v[32:35]
	v_mfma_f32_16x16x32_bf16 v[20:23], v[162:165], v[194:197], v[20:23]
	v_mfma_f32_16x16x32_bf16 v[16:19], v[170:173], v[194:197], v[16:19]
	v_mfma_f32_16x16x32_bf16 v[4:7], v[162:165], v[202:205], v[4:7]
	v_mfma_f32_16x16x32_bf16 v[0:3], v[170:173], v[202:205], v[0:3]
	v_mfma_f32_16x16x32_bf16 v[52:55], v[166:169], v[182:185], v[52:55]
	v_mfma_f32_16x16x32_bf16 v[48:51], v[174:177], v[182:185], v[48:51]
	v_mfma_f32_16x16x32_bf16 v[36:39], v[166:169], v[190:193], v[36:39]
	v_mfma_f32_16x16x32_bf16 v[32:35], v[174:177], v[190:193], v[32:35]
	v_mfma_f32_16x16x32_bf16 v[20:23], v[166:169], v[198:201], v[20:23]
	v_mfma_f32_16x16x32_bf16 v[16:19], v[174:177], v[198:201], v[16:19]
	v_mfma_f32_16x16x32_bf16 v[4:7], v[166:169], v[206:209], v[4:7]
	v_mfma_f32_16x16x32_bf16 v[0:3], v[174:177], v[206:209], v[0:3]
	s_setprio 0
	s_barrier
	s_add_i32 s71, 0, 0x18000
	s_add_i32 s72, 0, 0x1c000
	v_add_u32_e32 v156, s71, v145
	v_add_u32_e32 v174, s72, v145
	ds_read_b128 v[138:141], v156
	ds_read_b128 v[148:151], v156 offset:1024
	ds_read_b128 v[152:155], v156 offset:2048
	ds_read_b128 v[156:159], v156 offset:3072
	ds_read_b128 v[162:165], v174
	ds_read_b128 v[166:169], v174 offset:1024
	ds_read_b128 v[170:173], v174 offset:2048
	ds_read_b128 v[174:177], v174 offset:3072
	s_add_u32 s24, s28, 0xb0000
	s_addc_u32 s25, s29, 0
	s_mov_b32 m0, s59
	ds_read_b128 v[178:181], v147 offset:32768
	ds_read_b128 v[182:185], v147 offset:33792
	ds_read_b128 v[186:189], v147 offset:34816
	ds_read_b128 v[190:193], v147 offset:35840
	ds_read_b128 v[194:197], v147 offset:36864
	ds_read_b128 v[198:201], v147 offset:37888
	ds_read_b128 v[202:205], v147 offset:38912
	ds_read_b128 v[206:209], v147 offset:39936
	global_load_lds_dwordx4 v128, s[24:25]
	s_mov_b32 m0, s60
	s_nop 0
	global_load_lds_dwordx4 v130, s[24:25]
	s_waitcnt vmcnt(8) lgkmcnt(0)
	s_barrier
	s_setprio 1
	v_mfma_f32_16x16x32_bf16 v[124:127], v[138:141], v[178:181], v[124:127]
	v_mfma_f32_16x16x32_bf16 v[120:123], v[152:155], v[178:181], v[120:123]
	v_mfma_f32_16x16x32_bf16 v[108:111], v[138:141], v[186:189], v[108:111]
	v_mfma_f32_16x16x32_bf16 v[104:107], v[152:155], v[186:189], v[104:107]
	v_mfma_f32_16x16x32_bf16 v[92:95], v[138:141], v[194:197], v[92:95]
	v_mfma_f32_16x16x32_bf16 v[88:91], v[152:155], v[194:197], v[88:91]
	v_mfma_f32_16x16x32_bf16 v[76:79], v[138:141], v[202:205], v[76:79]
	v_mfma_f32_16x16x32_bf16 v[72:75], v[152:155], v[202:205], v[72:75]
	v_mfma_f32_16x16x32_bf16 v[124:127], v[148:151], v[182:185], v[124:127]
	v_mfma_f32_16x16x32_bf16 v[120:123], v[156:159], v[182:185], v[120:123]
	v_mfma_f32_16x16x32_bf16 v[108:111], v[148:151], v[190:193], v[108:111]
	v_mfma_f32_16x16x32_bf16 v[104:107], v[156:159], v[190:193], v[104:107]
	v_mfma_f32_16x16x32_bf16 v[92:95], v[148:151], v[198:201], v[92:95]
	v_mfma_f32_16x16x32_bf16 v[88:91], v[156:159], v[198:201], v[88:91]
	v_mfma_f32_16x16x32_bf16 v[76:79], v[148:151], v[206:209], v[76:79]
	v_mfma_f32_16x16x32_bf16 v[72:75], v[156:159], v[206:209], v[72:75]
	v_mfma_f32_16x16x32_bf16 v[116:119], v[162:165], v[178:181], v[116:119]
	v_mfma_f32_16x16x32_bf16 v[112:115], v[170:173], v[178:181], v[112:115]
	v_mfma_f32_16x16x32_bf16 v[100:103], v[162:165], v[186:189], v[100:103]
	v_mfma_f32_16x16x32_bf16 v[96:99], v[170:173], v[186:189], v[96:99]
	v_mfma_f32_16x16x32_bf16 v[84:87], v[162:165], v[194:197], v[84:87]
	v_mfma_f32_16x16x32_bf16 v[80:83], v[170:173], v[194:197], v[80:83]
	v_mfma_f32_16x16x32_bf16 v[68:71], v[162:165], v[202:205], v[68:71]
	v_mfma_f32_16x16x32_bf16 v[64:67], v[170:173], v[202:205], v[64:67]
	v_mfma_f32_16x16x32_bf16 v[116:119], v[166:169], v[182:185], v[116:119]
	v_mfma_f32_16x16x32_bf16 v[112:115], v[174:177], v[182:185], v[112:115]
	v_mfma_f32_16x16x32_bf16 v[100:103], v[166:169], v[190:193], v[100:103]
	v_mfma_f32_16x16x32_bf16 v[96:99], v[174:177], v[190:193], v[96:99]
	v_mfma_f32_16x16x32_bf16 v[84:87], v[166:169], v[198:201], v[84:87]
	v_mfma_f32_16x16x32_bf16 v[80:83], v[174:177], v[198:201], v[80:83]
	v_mfma_f32_16x16x32_bf16 v[68:71], v[166:169], v[206:209], v[68:71]
	v_mfma_f32_16x16x32_bf16 v[64:67], v[174:177], v[206:209], v[64:67]
	s_setprio 0
	s_barrier
; #define PG8_STAGE(bufoff, gbase, voff) do { _Pragma("unroll") for (int _i = 0; _i < 2; ++_i) \
;         __builtin_amdgcn_global_load_lds((const unsigned*)((const char*)(gbase) + (voff)[_i]), (LAS unsigned*)(lds + (bufoff) + ldsw + _i * 8192), 16, 0, 0); } while (0)
; #define PG8_LDA(dst, b, h) do { _Pragma("unroll") for (int m = 0; m < 4; ++m) _Pragma("unroll") for (int k = 0; k < 2; ++k) dst[m][k] = *(const LAS bf16x8*)(lds + PG8_SA(b, h) + aoff + m * 2048 + k * 1024); } while (0)
; #define PG8_MMA(ai, bj, At, Bt) do { __builtin_amdgcn_s_setprio(1); _Pragma("unroll") for (int m = 0; m < 4; ++m) _Pragma("unroll") for (int n = 0; n < 2; ++n) _Pragma("unroll") for (int k = 0; k < 2; ++k) \
;         acc[ai][bj][m][n] = __builtin_amdgcn_mfma_f32_16x16x32_bf16(Bt[n][k], At[m][k], acc[ai][bj][m][n], 0, 0, 0); __builtin_amdgcn_s_setprio(0); } while (0)
; #define PG8_WAIT_V(n) asm volatile("s_waitcnt vmcnt(" #n ")" ::: "memory")
; #define PG8_WAIT_L(n) asm volatile("s_waitcnt lgkmcnt(" #n ")" ::: "memory")
; #define PG8_BAR __builtin_amdgcn_s_barrier()
; #define PG8_SCHED __builtin_amdgcn_sched_barrier(0)
; template <class Epi, bool ALIGN_EPI = true>
; __device__ __forceinline__ void gemm_phase(LAS unsigned char* lds, const Gemm g, const StaticOrder& S, const Epi& E, int wave_k) {
;     ...
;             PG8_LDA(At, 1, 1); PG8_STAGE(PG8_SB(1, 0), b3, voffB); PG8_STAGE(PG8_SB(1, 1), b3 + hstepB, voffB); PG8_STAGE(PG8_SA(1, 0), a3, voffA);
;             PG8_WAIT_V(8); PG8_WAIT_L(0); PG8_BAR; PG8_MMA(1, 0, At, B0); PG8_MMA(1, 1, At, B1); PG8_BAR; PG8_SCHED;
;         }
	s_add_i32 s24, s71, s52
	v_lshl_add_u64 v[142:143], v[142:143], 0, s[22:23]
	s_mov_b32 m0, s24
	ds_read_b128 v[178:181], v147 offset:49152
	ds_read_b128 v[182:185], v147 offset:50176
	ds_read_b128 v[186:189], v147 offset:51200
	ds_read_b128 v[190:193], v147 offset:52224
	ds_read_b128 v[194:197], v147 offset:53248
	ds_read_b128 v[198:201], v147 offset:54272
	ds_read_b128 v[202:205], v147 offset:55296
	ds_read_b128 v[206:209], v147 offset:56320
	global_load_lds_dwordx4 v[142:143], off
	s_add_i32 m0, s24, 0x2000
	s_add_u32 s24, s26, 0xb0080
	v_lshl_add_u64 v[142:143], v[210:211], 0, s[22:23]
	s_addc_u32 s25, s27, 0
	s_add_i32 s26, s72, s52
	global_load_lds_dwordx4 v[142:143], off
	s_mov_b32 m0, s26
	s_nop 0
	global_load_lds_dwordx4 v160, s[24:25]
	s_add_i32 m0, s26, 0x2000
	s_nop 0
	global_load_lds_dwordx4 v132, s[24:25]
	v_lshl_add_u64 v[142:143], v[212:213], 0, s[22:23]
	s_mov_b32 m0, s50
	s_nop 0
	global_load_lds_dwordx4 v[142:143], off
	v_lshl_add_u64 v[142:143], v[218:219], 0, s[22:23]
	s_mov_b32 m0, s51
	s_nop 0
	global_load_lds_dwordx4 v[142:143], off
	s_waitcnt vmcnt(8) lgkmcnt(0)
	s_barrier
	s_setprio 1
	v_mfma_f32_16x16x32_bf16 v[60:63], v[138:141], v[178:181], v[60:63]
	v_mfma_f32_16x16x32_bf16 v[56:59], v[152:155], v[178:181], v[56:59]
	v_mfma_f32_16x16x32_bf16 v[44:47], v[138:141], v[186:189], v[44:47]
	v_mfma_f32_16x16x32_bf16 v[40:43], v[152:155], v[186:189], v[40:43]
	v_mfma_f32_16x16x32_bf16 v[28:31], v[138:141], v[194:197], v[28:31]
	v_mfma_f32_16x16x32_bf16 v[24:27], v[152:155], v[194:197], v[24:27]
	v_mfma_f32_16x16x32_bf16 v[12:15], v[138:141], v[202:205], v[12:15]
	v_mfma_f32_16x16x32_bf16 v[8:11], v[152:155], v[202:205], v[8:11]
	v_mfma_f32_16x16x32_bf16 v[60:63], v[148:151], v[182:185], v[60:63]
	v_mfma_f32_16x16x32_bf16 v[56:59], v[156:159], v[182:185], v[56:59]
	v_mfma_f32_16x16x32_bf16 v[44:47], v[148:151], v[190:193], v[44:47]
	v_mfma_f32_16x16x32_bf16 v[40:43], v[156:159], v[190:193], v[40:43]
	v_mfma_f32_16x16x32_bf16 v[28:31], v[148:151], v[198:201], v[28:31]
	v_mfma_f32_16x16x32_bf16 v[24:27], v[156:159], v[198:201], v[24:27]
	v_mfma_f32_16x16x32_bf16 v[12:15], v[148:151], v[206:209], v[12:15]
	v_mfma_f32_16x16x32_bf16 v[8:11], v[156:159], v[206:209], v[8:11]
	v_mfma_f32_16x16x32_bf16 v[52:55], v[162:165], v[178:181], v[52:55]
	v_mfma_f32_16x16x32_bf16 v[48:51], v[170:173], v[178:181], v[48:51]
	v_mfma_f32_16x16x32_bf16 v[36:39], v[162:165], v[186:189], v[36:39]
	v_mfma_f32_16x16x32_bf16 v[32:35], v[170:173], v[186:189], v[32:35]
	v_mfma_f32_16x16x32_bf16 v[20:23], v[162:165], v[194:197], v[20:23]
	v_mfma_f32_16x16x32_bf16 v[16:19], v[170:173], v[194:197], v[16:19]
	v_mfma_f32_16x16x32_bf16 v[4:7], v[162:165], v[202:205], v[4:7]
	v_mfma_f32_16x16x32_bf16 v[0:3], v[170:173], v[202:205], v[0:3]
	v_mfma_f32_16x16x32_bf16 v[52:55], v[166:169], v[182:185], v[52:55]
	v_mfma_f32_16x16x32_bf16 v[48:51], v[174:177], v[182:185], v[48:51]
	v_mfma_f32_16x16x32_bf16 v[36:39], v[166:169], v[190:193], v[36:39]
	v_mfma_f32_16x16x32_bf16 v[32:35], v[174:177], v[190:193], v[32:35]
	v_mfma_f32_16x16x32_bf16 v[20:23], v[166:169], v[198:201], v[20:23]
	v_mfma_f32_16x16x32_bf16 v[16:19], v[174:177], v[198:201], v[16:19]
	v_mfma_f32_16x16x32_bf16 v[4:7], v[166:169], v[206:209], v[4:7]
	v_mfma_f32_16x16x32_bf16 v[0:3], v[174:177], v[206:209], v[0:3]
	s_setprio 0
	s_barrier
	s_add_i32 s70, s70, 2
	s_add_u32 s46, s46, 0x100
	s_addc_u32 s47, s47, 0
	s_cmp_gt_u32 s70, 41
	s_mov_b64 s[24:25], s[16:17]
	s_cbranch_scc0 .LBB0_170
	s_and_b64 vcc, exec, s[34:35]
	s_cbranch_vccz .LBB0_173
	s_barrier

; #define PG8_STAGE(bufoff, gbase, voff) do { _Pragma("unroll") for (int _i = 0; _i < 2; ++_i) \
;         __builtin_amdgcn_global_load_lds((const unsigned*)((const char*)(gbase) + (voff)[_i]), (LAS unsigned*)(lds + (bufoff) + ldsw + _i * 8192), 16, 0, 0); } while (0)
; #define PG8_LDA(dst, b, h) do { _Pragma("unroll") for (int m = 0; m < 4; ++m) _Pragma("unroll") for (int k = 0; k < 2; ++k) dst[m][k] = *(const LAS bf16x8*)(lds + PG8_SA(b, h) + aoff + m * 2048 + k * 1024); } while (0)
; #define PG8_LDB(dst, b, h) do { _Pragma("unroll") for (int n = 0; n < 2; ++n) _Pragma("unroll") for (int k = 0; k < 2; ++k) dst[n][k] = *(const LAS bf16x8*)(lds + PG8_SB(b, h) + boff + n * 2048 + k * 1024); } while (0)
; #define PG8_MMA(ai, bj, At, Bt) do { __builtin_amdgcn_s_setprio(1); _Pragma("unroll") for (int m = 0; m < 4; ++m) _Pragma("unroll") for (int n = 0; n < 2; ++n) _Pragma("unroll") for (int k = 0; k < 2; ++k) \
;         acc[ai][bj][m][n] = __builtin_amdgcn_mfma_f32_16x16x32_bf16(Bt[n][k], At[m][k], acc[ai][bj][m][n], 0, 0, 0); __builtin_amdgcn_s_setprio(0); } while (0)
; #define PG8_WAIT_V(n) asm volatile("s_waitcnt vmcnt(" #n ")" ::: "memory")
; #define PG8_WAIT_L(n) asm volatile("s_waitcnt lgkmcnt(" #n ")" ::: "memory")
; #define PG8_BAR __builtin_amdgcn_s_barrier()
; #define PG8_SCHED __builtin_amdgcn_sched_barrier(0)
; template <class Epi, bool ALIGN_EPI = true>
; __device__ __forceinline__ void gemm_phase(LAS unsigned char* lds, const Gemm g, const StaticOrder& S, const Epi& E, int wave_k) {
;     ...
;             const char* a1 = cA + (size_t)(t + 1) * kstep;
;             const char* a2 = last ? nA : cA + (size_t)(t + 2) * kstep; const char* b2 = last ? nB : cB + (size_t)(t + 2) * kstep;
;             const char* a3 = a2 + kstep; const char* b3 = b2 + kstep;
;             PG8_LDB(B0, 0, 0); PG8_LDB(B1, 0, 1); PG8_SCHED; PG8_LDA(At, 0, 0); PG8_STAGE(PG8_SA(1, 1), a1 + hstepA, voffA);
;             PG8_WAIT_V(8); PG8_WAIT_L(0); PG8_BAR; PG8_MMA(0, 0, At, B0); PG8_MMA(0, 1, At, B1); PG8_BAR; PG8_SCHED;
;             PG8_LDA(At, 0, 1); PG8_STAGE(PG8_SB(0, 0), b2, voffB); PG8_STAGE(PG8_SB(0, 1), b2 + hstepB, voffB); PG8_STAGE(PG8_SA(0, 0), a2, voffA);
;             PG8_WAIT_V(8); PG8_WAIT_L(0); PG8_BAR; PG8_MMA(1, 0, At, B0); PG8_MMA(1, 1, At, B1); PG8_BAR; PG8_SCHED;
.LBB0_256:
	s_add_u32 s16, s46, 0xfffc0080
	s_addc_u32 s17, s47, -1
	s_add_i32 s49, 0, 0x10000
	s_cmp_eq_u32 s48, 12
	s_cselect_b32 s25, s1, s17
	s_cselect_b32 s24, s26, s16
	s_cselect_b32 s17, s27, s45
	s_cselect_b32 s16, s37, s41
	s_add_i32 s72, 0, 0x14000
	v_add_u32_e32 v152, s49, v168
	v_add_u32_e32 v160, s72, v168
	ds_read_b128 v[140:143], v152
	ds_read_b128 v[144:147], v152 offset:1024
	ds_read_b128 v[148:151], v152 offset:2048
	ds_read_b128 v[152:155], v152 offset:3072
	ds_read_b128 v[156:159], v160
	ds_read_b128 v[162:165], v160 offset:1024
	ds_read_b128 v[170:173], v160 offset:2048
	ds_read_b128 v[174:177], v160 offset:3072
	s_add_i32 m0, s59, 0xc000
	ds_read_b128 v[178:181], v169
	ds_read_b128 v[182:185], v169 offset:1024
	ds_read_b128 v[186:189], v169 offset:2048
	ds_read_b128 v[190:193], v169 offset:3072
	ds_read_b128 v[194:197], v169 offset:4096
	ds_read_b128 v[198:201], v169 offset:5120
	ds_read_b128 v[202:205], v169 offset:6144
	ds_read_b128 v[206:209], v169 offset:7168
	global_load_lds_dwordx4 v136, s[46:47]
	s_add_i32 m0, s59, 0xe000
	s_nop 0
	global_load_lds_dwordx4 v138, s[46:47]
	s_waitcnt vmcnt(8) lgkmcnt(0)
	s_barrier
	s_setprio 1
	v_mfma_f32_16x16x32_bf16 v[124:127], v[140:143], v[178:181], v[124:127]
	v_mfma_f32_16x16x32_bf16 v[120:123], v[148:151], v[178:181], v[120:123]
	v_mfma_f32_16x16x32_bf16 v[108:111], v[140:143], v[186:189], v[108:111]
	v_mfma_f32_16x16x32_bf16 v[104:107], v[148:151], v[186:189], v[104:107]
	v_mfma_f32_16x16x32_bf16 v[92:95], v[140:143], v[194:197], v[92:95]
	v_mfma_f32_16x16x32_bf16 v[88:91], v[148:151], v[194:197], v[88:91]
	v_mfma_f32_16x16x32_bf16 v[76:79], v[140:143], v[202:205], v[76:79]
	v_mfma_f32_16x16x32_bf16 v[72:75], v[148:151], v[202:205], v[72:75]
	v_mfma_f32_16x16x32_bf16 v[124:127], v[144:147], v[182:185], v[124:127]
	v_mfma_f32_16x16x32_bf16 v[120:123], v[152:155], v[182:185], v[120:123]
	v_mfma_f32_16x16x32_bf16 v[108:111], v[144:147], v[190:193], v[108:111]
	v_mfma_f32_16x16x32_bf16 v[104:107], v[152:155], v[190:193], v[104:107]
	v_mfma_f32_16x16x32_bf16 v[92:95], v[144:147], v[198:201], v[92:95]
	v_mfma_f32_16x16x32_bf16 v[88:91], v[152:155], v[198:201], v[88:91]
	v_mfma_f32_16x16x32_bf16 v[76:79], v[144:147], v[206:209], v[76:79]
	v_mfma_f32_16x16x32_bf16 v[72:75], v[152:155], v[206:209], v[72:75]
	v_mfma_f32_16x16x32_bf16 v[116:119], v[156:159], v[178:181], v[116:119]
	v_mfma_f32_16x16x32_bf16 v[112:115], v[170:173], v[178:181], v[112:115]
	v_mfma_f32_16x16x32_bf16 v[100:103], v[156:159], v[186:189], v[100:103]
	v_mfma_f32_16x16x32_bf16 v[96:99], v[170:173], v[186:189], v[96:99]
	v_mfma_f32_16x16x32_bf16 v[84:87], v[156:159], v[194:197], v[84:87]
	v_mfma_f32_16x16x32_bf16 v[80:83], v[170:173], v[194:197], v[80:83]
	v_mfma_f32_16x16x32_bf16 v[68:71], v[156:159], v[202:205], v[68:71]
	v_mfma_f32_16x16x32_bf16 v[64:67], v[170:173], v[202:205], v[64:67]
	v_mfma_f32_16x16x32_bf16 v[116:119], v[162:165], v[182:185], v[116:119]
	v_mfma_f32_16x16x32_bf16 v[112:115], v[174:177], v[182:185], v[112:115]
	v_mfma_f32_16x16x32_bf16 v[100:103], v[162:165], v[190:193], v[100:103]
	v_mfma_f32_16x16x32_bf16 v[96:99], v[174:177], v[190:193], v[96:99]
	v_mfma_f32_16x16x32_bf16 v[84:87], v[162:165], v[198:201], v[84:87]
	v_mfma_f32_16x16x32_bf16 v[80:83], v[174:177], v[198:201], v[80:83]
	v_mfma_f32_16x16x32_bf16 v[68:71], v[162:165], v[206:209], v[68:71]
	v_mfma_f32_16x16x32_bf16 v[64:67], v[174:177], v[206:209], v[64:67]
	s_setprio 0
	s_barrier
	s_add_i32 s49, s49, s58
	v_lshl_add_u64 v[210:211], s[16:17], 0, v[130:131]
	s_mov_b32 m0, s49
	ds_read_b128 v[178:181], v169 offset:16384
	ds_read_b128 v[182:185], v169 offset:17408
	ds_read_b128 v[186:189], v169 offset:18432
	ds_read_b128 v[190:193], v169 offset:19456
	ds_read_b128 v[194:197], v169 offset:20480
	ds_read_b128 v[198:201], v169 offset:21504
	ds_read_b128 v[202:205], v169 offset:22528
	ds_read_b128 v[206:209], v169 offset:23552
	global_load_lds_dwordx4 v[210:211], off
	s_add_i32 m0, s49, 0x2000
	s_add_u32 s66, s16, 0x40000
	v_lshl_add_u64 v[212:213], s[16:17], 0, v[134:135]
	s_addc_u32 s67, s17, 0
	s_add_i32 s49, s72, s58
	global_load_lds_dwordx4 v[212:213], off
	s_mov_b32 m0, s49
	v_lshl_add_u64 v[220:221], s[24:25], 0, v[132:133]
	global_load_lds_dwordx4 v130, s[66:67]
	s_add_i32 m0, s49, 0x2000
	s_nop 0
	global_load_lds_dwordx4 v134, s[66:67]
	v_lshl_add_u64 v[218:219], s[24:25], 0, v[128:129]
	s_mov_b32 m0, s59
	s_nop 0
	global_load_lds_dwordx4 v[218:219], off
	s_mov_b32 m0, s60
	s_nop 0
	global_load_lds_dwordx4 v[220:221], off
	s_waitcnt vmcnt(8) lgkmcnt(0)
	s_barrier
; #define PG8_STAGE(bufoff, gbase, voff) do { _Pragma("unroll") for (int _i = 0; _i < 2; ++_i) \
;         __builtin_amdgcn_global_load_lds((const unsigned*)((const char*)(gbase) + (voff)[_i]), (LAS unsigned*)(lds + (bufoff) + ldsw + _i * 8192), 16, 0, 0); } while (0)
; #define PG8_LDA(dst, b, h) do { _Pragma("unroll") for (int m = 0; m < 4; ++m) _Pragma("unroll") for (int k = 0; k < 2; ++k) dst[m][k] = *(const LAS bf16x8*)(lds + PG8_SA(b, h) + aoff + m * 2048 + k * 1024); } while (0)
; #define PG8_LDB(dst, b, h) do { _Pragma("unroll") for (int n = 0; n < 2; ++n) _Pragma("unroll") for (int k = 0; k < 2; ++k) dst[n][k] = *(const LAS bf16x8*)(lds + PG8_SB(b, h) + boff + n * 2048 + k * 1024); } while (0)
; #define PG8_MMA(ai, bj, At, Bt) do { __builtin_amdgcn_s_setprio(1); _Pragma("unroll") for (int m = 0; m < 4; ++m) _Pragma("unroll") for (int n = 0; n < 2; ++n) _Pragma("unroll") for (int k = 0; k < 2; ++k) \
;         acc[ai][bj][m][n] = __builtin_amdgcn_mfma_f32_16x16x32_bf16(Bt[n][k], At[m][k], acc[ai][bj][m][n], 0, 0, 0); __builtin_amdgcn_s_setprio(0); } while (0)
; #define PG8_WAIT_V(n) asm volatile("s_waitcnt vmcnt(" #n ")" ::: "memory")
; #define PG8_WAIT_L(n) asm volatile("s_waitcnt lgkmcnt(" #n ")" ::: "memory")
; #define PG8_BAR __builtin_amdgcn_s_barrier()
; #define PG8_SCHED __builtin_amdgcn_sched_barrier(0)
; template <class Epi, bool ALIGN_EPI = true>
; __device__ __forceinline__ void gemm_phase(LAS unsigned char* lds, const Gemm g, const StaticOrder& S, const Epi& E, int wave_k) {
;     ...
;             PG8_WAIT_V(8); PG8_WAIT_L(0); PG8_BAR; PG8_MMA(1, 0, At, B0); PG8_MMA(1, 1, At, B1); PG8_BAR; PG8_SCHED;
;             PG8_LDB(B0, 1, 0); PG8_LDB(B1, 1, 1); PG8_SCHED; PG8_LDA(At, 1, 0); PG8_STAGE(PG8_SA(0, 1), a2 + hstepA, voffA);
;             PG8_WAIT_V(8); PG8_WAIT_L(0); PG8_BAR; PG8_MMA(0, 0, At, B0); PG8_MMA(0, 1, At, B1); PG8_BAR; PG8_SCHED;
	s_setprio 1
	v_mfma_f32_16x16x32_bf16 v[60:63], v[140:143], v[178:181], v[60:63]
	v_mfma_f32_16x16x32_bf16 v[56:59], v[148:151], v[178:181], v[56:59]
	v_mfma_f32_16x16x32_bf16 v[44:47], v[140:143], v[186:189], v[44:47]
	v_mfma_f32_16x16x32_bf16 v[40:43], v[148:151], v[186:189], v[40:43]
	v_mfma_f32_16x16x32_bf16 v[28:31], v[140:143], v[194:197], v[28:31]
	v_mfma_f32_16x16x32_bf16 v[24:27], v[148:151], v[194:197], v[24:27]
	v_mfma_f32_16x16x32_bf16 v[12:15], v[140:143], v[202:205], v[12:15]
	v_mfma_f32_16x16x32_bf16 v[8:11], v[148:151], v[202:205], v[8:11]
	v_mfma_f32_16x16x32_bf16 v[60:63], v[144:147], v[182:185], v[60:63]
	v_mfma_f32_16x16x32_bf16 v[56:59], v[152:155], v[182:185], v[56:59]
	v_mfma_f32_16x16x32_bf16 v[44:47], v[144:147], v[190:193], v[44:47]
	v_mfma_f32_16x16x32_bf16 v[40:43], v[152:155], v[190:193], v[40:43]
	v_mfma_f32_16x16x32_bf16 v[28:31], v[144:147], v[198:201], v[28:31]
	v_mfma_f32_16x16x32_bf16 v[24:27], v[152:155], v[198:201], v[24:27]
	v_mfma_f32_16x16x32_bf16 v[12:15], v[144:147], v[206:209], v[12:15]
	v_mfma_f32_16x16x32_bf16 v[8:11], v[152:155], v[206:209], v[8:11]
	v_mfma_f32_16x16x32_bf16 v[52:55], v[156:159], v[178:181], v[52:55]
	v_mfma_f32_16x16x32_bf16 v[48:51], v[170:173], v[178:181], v[48:51]
	v_mfma_f32_16x16x32_bf16 v[36:39], v[156:159], v[186:189], v[36:39]
	v_mfma_f32_16x16x32_bf16 v[32:35], v[170:173], v[186:189], v[32:35]
	v_mfma_f32_16x16x32_bf16 v[20:23], v[156:159], v[194:197], v[20:23]
	v_mfma_f32_16x16x32_bf16 v[16:19], v[170:173], v[194:197], v[16:19]
	v_mfma_f32_16x16x32_bf16 v[4:7], v[156:159], v[202:205], v[4:7]
	v_mfma_f32_16x16x32_bf16 v[0:3], v[170:173], v[202:205], v[0:3]
	v_mfma_f32_16x16x32_bf16 v[52:55], v[162:165], v[182:185], v[52:55]
	v_mfma_f32_16x16x32_bf16 v[48:51], v[174:177], v[182:185], v[48:51]
	v_mfma_f32_16x16x32_bf16 v[36:39], v[162:165], v[190:193], v[36:39]
	v_mfma_f32_16x16x32_bf16 v[32:35], v[174:177], v[190:193], v[32:35]
	v_mfma_f32_16x16x32_bf16 v[20:23], v[162:165], v[198:201], v[20:23]
	v_mfma_f32_16x16x32_bf16 v[16:19], v[174:177], v[198:201], v[16:19]
	v_mfma_f32_16x16x32_bf16 v[4:7], v[162:165], v[206:209], v[4:7]
	v_mfma_f32_16x16x32_bf16 v[0:3], v[174:177], v[206:209], v[0:3]
	s_setprio 0
	s_barrier
	s_add_i32 s49, 0, 0x18000
	s_add_i32 s66, 0, 0x1c000
	v_add_u32_e32 v152, s49, v168
	v_add_u32_e32 v160, s66, v168
	ds_read_b128 v[140:143], v152
	ds_read_b128 v[144:147], v152 offset:1024
	ds_read_b128 v[148:151], v152 offset:2048
	ds_read_b128 v[152:155], v152 offset:3072
	ds_read_b128 v[156:159], v160
	ds_read_b128 v[162:165], v160 offset:1024
	ds_read_b128 v[170:173], v160 offset:2048
	ds_read_b128 v[174:177], v160 offset:3072
	s_add_u32 s24, s24, 0x40000
	s_addc_u32 s25, s25, 0
	s_mov_b32 m0, s61
	ds_read_b128 v[178:181], v169 offset:32768
	ds_read_b128 v[182:185], v169 offset:33792
	ds_read_b128 v[186:189], v169 offset:34816
	ds_read_b128 v[190:193], v169 offset:35840
	ds_read_b128 v[194:197], v169 offset:36864
	ds_read_b128 v[198:201], v169 offset:37888
	ds_read_b128 v[202:205], v169 offset:38912
	ds_read_b128 v[206:209], v169 offset:39936
	global_load_lds_dwordx4 v128, s[24:25]
	s_mov_b32 m0, s62
	s_nop 0
	global_load_lds_dwordx4 v132, s[24:25]
	s_waitcnt vmcnt(8) lgkmcnt(0)
	s_barrier
	s_setprio 1
	v_mfma_f32_16x16x32_bf16 v[124:127], v[140:143], v[178:181], v[124:127]
	v_mfma_f32_16x16x32_bf16 v[120:123], v[148:151], v[178:181], v[120:123]
	v_mfma_f32_16x16x32_bf16 v[108:111], v[140:143], v[186:189], v[108:111]
	v_mfma_f32_16x16x32_bf16 v[104:107], v[148:151], v[186:189], v[104:107]
	v_mfma_f32_16x16x32_bf16 v[92:95], v[140:143], v[194:197], v[92:95]
	v_mfma_f32_16x16x32_bf16 v[88:91], v[148:151], v[194:197], v[88:91]
	v_mfma_f32_16x16x32_bf16 v[76:79], v[140:143], v[202:205], v[76:79]
	v_mfma_f32_16x16x32_bf16 v[72:75], v[148:151], v[202:205], v[72:75]
	v_mfma_f32_16x16x32_bf16 v[124:127], v[144:147], v[182:185], v[124:127]
	v_mfma_f32_16x16x32_bf16 v[120:123], v[152:155], v[182:185], v[120:123]
	v_mfma_f32_16x16x32_bf16 v[108:111], v[144:147], v[190:193], v[108:111]
	v_mfma_f32_16x16x32_bf16 v[104:107], v[152:155], v[190:193], v[104:107]
	v_mfma_f32_16x16x32_bf16 v[92:95], v[144:147], v[198:201], v[92:95]
	v_mfma_f32_16x16x32_bf16 v[88:91], v[152:155], v[198:201], v[88:91]
	v_mfma_f32_16x16x32_bf16 v[76:79], v[144:147], v[206:209], v[76:79]
	v_mfma_f32_16x16x32_bf16 v[72:75], v[152:155], v[206:209], v[72:75]
	v_mfma_f32_16x16x32_bf16 v[116:119], v[156:159], v[178:181], v[116:119]
	v_mfma_f32_16x16x32_bf16 v[112:115], v[170:173], v[178:181], v[112:115]
	v_mfma_f32_16x16x32_bf16 v[100:103], v[156:159], v[186:189], v[100:103]
	v_mfma_f32_16x16x32_bf16 v[96:99], v[170:173], v[186:189], v[96:99]
	v_mfma_f32_16x16x32_bf16 v[84:87], v[156:159], v[194:197], v[84:87]
	v_mfma_f32_16x16x32_bf16 v[80:83], v[170:173], v[194:197], v[80:83]
	v_mfma_f32_16x16x32_bf16 v[68:71], v[156:159], v[202:205], v[68:71]
	v_mfma_f32_16x16x32_bf16 v[64:67], v[170:173], v[202:205], v[64:67]
	v_mfma_f32_16x16x32_bf16 v[116:119], v[162:165], v[182:185], v[116:119]
	v_mfma_f32_16x16x32_bf16 v[112:115], v[174:177], v[182:185], v[112:115]
	v_mfma_f32_16x16x32_bf16 v[100:103], v[162:165], v[190:193], v[100:103]
	v_mfma_f32_16x16x32_bf16 v[96:99], v[174:177], v[190:193], v[96:99]
	v_mfma_f32_16x16x32_bf16 v[84:87], v[162:165], v[198:201], v[84:87]
	v_mfma_f32_16x16x32_bf16 v[80:83], v[174:177], v[198:201], v[80:83]
	v_mfma_f32_16x16x32_bf16 v[68:71], v[162:165], v[206:209], v[68:71]
	v_mfma_f32_16x16x32_bf16 v[64:67], v[174:177], v[206:209], v[64:67]
	s_setprio 0
	s_barrier
; #define PG8_STAGE(bufoff, gbase, voff) do { _Pragma("unroll") for (int _i = 0; _i < 2; ++_i) \
;         __builtin_amdgcn_global_load_lds((const unsigned*)((const char*)(gbase) + (voff)[_i]), (LAS unsigned*)(lds + (bufoff) + ldsw + _i * 8192), 16, 0, 0); } while (0)
; #define PG8_LDA(dst, b, h) do { _Pragma("unroll") for (int m = 0; m < 4; ++m) _Pragma("unroll") for (int k = 0; k < 2; ++k) dst[m][k] = *(const LAS bf16x8*)(lds + PG8_SA(b, h) + aoff + m * 2048 + k * 1024); } while (0)
; #define PG8_MMA(ai, bj, At, Bt) do { __builtin_amdgcn_s_setprio(1); _Pragma("unroll") for (int m = 0; m < 4; ++m) _Pragma("unroll") for (int n = 0; n < 2; ++n) _Pragma("unroll") for (int k = 0; k < 2; ++k) \
;         acc[ai][bj][m][n] = __builtin_amdgcn_mfma_f32_16x16x32_bf16(Bt[n][k], At[m][k], acc[ai][bj][m][n], 0, 0, 0); __builtin_amdgcn_s_setprio(0); } while (0)
; #define PG8_WAIT_V(n) asm volatile("s_waitcnt vmcnt(" #n ")" ::: "memory")
; #define PG8_WAIT_L(n) asm volatile("s_waitcnt lgkmcnt(" #n ")" ::: "memory")
; #define PG8_BAR __builtin_amdgcn_s_barrier()
; #define PG8_SCHED __builtin_amdgcn_sched_barrier(0)
; template <class Epi, bool ALIGN_EPI = true>
; __device__ __forceinline__ void gemm_phase(LAS unsigned char* lds, const Gemm g, const StaticOrder& S, const Epi& E, int wave_k) {
;     ...
;             PG8_LDA(At, 1, 1); PG8_STAGE(PG8_SB(1, 0), b3, voffB); PG8_STAGE(PG8_SB(1, 1), b3 + hstepB, voffB); PG8_STAGE(PG8_SA(1, 0), a3, voffA);
;             PG8_WAIT_V(8); PG8_WAIT_L(0); PG8_BAR; PG8_MMA(1, 0, At, B0); PG8_MMA(1, 1, At, B1); PG8_BAR; PG8_SCHED;
;         }
	s_add_i32 s24, s49, s58
	v_lshl_add_u64 v[210:211], v[210:211], 0, s[22:23]
	s_mov_b32 m0, s24
	ds_read_b128 v[178:181], v169 offset:49152
	ds_read_b128 v[182:185], v169 offset:50176
	ds_read_b128 v[186:189], v169 offset:51200
	ds_read_b128 v[190:193], v169 offset:52224
	ds_read_b128 v[194:197], v169 offset:53248
	ds_read_b128 v[198:201], v169 offset:54272
	ds_read_b128 v[202:205], v169 offset:55296
	ds_read_b128 v[206:209], v169 offset:56320
	global_load_lds_dwordx4 v[210:211], off
	s_add_i32 m0, s24, 0x2000
	s_add_u32 s16, s16, 0x40080
	v_lshl_add_u64 v[210:211], v[212:213], 0, s[22:23]
	s_addc_u32 s17, s17, 0
	s_add_i32 s24, s66, s58
	global_load_lds_dwordx4 v[210:211], off
	s_mov_b32 m0, s24
	s_nop 0
	global_load_lds_dwordx4 v130, s[16:17]
	s_add_i32 m0, s24, 0x2000
	s_nop 0
	global_load_lds_dwordx4 v134, s[16:17]
	v_lshl_add_u64 v[210:211], v[218:219], 0, s[22:23]
	s_mov_b32 m0, s64
	s_nop 0
	global_load_lds_dwordx4 v[210:211], off
	v_lshl_add_u64 v[210:211], v[220:221], 0, s[22:23]
	s_mov_b32 m0, s65
	s_nop 0
	global_load_lds_dwordx4 v[210:211], off
	s_waitcnt vmcnt(8) lgkmcnt(0)
	s_barrier
	s_setprio 1
	v_mfma_f32_16x16x32_bf16 v[60:63], v[140:143], v[178:181], v[60:63]
	v_mfma_f32_16x16x32_bf16 v[56:59], v[148:151], v[178:181], v[56:59]
	v_mfma_f32_16x16x32_bf16 v[44:47], v[140:143], v[186:189], v[44:47]
	v_mfma_f32_16x16x32_bf16 v[40:43], v[148:151], v[186:189], v[40:43]
	v_mfma_f32_16x16x32_bf16 v[28:31], v[140:143], v[194:197], v[28:31]
	v_mfma_f32_16x16x32_bf16 v[24:27], v[148:151], v[194:197], v[24:27]
	v_mfma_f32_16x16x32_bf16 v[12:15], v[140:143], v[202:205], v[12:15]
	v_mfma_f32_16x16x32_bf16 v[8:11], v[148:151], v[202:205], v[8:11]
	v_mfma_f32_16x16x32_bf16 v[60:63], v[144:147], v[182:185], v[60:63]
	v_mfma_f32_16x16x32_bf16 v[56:59], v[152:155], v[182:185], v[56:59]
	v_mfma_f32_16x16x32_bf16 v[44:47], v[144:147], v[190:193], v[44:47]
	v_mfma_f32_16x16x32_bf16 v[40:43], v[152:155], v[190:193], v[40:43]
	v_mfma_f32_16x16x32_bf16 v[28:31], v[144:147], v[198:201], v[28:31]
	v_mfma_f32_16x16x32_bf16 v[24:27], v[152:155], v[198:201], v[24:27]
	v_mfma_f32_16x16x32_bf16 v[12:15], v[144:147], v[206:209], v[12:15]
	v_mfma_f32_16x16x32_bf16 v[8:11], v[152:155], v[206:209], v[8:11]
	v_mfma_f32_16x16x32_bf16 v[52:55], v[156:159], v[178:181], v[52:55]
	v_mfma_f32_16x16x32_bf16 v[48:51], v[170:173], v[178:181], v[48:51]
	v_mfma_f32_16x16x32_bf16 v[36:39], v[156:159], v[186:189], v[36:39]
	v_mfma_f32_16x16x32_bf16 v[32:35], v[170:173], v[186:189], v[32:35]
	v_mfma_f32_16x16x32_bf16 v[20:23], v[156:159], v[194:197], v[20:23]
	v_mfma_f32_16x16x32_bf16 v[16:19], v[170:173], v[194:197], v[16:19]
	v_mfma_f32_16x16x32_bf16 v[4:7], v[156:159], v[202:205], v[4:7]
	v_mfma_f32_16x16x32_bf16 v[0:3], v[170:173], v[202:205], v[0:3]
	v_mfma_f32_16x16x32_bf16 v[52:55], v[162:165], v[182:185], v[52:55]
	v_mfma_f32_16x16x32_bf16 v[48:51], v[174:177], v[182:185], v[48:51]
	v_mfma_f32_16x16x32_bf16 v[36:39], v[162:165], v[190:193], v[36:39]
	v_mfma_f32_16x16x32_bf16 v[32:35], v[174:177], v[190:193], v[32:35]
	v_mfma_f32_16x16x32_bf16 v[20:23], v[162:165], v[198:201], v[20:23]
	v_mfma_f32_16x16x32_bf16 v[16:19], v[174:177], v[198:201], v[16:19]
	v_mfma_f32_16x16x32_bf16 v[4:7], v[162:165], v[206:209], v[4:7]
	v_mfma_f32_16x16x32_bf16 v[0:3], v[174:177], v[206:209], v[0:3]
	s_setprio 0
	s_barrier
	s_add_i32 s48, s48, 2
	s_add_u32 s46, s46, 0x100
	s_addc_u32 s47, s47, 0
	s_add_u32 s41, s41, 0x100
	s_addc_u32 s45, s45, 0
	s_cmp_gt_u32 s48, 13
	s_cbranch_scc0 .LBB0_256
	s_and_b64 vcc, exec, s[34:35]
	s_cbranch_vccz .LBB0_259
	s_barrier

; #define PG8_STAGE(bufoff, gbase, voff) do { _Pragma("unroll") for (int _i = 0; _i < 2; ++_i) \
;         __builtin_amdgcn_global_load_lds((const unsigned*)((const char*)(gbase) + (voff)[_i]), (LAS unsigned*)(lds + (bufoff) + ldsw + _i * 8192), 16, 0, 0); } while (0)
; #define PG8_LDA(dst, b, h) do { _Pragma("unroll") for (int m = 0; m < 4; ++m) _Pragma("unroll") for (int k = 0; k < 2; ++k) dst[m][k] = *(const LAS bf16x8*)(lds + PG8_SA(b, h) + aoff + m * 2048 + k * 1024); } while (0)
; #define PG8_LDB(dst, b, h) do { _Pragma("unroll") for (int n = 0; n < 2; ++n) _Pragma("unroll") for (int k = 0; k < 2; ++k) dst[n][k] = *(const LAS bf16x8*)(lds + PG8_SB(b, h) + boff + n * 2048 + k * 1024); } while (0)
; #define PG8_MMA(ai, bj, At, Bt) do { __builtin_amdgcn_s_setprio(1); _Pragma("unroll") for (int m = 0; m < 4; ++m) _Pragma("unroll") for (int n = 0; n < 2; ++n) _Pragma("unroll") for (int k = 0; k < 2; ++k) \
;         acc[ai][bj][m][n] = __builtin_amdgcn_mfma_f32_16x16x32_bf16(Bt[n][k], At[m][k], acc[ai][bj][m][n], 0, 0, 0); __builtin_amdgcn_s_setprio(0); } while (0)
; #define PG8_BAR __builtin_amdgcn_s_barrier()
; template <class Epi, bool ALIGN_EPI = true>
; __device__ __forceinline__ void gemm_phase(LAS unsigned char* lds, const Gemm g, const StaticOrder& S, const Epi& E, int wave_k) {
;     ...
;         const bool has_next = S.next(ui + 1, nxt);
;         const char* nA = has_next ? (const char*)g.A + (size_t)nxt.pm * tstepA : cA; const char* nB = has_next ? (const char*)g.Bt + (size_t)nxt.pn * tstepB : cB;
;         for (int t = 0; t < nt; t += 2) {
;             const bool last = (t == nt - 2);
;             const char* a1 = cA + (size_t)(t + 1) * kstep;
;             const char* a2 = last ? nA : cA + (size_t)(t + 2) * kstep; const char* b2 = last ? nB : cB + (size_t)(t + 2) * kstep;
;             const char* a3 = a2 + kstep; const char* b3 = b2 + kstep;
;             PG8_LDB(B0, 0, 0); PG8_LDB(B1, 0, 1); PG8_SCHED; PG8_LDA(At, 0, 0); PG8_STAGE(PG8_SA(1, 1), a1 + hstepA, voffA);
;             PG8_WAIT_V(8); PG8_WAIT_L(0); PG8_BAR; PG8_MMA(0, 0, At, B0); PG8_MMA(0, 1, At, B1); PG8_BAR; PG8_SCHED;
;             PG8_LDA(At, 0, 1); PG8_STAGE(PG8_SB(0, 0), b2, voffB); PG8_STAGE(PG8_SB(0, 1), b2 + hstepB, voffB); PG8_STAGE(PG8_SA(0, 0), a2, voffA);
;             PG8_WAIT_V(8); PG8_WAIT_L(0); PG8_BAR; PG8_MMA(1, 0, At, B0); PG8_MMA(1, 1, At, B1); PG8_BAR; PG8_SCHED;
.LBB0_774:
	s_add_u32 s16, s24, 0x100
	s_addc_u32 s17, s25, 0
	s_add_i32 s61, 0, 0x10000
	s_cmp_eq_u32 s60, 2
	s_cselect_b32 s29, s19, s17
	s_cselect_b32 s28, s18, s16
	s_cselect_b32 s27, s21, s45
	s_cselect_b32 s26, s20, s44
	s_add_i32 s62, 0, 0x14000
	v_add_u32_e32 v154, s61, v139
	v_add_u32_e32 v158, s62, v139
	ds_read_b128 v[142:145], v154
	ds_read_b128 v[146:149], v154 offset:1024
	ds_read_b128 v[150:153], v154 offset:2048
	ds_read_b128 v[154:157], v154 offset:3072
	ds_read_b128 v[162:165], v158
	ds_read_b128 v[166:169], v158 offset:1024
	ds_read_b128 v[170:173], v158 offset:2048
	ds_read_b128 v[174:177], v158 offset:3072
	v_lshl_add_u64 v[158:159], s[24:25], 0, v[134:135]
	s_add_i32 m0, s48, 0xc000
	ds_read_b128 v[178:181], v141
	ds_read_b128 v[182:185], v141 offset:1024
	ds_read_b128 v[186:189], v141 offset:2048
	ds_read_b128 v[190:193], v141 offset:3072
	ds_read_b128 v[194:197], v141 offset:4096
	ds_read_b128 v[198:201], v141 offset:5120
	ds_read_b128 v[202:205], v141 offset:6144
	ds_read_b128 v[206:209], v141 offset:7168
	global_load_lds_dwordx4 v[158:159], off
	v_lshl_add_u64 v[158:159], s[24:25], 0, v[136:137]
	s_add_i32 m0, s48, 0xe000
	s_nop 0
	global_load_lds_dwordx4 v[158:159], off
	s_waitcnt vmcnt(8) lgkmcnt(0)
	s_barrier
	s_setprio 1
	v_mfma_f32_16x16x32_bf16 v[124:127], v[142:145], v[178:181], v[124:127]
	v_mfma_f32_16x16x32_bf16 v[120:123], v[150:153], v[178:181], v[120:123]
	v_mfma_f32_16x16x32_bf16 v[116:119], v[142:145], v[186:189], v[116:119]
	v_mfma_f32_16x16x32_bf16 v[112:115], v[150:153], v[186:189], v[112:115]
	v_mfma_f32_16x16x32_bf16 v[100:103], v[142:145], v[194:197], v[100:103]
	v_mfma_f32_16x16x32_bf16 v[96:99], v[150:153], v[194:197], v[96:99]
	v_mfma_f32_16x16x32_bf16 v[84:87], v[142:145], v[202:205], v[84:87]
	v_mfma_f32_16x16x32_bf16 v[80:83], v[150:153], v[202:205], v[80:83]
	v_mfma_f32_16x16x32_bf16 v[124:127], v[146:149], v[182:185], v[124:127]
	v_mfma_f32_16x16x32_bf16 v[120:123], v[154:157], v[182:185], v[120:123]
	v_mfma_f32_16x16x32_bf16 v[116:119], v[146:149], v[190:193], v[116:119]
	v_mfma_f32_16x16x32_bf16 v[112:115], v[154:157], v[190:193], v[112:115]
	v_mfma_f32_16x16x32_bf16 v[100:103], v[146:149], v[198:201], v[100:103]
	v_mfma_f32_16x16x32_bf16 v[96:99], v[154:157], v[198:201], v[96:99]
	v_mfma_f32_16x16x32_bf16 v[84:87], v[146:149], v[206:209], v[84:87]
	v_mfma_f32_16x16x32_bf16 v[80:83], v[154:157], v[206:209], v[80:83]
	v_mfma_f32_16x16x32_bf16 v[108:111], v[162:165], v[178:181], v[108:111]
	v_mfma_f32_16x16x32_bf16 v[104:107], v[170:173], v[178:181], v[104:107]
	v_mfma_f32_16x16x32_bf16 v[92:95], v[162:165], v[186:189], v[92:95]
	v_mfma_f32_16x16x32_bf16 v[88:91], v[170:173], v[186:189], v[88:91]
	v_mfma_f32_16x16x32_bf16 v[76:79], v[162:165], v[194:197], v[76:79]
	v_mfma_f32_16x16x32_bf16 v[72:75], v[170:173], v[194:197], v[72:75]
	v_mfma_f32_16x16x32_bf16 v[68:71], v[162:165], v[202:205], v[68:71]
	v_mfma_f32_16x16x32_bf16 v[64:67], v[170:173], v[202:205], v[64:67]
	v_mfma_f32_16x16x32_bf16 v[108:111], v[166:169], v[182:185], v[108:111]
	v_mfma_f32_16x16x32_bf16 v[104:107], v[174:177], v[182:185], v[104:107]
	v_mfma_f32_16x16x32_bf16 v[92:95], v[166:169], v[190:193], v[92:95]
	v_mfma_f32_16x16x32_bf16 v[88:91], v[174:177], v[190:193], v[88:91]
	v_mfma_f32_16x16x32_bf16 v[76:79], v[166:169], v[198:201], v[76:79]
	v_mfma_f32_16x16x32_bf16 v[72:75], v[174:177], v[198:201], v[72:75]
	v_mfma_f32_16x16x32_bf16 v[68:71], v[166:169], v[206:209], v[68:71]
	v_mfma_f32_16x16x32_bf16 v[64:67], v[174:177], v[206:209], v[64:67]
	s_setprio 0
	s_barrier
	s_add_i32 s24, s61, s46
	v_lshl_add_u64 v[158:159], s[26:27], 0, v[160:161]
	s_mov_b32 m0, s24
	ds_read_b128 v[178:181], v141 offset:16384
	ds_read_b128 v[182:185], v141 offset:17408
	ds_read_b128 v[186:189], v141 offset:18432
	ds_read_b128 v[190:193], v141 offset:19456
	ds_read_b128 v[194:197], v141 offset:20480
	ds_read_b128 v[198:201], v141 offset:21504
	ds_read_b128 v[202:205], v141 offset:22528
	ds_read_b128 v[206:209], v141 offset:23552
	global_load_lds_dwordx4 v[158:159], off
	s_add_i32 m0, s24, 0x2000
	s_add_u32 s24, s26, 0x18000
	v_lshl_add_u64 v[210:211], s[26:27], 0, v[128:129]
	s_addc_u32 s25, s27, 0
	s_add_i32 s61, s62, s46
	global_load_lds_dwordx4 v[210:211], off
	s_mov_b32 m0, s61
	v_lshl_add_u64 v[218:219], s[28:29], 0, v[130:131]
	global_load_lds_dwordx4 v160, s[24:25]
	s_add_i32 m0, s61, 0x2000
	s_nop 0
	global_load_lds_dwordx4 v128, s[24:25]
	v_lshl_add_u64 v[212:213], s[28:29], 0, v[132:133]
	s_mov_b32 m0, s48
	s_nop 0
	global_load_lds_dwordx4 v[212:213], off
	s_mov_b32 m0, s49
	s_nop 0
	global_load_lds_dwordx4 v[218:219], off
	s_waitcnt vmcnt(8) lgkmcnt(0)
	s_barrier
; #define PG8_STAGE(bufoff, gbase, voff) do { _Pragma("unroll") for (int _i = 0; _i < 2; ++_i) \
;         __builtin_amdgcn_global_load_lds((const unsigned*)((const char*)(gbase) + (voff)[_i]), (LAS unsigned*)(lds + (bufoff) + ldsw + _i * 8192), 16, 0, 0); } while (0)
; #define PG8_LDA(dst, b, h) do { _Pragma("unroll") for (int m = 0; m < 4; ++m) _Pragma("unroll") for (int k = 0; k < 2; ++k) dst[m][k] = *(const LAS bf16x8*)(lds + PG8_SA(b, h) + aoff + m * 2048 + k * 1024); } while (0)
; #define PG8_LDB(dst, b, h) do { _Pragma("unroll") for (int n = 0; n < 2; ++n) _Pragma("unroll") for (int k = 0; k < 2; ++k) dst[n][k] = *(const LAS bf16x8*)(lds + PG8_SB(b, h) + boff + n * 2048 + k * 1024); } while (0)
; #define PG8_MMA(ai, bj, At, Bt) do { __builtin_amdgcn_s_setprio(1); _Pragma("unroll") for (int m = 0; m < 4; ++m) _Pragma("unroll") for (int n = 0; n < 2; ++n) _Pragma("unroll") for (int k = 0; k < 2; ++k) \
;         acc[ai][bj][m][n] = __builtin_amdgcn_mfma_f32_16x16x32_bf16(Bt[n][k], At[m][k], acc[ai][bj][m][n], 0, 0, 0); __builtin_amdgcn_s_setprio(0); } while (0)
; #define PG8_WAIT_V(n) asm volatile("s_waitcnt vmcnt(" #n ")" ::: "memory")
; #define PG8_WAIT_L(n) asm volatile("s_waitcnt lgkmcnt(" #n ")" ::: "memory")
; #define PG8_BAR __builtin_amdgcn_s_barrier()
; #define PG8_SCHED __builtin_amdgcn_sched_barrier(0)
; template <class Epi, bool ALIGN_EPI = true>
; __device__ __forceinline__ void gemm_phase(LAS unsigned char* lds, const Gemm g, const StaticOrder& S, const Epi& E, int wave_k) {
;     ...
;             PG8_WAIT_V(8); PG8_WAIT_L(0); PG8_BAR; PG8_MMA(1, 0, At, B0); PG8_MMA(1, 1, At, B1); PG8_BAR; PG8_SCHED;
;             PG8_LDB(B0, 1, 0); PG8_LDB(B1, 1, 1); PG8_SCHED; PG8_LDA(At, 1, 0); PG8_STAGE(PG8_SA(0, 1), a2 + hstepA, voffA);
;             PG8_WAIT_V(8); PG8_WAIT_L(0); PG8_BAR; PG8_MMA(0, 0, At, B0); PG8_MMA(0, 1, At, B1); PG8_BAR; PG8_SCHED;
	s_setprio 1
	v_mfma_f32_16x16x32_bf16 v[60:63], v[142:145], v[178:181], v[60:63]
	v_mfma_f32_16x16x32_bf16 v[56:59], v[150:153], v[178:181], v[56:59]
	v_mfma_f32_16x16x32_bf16 v[52:55], v[142:145], v[186:189], v[52:55]
	v_mfma_f32_16x16x32_bf16 v[48:51], v[150:153], v[186:189], v[48:51]
	v_mfma_f32_16x16x32_bf16 v[36:39], v[142:145], v[194:197], v[36:39]
	v_mfma_f32_16x16x32_bf16 v[32:35], v[150:153], v[194:197], v[32:35]
	v_mfma_f32_16x16x32_bf16 v[20:23], v[142:145], v[202:205], v[20:23]
	v_mfma_f32_16x16x32_bf16 v[16:19], v[150:153], v[202:205], v[16:19]
	v_mfma_f32_16x16x32_bf16 v[60:63], v[146:149], v[182:185], v[60:63]
	v_mfma_f32_16x16x32_bf16 v[56:59], v[154:157], v[182:185], v[56:59]
	v_mfma_f32_16x16x32_bf16 v[52:55], v[146:149], v[190:193], v[52:55]
	v_mfma_f32_16x16x32_bf16 v[48:51], v[154:157], v[190:193], v[48:51]
	v_mfma_f32_16x16x32_bf16 v[36:39], v[146:149], v[198:201], v[36:39]
	v_mfma_f32_16x16x32_bf16 v[32:35], v[154:157], v[198:201], v[32:35]
	v_mfma_f32_16x16x32_bf16 v[20:23], v[146:149], v[206:209], v[20:23]
	v_mfma_f32_16x16x32_bf16 v[16:19], v[154:157], v[206:209], v[16:19]
	v_mfma_f32_16x16x32_bf16 v[44:47], v[162:165], v[178:181], v[44:47]
	v_mfma_f32_16x16x32_bf16 v[40:43], v[170:173], v[178:181], v[40:43]
	v_mfma_f32_16x16x32_bf16 v[28:31], v[162:165], v[186:189], v[28:31]
	v_mfma_f32_16x16x32_bf16 v[24:27], v[170:173], v[186:189], v[24:27]
	v_mfma_f32_16x16x32_bf16 v[12:15], v[162:165], v[194:197], v[12:15]
	v_mfma_f32_16x16x32_bf16 v[8:11], v[170:173], v[194:197], v[8:11]
	v_mfma_f32_16x16x32_bf16 v[4:7], v[162:165], v[202:205], v[4:7]
	v_mfma_f32_16x16x32_bf16 v[0:3], v[170:173], v[202:205], v[0:3]
	v_mfma_f32_16x16x32_bf16 v[44:47], v[166:169], v[182:185], v[44:47]
	v_mfma_f32_16x16x32_bf16 v[40:43], v[174:177], v[182:185], v[40:43]
	v_mfma_f32_16x16x32_bf16 v[28:31], v[166:169], v[190:193], v[28:31]
	v_mfma_f32_16x16x32_bf16 v[24:27], v[174:177], v[190:193], v[24:27]
	v_mfma_f32_16x16x32_bf16 v[12:15], v[166:169], v[198:201], v[12:15]
	v_mfma_f32_16x16x32_bf16 v[8:11], v[174:177], v[198:201], v[8:11]
	v_mfma_f32_16x16x32_bf16 v[4:7], v[166:169], v[206:209], v[4:7]
	v_mfma_f32_16x16x32_bf16 v[0:3], v[174:177], v[206:209], v[0:3]
	s_setprio 0
	s_barrier
	s_add_i32 s61, 0, 0x18000
	s_add_i32 s62, 0, 0x1c000
	v_add_u32_e32 v154, s61, v139
	v_add_u32_e32 v174, s62, v139
	ds_read_b128 v[142:145], v154
	ds_read_b128 v[146:149], v154 offset:1024
	ds_read_b128 v[150:153], v154 offset:2048
	ds_read_b128 v[154:157], v154 offset:3072
	ds_read_b128 v[162:165], v174
	ds_read_b128 v[166:169], v174 offset:1024
	ds_read_b128 v[170:173], v174 offset:2048
	ds_read_b128 v[174:177], v174 offset:3072
	s_add_u32 s24, s28, 0x28000
	s_addc_u32 s25, s29, 0
	s_mov_b32 m0, s50
	ds_read_b128 v[178:181], v141 offset:32768
	ds_read_b128 v[182:185], v141 offset:33792
	ds_read_b128 v[186:189], v141 offset:34816
	ds_read_b128 v[190:193], v141 offset:35840
	ds_read_b128 v[194:197], v141 offset:36864
	ds_read_b128 v[198:201], v141 offset:37888
	ds_read_b128 v[202:205], v141 offset:38912
	ds_read_b128 v[206:209], v141 offset:39936
	global_load_lds_dwordx4 v132, s[24:25]
	s_mov_b32 m0, s51
	s_nop 0
	global_load_lds_dwordx4 v130, s[24:25]
	s_waitcnt vmcnt(8) lgkmcnt(0)
	s_barrier
	s_setprio 1
	v_mfma_f32_16x16x32_bf16 v[124:127], v[142:145], v[178:181], v[124:127]
	v_mfma_f32_16x16x32_bf16 v[120:123], v[150:153], v[178:181], v[120:123]
	v_mfma_f32_16x16x32_bf16 v[116:119], v[142:145], v[186:189], v[116:119]
	v_mfma_f32_16x16x32_bf16 v[112:115], v[150:153], v[186:189], v[112:115]
	v_mfma_f32_16x16x32_bf16 v[100:103], v[142:145], v[194:197], v[100:103]
	v_mfma_f32_16x16x32_bf16 v[96:99], v[150:153], v[194:197], v[96:99]
	v_mfma_f32_16x16x32_bf16 v[84:87], v[142:145], v[202:205], v[84:87]
	v_mfma_f32_16x16x32_bf16 v[80:83], v[150:153], v[202:205], v[80:83]
	v_mfma_f32_16x16x32_bf16 v[124:127], v[146:149], v[182:185], v[124:127]
	v_mfma_f32_16x16x32_bf16 v[120:123], v[154:157], v[182:185], v[120:123]
	v_mfma_f32_16x16x32_bf16 v[116:119], v[146:149], v[190:193], v[116:119]
	v_mfma_f32_16x16x32_bf16 v[112:115], v[154:157], v[190:193], v[112:115]
	v_mfma_f32_16x16x32_bf16 v[100:103], v[146:149], v[198:201], v[100:103]
	v_mfma_f32_16x16x32_bf16 v[96:99], v[154:157], v[198:201], v[96:99]
	v_mfma_f32_16x16x32_bf16 v[84:87], v[146:149], v[206:209], v[84:87]
	v_mfma_f32_16x16x32_bf16 v[80:83], v[154:157], v[206:209], v[80:83]
	v_mfma_f32_16x16x32_bf16 v[108:111], v[162:165], v[178:181], v[108:111]
	v_mfma_f32_16x16x32_bf16 v[104:107], v[170:173], v[178:181], v[104:107]
	v_mfma_f32_16x16x32_bf16 v[92:95], v[162:165], v[186:189], v[92:95]
	v_mfma_f32_16x16x32_bf16 v[88:91], v[170:173], v[186:189], v[88:91]
	v_mfma_f32_16x16x32_bf16 v[76:79], v[162:165], v[194:197], v[76:79]
	v_mfma_f32_16x16x32_bf16 v[72:75], v[170:173], v[194:197], v[72:75]
	v_mfma_f32_16x16x32_bf16 v[68:71], v[162:165], v[202:205], v[68:71]
	v_mfma_f32_16x16x32_bf16 v[64:67], v[170:173], v[202:205], v[64:67]
	v_mfma_f32_16x16x32_bf16 v[108:111], v[166:169], v[182:185], v[108:111]
	v_mfma_f32_16x16x32_bf16 v[104:107], v[174:177], v[182:185], v[104:107]
	v_mfma_f32_16x16x32_bf16 v[92:95], v[166:169], v[190:193], v[92:95]
	v_mfma_f32_16x16x32_bf16 v[88:91], v[174:177], v[190:193], v[88:91]
	v_mfma_f32_16x16x32_bf16 v[76:79], v[166:169], v[198:201], v[76:79]
	v_mfma_f32_16x16x32_bf16 v[72:75], v[174:177], v[198:201], v[72:75]
	v_mfma_f32_16x16x32_bf16 v[68:71], v[166:169], v[206:209], v[68:71]
	v_mfma_f32_16x16x32_bf16 v[64:67], v[174:177], v[206:209], v[64:67]
	s_setprio 0
	s_barrier
; #define PG8_STAGE(bufoff, gbase, voff) do { _Pragma("unroll") for (int _i = 0; _i < 2; ++_i) \
;         __builtin_amdgcn_global_load_lds((const unsigned*)((const char*)(gbase) + (voff)[_i]), (LAS unsigned*)(lds + (bufoff) + ldsw + _i * 8192), 16, 0, 0); } while (0)
; #define PG8_LDA(dst, b, h) do { _Pragma("unroll") for (int m = 0; m < 4; ++m) _Pragma("unroll") for (int k = 0; k < 2; ++k) dst[m][k] = *(const LAS bf16x8*)(lds + PG8_SA(b, h) + aoff + m * 2048 + k * 1024); } while (0)
; #define PG8_MMA(ai, bj, At, Bt) do { __builtin_amdgcn_s_setprio(1); _Pragma("unroll") for (int m = 0; m < 4; ++m) _Pragma("unroll") for (int n = 0; n < 2; ++n) _Pragma("unroll") for (int k = 0; k < 2; ++k) \
;         acc[ai][bj][m][n] = __builtin_amdgcn_mfma_f32_16x16x32_bf16(Bt[n][k], At[m][k], acc[ai][bj][m][n], 0, 0, 0); __builtin_amdgcn_s_setprio(0); } while (0)
; #define PG8_WAIT_V(n) asm volatile("s_waitcnt vmcnt(" #n ")" ::: "memory")
; #define PG8_WAIT_L(n) asm volatile("s_waitcnt lgkmcnt(" #n ")" ::: "memory")
; #define PG8_BAR __builtin_amdgcn_s_barrier()
; #define PG8_SCHED __builtin_amdgcn_sched_barrier(0)
; template <class Epi, bool ALIGN_EPI = true>
; __device__ __forceinline__ void gemm_phase(LAS unsigned char* lds, const Gemm g, const StaticOrder& S, const Epi& E, int wave_k) {
;     ...
;             PG8_LDA(At, 1, 1); PG8_STAGE(PG8_SB(1, 0), b3, voffB); PG8_STAGE(PG8_SB(1, 1), b3 + hstepB, voffB); PG8_STAGE(PG8_SA(1, 0), a3, voffA);
;             PG8_WAIT_V(8); PG8_WAIT_L(0); PG8_BAR; PG8_MMA(1, 0, At, B0); PG8_MMA(1, 1, At, B1); PG8_BAR; PG8_SCHED;
;         }
;         if constexpr (ALIGN_EPI) { if (wr == 0) PG8_BAR; }
	s_add_i32 s24, s61, s46
	v_lshl_add_u64 v[158:159], v[158:159], 0, s[22:23]
	s_mov_b32 m0, s24
	ds_read_b128 v[178:181], v141 offset:49152
	ds_read_b128 v[182:185], v141 offset:50176
	ds_read_b128 v[186:189], v141 offset:51200
	ds_read_b128 v[190:193], v141 offset:52224
	ds_read_b128 v[194:197], v141 offset:53248
	ds_read_b128 v[198:201], v141 offset:54272
	ds_read_b128 v[202:205], v141 offset:55296
	ds_read_b128 v[206:209], v141 offset:56320
	global_load_lds_dwordx4 v[158:159], off
	s_add_i32 m0, s24, 0x2000
	s_add_u32 s24, s26, 0x18080
	v_lshl_add_u64 v[158:159], v[210:211], 0, s[22:23]
	s_addc_u32 s25, s27, 0
	s_add_i32 s26, s62, s46
	global_load_lds_dwordx4 v[158:159], off
	s_mov_b32 m0, s26
	s_nop 0
	global_load_lds_dwordx4 v160, s[24:25]
	s_add_i32 m0, s26, 0x2000
	s_nop 0
	global_load_lds_dwordx4 v128, s[24:25]
	v_lshl_add_u64 v[158:159], v[212:213], 0, s[22:23]
	s_mov_b32 m0, s52
	s_nop 0
	global_load_lds_dwordx4 v[158:159], off
	v_lshl_add_u64 v[158:159], v[218:219], 0, s[22:23]
	s_mov_b32 m0, s53
	s_nop 0
	global_load_lds_dwordx4 v[158:159], off
	s_waitcnt vmcnt(8) lgkmcnt(0)
	s_barrier
	s_setprio 1
	v_mfma_f32_16x16x32_bf16 v[60:63], v[142:145], v[178:181], v[60:63]
	v_mfma_f32_16x16x32_bf16 v[56:59], v[150:153], v[178:181], v[56:59]
	v_mfma_f32_16x16x32_bf16 v[52:55], v[142:145], v[186:189], v[52:55]
	v_mfma_f32_16x16x32_bf16 v[48:51], v[150:153], v[186:189], v[48:51]
	v_mfma_f32_16x16x32_bf16 v[36:39], v[142:145], v[194:197], v[36:39]
	v_mfma_f32_16x16x32_bf16 v[32:35], v[150:153], v[194:197], v[32:35]
	v_mfma_f32_16x16x32_bf16 v[20:23], v[142:145], v[202:205], v[20:23]
	v_mfma_f32_16x16x32_bf16 v[16:19], v[150:153], v[202:205], v[16:19]
	v_mfma_f32_16x16x32_bf16 v[60:63], v[146:149], v[182:185], v[60:63]
	v_mfma_f32_16x16x32_bf16 v[56:59], v[154:157], v[182:185], v[56:59]
	v_mfma_f32_16x16x32_bf16 v[52:55], v[146:149], v[190:193], v[52:55]
	v_mfma_f32_16x16x32_bf16 v[48:51], v[154:157], v[190:193], v[48:51]
	v_mfma_f32_16x16x32_bf16 v[36:39], v[146:149], v[198:201], v[36:39]
	v_mfma_f32_16x16x32_bf16 v[32:35], v[154:157], v[198:201], v[32:35]
	v_mfma_f32_16x16x32_bf16 v[20:23], v[146:149], v[206:209], v[20:23]
	v_mfma_f32_16x16x32_bf16 v[16:19], v[154:157], v[206:209], v[16:19]
	v_mfma_f32_16x16x32_bf16 v[44:47], v[162:165], v[178:181], v[44:47]
	v_mfma_f32_16x16x32_bf16 v[40:43], v[170:173], v[178:181], v[40:43]
	v_mfma_f32_16x16x32_bf16 v[28:31], v[162:165], v[186:189], v[28:31]
	v_mfma_f32_16x16x32_bf16 v[24:27], v[170:173], v[186:189], v[24:27]
	v_mfma_f32_16x16x32_bf16 v[12:15], v[162:165], v[194:197], v[12:15]
	v_mfma_f32_16x16x32_bf16 v[8:11], v[170:173], v[194:197], v[8:11]
	v_mfma_f32_16x16x32_bf16 v[4:7], v[162:165], v[202:205], v[4:7]
	v_mfma_f32_16x16x32_bf16 v[0:3], v[170:173], v[202:205], v[0:3]
	v_mfma_f32_16x16x32_bf16 v[44:47], v[166:169], v[182:185], v[44:47]
	v_mfma_f32_16x16x32_bf16 v[40:43], v[174:177], v[182:185], v[40:43]
	v_mfma_f32_16x16x32_bf16 v[28:31], v[166:169], v[190:193], v[28:31]
	v_mfma_f32_16x16x32_bf16 v[24:27], v[174:177], v[190:193], v[24:27]
	v_mfma_f32_16x16x32_bf16 v[12:15], v[166:169], v[198:201], v[12:15]
	v_mfma_f32_16x16x32_bf16 v[8:11], v[174:177], v[198:201], v[8:11]
	v_mfma_f32_16x16x32_bf16 v[4:7], v[166:169], v[206:209], v[4:7]
	v_mfma_f32_16x16x32_bf16 v[0:3], v[174:177], v[206:209], v[0:3]
	s_setprio 0
	s_barrier
	s_add_i32 s60, s60, 2
	s_add_u32 s44, s44, 0x100
	s_addc_u32 s45, s45, 0
	s_cmp_gt_u32 s60, 3
	s_mov_b64 s[24:25], s[16:17]
	s_cbranch_scc0 .LBB0_774
	s_and_b64 vcc, exec, s[14:15]
	s_cbranch_vccz .LBB0_777
	s_barrier

; #define PG8_STAGE(bufoff, gbase, voff) do { _Pragma("unroll") for (int _i = 0; _i < 2; ++_i) \
;         __builtin_amdgcn_global_load_lds((const unsigned*)((const char*)(gbase) + (voff)[_i]), (LAS unsigned*)(lds + (bufoff) + ldsw + _i * 8192), 16, 0, 0); } while (0)
; #define PG8_LDA(dst, b, h) do { _Pragma("unroll") for (int m = 0; m < 4; ++m) _Pragma("unroll") for (int k = 0; k < 2; ++k) dst[m][k] = *(const LAS bf16x8*)(lds + PG8_SA(b, h) + aoff + m * 2048 + k * 1024); } while (0)
; #define PG8_LDB(dst, b, h) do { _Pragma("unroll") for (int n = 0; n < 2; ++n) _Pragma("unroll") for (int k = 0; k < 2; ++k) dst[n][k] = *(const LAS bf16x8*)(lds + PG8_SB(b, h) + boff + n * 2048 + k * 1024); } while (0)
; #define PG8_MMA(ai, bj, At, Bt) do { __builtin_amdgcn_s_setprio(1); _Pragma("unroll") for (int m = 0; m < 4; ++m) _Pragma("unroll") for (int n = 0; n < 2; ++n) _Pragma("unroll") for (int k = 0; k < 2; ++k) \
;         acc[ai][bj][m][n] = __builtin_amdgcn_mfma_f32_16x16x32_bf16(Bt[n][k], At[m][k], acc[ai][bj][m][n], 0, 0, 0); __builtin_amdgcn_s_setprio(0); } while (0)
; #define PG8_WAIT_V(n) asm volatile("s_waitcnt vmcnt(" #n ")" ::: "memory")
; template <class Epi, bool ALIGN_EPI = true>
; __device__ __forceinline__ void gemm_phase(LAS unsigned char* lds, const Gemm g, const StaticOrder& S, const Epi& E, int wave_k) {
;     ...
;         const char* nA = has_next ? (const char*)g.A + (size_t)nxt.pm * tstepA : cA; const char* nB = has_next ? (const char*)g.Bt + (size_t)nxt.pn * tstepB : cB;
;         for (int t = 0; t < nt; t += 2) {
;             const bool last = (t == nt - 2);
;             const char* a1 = cA + (size_t)(t + 1) * kstep;
;             const char* a2 = last ? nA : cA + (size_t)(t + 2) * kstep; const char* b2 = last ? nB : cB + (size_t)(t + 2) * kstep;
;             const char* a3 = a2 + kstep; const char* b3 = b2 + kstep;
;             PG8_LDB(B0, 0, 0); PG8_LDB(B1, 0, 1); PG8_SCHED; PG8_LDA(At, 0, 0); PG8_STAGE(PG8_SA(1, 1), a1 + hstepA, voffA);
;             PG8_WAIT_V(8); PG8_WAIT_L(0); PG8_BAR; PG8_MMA(0, 0, At, B0); PG8_MMA(0, 1, At, B1); PG8_BAR; PG8_SCHED;
;             PG8_LDA(At, 0, 1); PG8_STAGE(PG8_SB(0, 0), b2, voffB); PG8_STAGE(PG8_SB(0, 1), b2 + hstepB, voffB); PG8_STAGE(PG8_SA(0, 0), a2, voffA);
;             PG8_WAIT_V(8); PG8_WAIT_L(0); PG8_BAR; PG8_MMA(1, 0, At, B0); PG8_MMA(1, 1, At, B1); PG8_BAR; PG8_SCHED;
.LBB0_800:
	s_add_u32 s25, s20, s24
	s_addc_u32 s46, s21, 0
	s_add_u32 s28, s25, 0x100
	s_addc_u32 s29, s46, 0
	s_and_b64 s[26:27], s[16:17], exec
	s_cselect_b32 s27, s37, s29
	s_cselect_b32 s26, s36, s28
	s_add_u32 s24, s18, s24
	s_addc_u32 s28, s19, 0
	s_add_u32 s24, s24, 0x100
	s_addc_u32 s28, s28, 0
	s_add_i32 s79, 0, 0x10000
	s_and_b64 s[16:17], s[16:17], exec
	s_cselect_b32 s29, s35, s28
	s_cselect_b32 s28, s70, s24
	s_add_i32 s17, 0, 0x14000
	s_add_u32 s48, s25, 0x28080
	s_addc_u32 s49, s46, 0
	s_add_i32 s78, s79, s57
	s_add_i32 m0, s58, 0xc000
	s_add_i32 s81, s58, 0xe000
	s_add_i32 s75, s78, 0x2000
	s_add_u32 s46, s28, 0x10000
	v_add_u32_e32 v150, s79, v135
	v_add_u32_e32 v158, s17, v135
	s_addc_u32 s47, s29, 0
	s_add_i32 s77, s17, s57
	ds_read_b128 v[138:141], v150
	ds_read_b128 v[142:145], v150 offset:1024
	ds_read_b128 v[146:149], v150 offset:2048
	ds_read_b128 v[150:153], v150 offset:3072
	ds_read_b128 v[154:157], v158
	ds_read_b128 v[162:165], v158 offset:1024
	ds_read_b128 v[166:169], v158 offset:2048
	ds_read_b128 v[170:173], v158 offset:3072
	s_add_i32 s76, s77, 0x2000
	s_add_i32 s74, 0, 0x18000
	s_add_i32 s73, 0, 0x1c000
	s_add_u32 s24, s26, 0x28000
	s_addc_u32 s25, s27, 0
	s_add_i32 s72, s74, s57
	s_add_i32 s71, s72, 0x2000
	s_add_u32 s16, s28, 0x10080
	s_addc_u32 s17, s29, 0
	s_add_i32 s80, s73, s57
	s_add_i32 s79, s80, 0x2000
	ds_read_b128 v[174:177], v137
	ds_read_b128 v[178:181], v137 offset:1024
	ds_read_b128 v[182:185], v137 offset:2048
	ds_read_b128 v[186:189], v137 offset:3072
	ds_read_b128 v[190:193], v137 offset:4096
	ds_read_b128 v[194:197], v137 offset:5120
	ds_read_b128 v[198:201], v137 offset:6144
	ds_read_b128 v[202:205], v137 offset:7168
	global_load_lds_dwordx4 v128, s[48:49]
	s_mov_b32 m0, s81
	s_nop 0
	global_load_lds_dwordx4 v130, s[48:49]
	s_waitcnt vmcnt(8) lgkmcnt(0)
	s_barrier
	s_setprio 1
	v_mfma_f32_16x16x32_bf16 v[124:127], v[138:141], v[174:177], v[124:127]
	v_mfma_f32_16x16x32_bf16 v[120:123], v[146:149], v[174:177], v[120:123]
	v_mfma_f32_16x16x32_bf16 v[116:119], v[138:141], v[182:185], v[116:119]
	v_mfma_f32_16x16x32_bf16 v[112:115], v[146:149], v[182:185], v[112:115]
	v_mfma_f32_16x16x32_bf16 v[100:103], v[138:141], v[190:193], v[100:103]
	v_mfma_f32_16x16x32_bf16 v[96:99], v[146:149], v[190:193], v[96:99]
	v_mfma_f32_16x16x32_bf16 v[84:87], v[138:141], v[198:201], v[84:87]
	v_mfma_f32_16x16x32_bf16 v[80:83], v[146:149], v[198:201], v[80:83]
	v_mfma_f32_16x16x32_bf16 v[124:127], v[142:145], v[178:181], v[124:127]
	v_mfma_f32_16x16x32_bf16 v[120:123], v[150:153], v[178:181], v[120:123]
	v_mfma_f32_16x16x32_bf16 v[116:119], v[142:145], v[186:189], v[116:119]
	v_mfma_f32_16x16x32_bf16 v[112:115], v[150:153], v[186:189], v[112:115]
	v_mfma_f32_16x16x32_bf16 v[100:103], v[142:145], v[194:197], v[100:103]
	v_mfma_f32_16x16x32_bf16 v[96:99], v[150:153], v[194:197], v[96:99]
	v_mfma_f32_16x16x32_bf16 v[84:87], v[142:145], v[202:205], v[84:87]
	v_mfma_f32_16x16x32_bf16 v[80:83], v[150:153], v[202:205], v[80:83]
	v_mfma_f32_16x16x32_bf16 v[108:111], v[154:157], v[174:177], v[108:111]
	v_mfma_f32_16x16x32_bf16 v[104:107], v[166:169], v[174:177], v[104:107]
	v_mfma_f32_16x16x32_bf16 v[92:95], v[154:157], v[182:185], v[92:95]
	v_mfma_f32_16x16x32_bf16 v[88:91], v[166:169], v[182:185], v[88:91]
	v_mfma_f32_16x16x32_bf16 v[76:79], v[154:157], v[190:193], v[76:79]
	v_mfma_f32_16x16x32_bf16 v[72:75], v[166:169], v[190:193], v[72:75]
	v_mfma_f32_16x16x32_bf16 v[68:71], v[154:157], v[198:201], v[68:71]
	v_mfma_f32_16x16x32_bf16 v[64:67], v[166:169], v[198:201], v[64:67]
	v_mfma_f32_16x16x32_bf16 v[108:111], v[162:165], v[178:181], v[108:111]
	v_mfma_f32_16x16x32_bf16 v[104:107], v[170:173], v[178:181], v[104:107]
	v_mfma_f32_16x16x32_bf16 v[92:95], v[162:165], v[186:189], v[92:95]
	v_mfma_f32_16x16x32_bf16 v[88:91], v[170:173], v[186:189], v[88:91]
	v_mfma_f32_16x16x32_bf16 v[76:79], v[162:165], v[194:197], v[76:79]
	v_mfma_f32_16x16x32_bf16 v[72:75], v[170:173], v[194:197], v[72:75]
	v_mfma_f32_16x16x32_bf16 v[68:71], v[162:165], v[202:205], v[68:71]
	v_mfma_f32_16x16x32_bf16 v[64:67], v[170:173], v[202:205], v[64:67]
	s_setprio 0
	s_barrier
	s_mov_b32 m0, s78
	v_lshl_add_u64 v[158:159], s[28:29], 0, v[160:161]
	ds_read_b128 v[174:177], v137 offset:16384
	ds_read_b128 v[178:181], v137 offset:17408
	ds_read_b128 v[182:185], v137 offset:18432
	ds_read_b128 v[186:189], v137 offset:19456
	ds_read_b128 v[190:193], v137 offset:20480
	ds_read_b128 v[194:197], v137 offset:21504
	ds_read_b128 v[198:201], v137 offset:22528
	ds_read_b128 v[202:205], v137 offset:23552
	global_load_lds_dwordx4 v[158:159], off
	v_lshl_add_u64 v[206:207], s[28:29], 0, v[132:133]
	s_mov_b32 m0, s75
	global_load_lds_dwordx4 v[206:207], off
	s_mov_b32 m0, s77
	v_lshl_add_u64 v[210:211], s[26:27], 0, v[130:131]
	global_load_lds_dwordx4 v160, s[46:47]
	s_mov_b32 m0, s76
	s_nop 0
	global_load_lds_dwordx4 v132, s[46:47]
	v_lshl_add_u64 v[208:209], s[26:27], 0, v[128:129]
	s_mov_b32 m0, s58
	s_nop 0
	global_load_lds_dwordx4 v[208:209], off
	s_mov_b32 m0, s59
	s_nop 0
	global_load_lds_dwordx4 v[210:211], off
	s_waitcnt vmcnt(8) lgkmcnt(0)
	s_barrier
; #define PG8_STAGE(bufoff, gbase, voff) do { _Pragma("unroll") for (int _i = 0; _i < 2; ++_i) \
;         __builtin_amdgcn_global_load_lds((const unsigned*)((const char*)(gbase) + (voff)[_i]), (LAS unsigned*)(lds + (bufoff) + ldsw + _i * 8192), 16, 0, 0); } while (0)
; #define PG8_LDA(dst, b, h) do { _Pragma("unroll") for (int m = 0; m < 4; ++m) _Pragma("unroll") for (int k = 0; k < 2; ++k) dst[m][k] = *(const LAS bf16x8*)(lds + PG8_SA(b, h) + aoff + m * 2048 + k * 1024); } while (0)
; #define PG8_LDB(dst, b, h) do { _Pragma("unroll") for (int n = 0; n < 2; ++n) _Pragma("unroll") for (int k = 0; k < 2; ++k) dst[n][k] = *(const LAS bf16x8*)(lds + PG8_SB(b, h) + boff + n * 2048 + k * 1024); } while (0)
; #define PG8_MMA(ai, bj, At, Bt) do { __builtin_amdgcn_s_setprio(1); _Pragma("unroll") for (int m = 0; m < 4; ++m) _Pragma("unroll") for (int n = 0; n < 2; ++n) _Pragma("unroll") for (int k = 0; k < 2; ++k) \
;         acc[ai][bj][m][n] = __builtin_amdgcn_mfma_f32_16x16x32_bf16(Bt[n][k], At[m][k], acc[ai][bj][m][n], 0, 0, 0); __builtin_amdgcn_s_setprio(0); } while (0)
; #define PG8_WAIT_V(n) asm volatile("s_waitcnt vmcnt(" #n ")" ::: "memory")
; #define PG8_WAIT_L(n) asm volatile("s_waitcnt lgkmcnt(" #n ")" ::: "memory")
; #define PG8_BAR __builtin_amdgcn_s_barrier()
; #define PG8_SCHED __builtin_amdgcn_sched_barrier(0)
; template <class Epi, bool ALIGN_EPI = true>
; __device__ __forceinline__ void gemm_phase(LAS unsigned char* lds, const Gemm g, const StaticOrder& S, const Epi& E, int wave_k) {
;     ...
;             PG8_WAIT_V(8); PG8_WAIT_L(0); PG8_BAR; PG8_MMA(1, 0, At, B0); PG8_MMA(1, 1, At, B1); PG8_BAR; PG8_SCHED;
;             PG8_LDB(B0, 1, 0); PG8_LDB(B1, 1, 1); PG8_SCHED; PG8_LDA(At, 1, 0); PG8_STAGE(PG8_SA(0, 1), a2 + hstepA, voffA);
;             PG8_WAIT_V(8); PG8_WAIT_L(0); PG8_BAR; PG8_MMA(0, 0, At, B0); PG8_MMA(0, 1, At, B1); PG8_BAR; PG8_SCHED;
	s_setprio 1
	v_mfma_f32_16x16x32_bf16 v[60:63], v[138:141], v[174:177], v[60:63]
	v_mfma_f32_16x16x32_bf16 v[56:59], v[146:149], v[174:177], v[56:59]
	v_mfma_f32_16x16x32_bf16 v[52:55], v[138:141], v[182:185], v[52:55]
	v_mfma_f32_16x16x32_bf16 v[48:51], v[146:149], v[182:185], v[48:51]
	v_mfma_f32_16x16x32_bf16 v[36:39], v[138:141], v[190:193], v[36:39]
	v_mfma_f32_16x16x32_bf16 v[32:35], v[146:149], v[190:193], v[32:35]
	v_mfma_f32_16x16x32_bf16 v[20:23], v[138:141], v[198:201], v[20:23]
	v_mfma_f32_16x16x32_bf16 v[16:19], v[146:149], v[198:201], v[16:19]
	v_mfma_f32_16x16x32_bf16 v[60:63], v[142:145], v[178:181], v[60:63]
	v_mfma_f32_16x16x32_bf16 v[56:59], v[150:153], v[178:181], v[56:59]
	v_mfma_f32_16x16x32_bf16 v[52:55], v[142:145], v[186:189], v[52:55]
	v_mfma_f32_16x16x32_bf16 v[48:51], v[150:153], v[186:189], v[48:51]
	v_mfma_f32_16x16x32_bf16 v[36:39], v[142:145], v[194:197], v[36:39]
	v_mfma_f32_16x16x32_bf16 v[32:35], v[150:153], v[194:197], v[32:35]
	v_mfma_f32_16x16x32_bf16 v[20:23], v[142:145], v[202:205], v[20:23]
	v_mfma_f32_16x16x32_bf16 v[16:19], v[150:153], v[202:205], v[16:19]
	v_mfma_f32_16x16x32_bf16 v[44:47], v[154:157], v[174:177], v[44:47]
	v_mfma_f32_16x16x32_bf16 v[40:43], v[166:169], v[174:177], v[40:43]
	v_mfma_f32_16x16x32_bf16 v[28:31], v[154:157], v[182:185], v[28:31]
	v_mfma_f32_16x16x32_bf16 v[24:27], v[166:169], v[182:185], v[24:27]
	v_mfma_f32_16x16x32_bf16 v[12:15], v[154:157], v[190:193], v[12:15]
	v_mfma_f32_16x16x32_bf16 v[8:11], v[166:169], v[190:193], v[8:11]
	v_mfma_f32_16x16x32_bf16 v[4:7], v[154:157], v[198:201], v[4:7]
	v_mfma_f32_16x16x32_bf16 v[0:3], v[166:169], v[198:201], v[0:3]
	v_mfma_f32_16x16x32_bf16 v[44:47], v[162:165], v[178:181], v[44:47]
	v_mfma_f32_16x16x32_bf16 v[40:43], v[170:173], v[178:181], v[40:43]
	v_mfma_f32_16x16x32_bf16 v[28:31], v[162:165], v[186:189], v[28:31]
	v_mfma_f32_16x16x32_bf16 v[24:27], v[170:173], v[186:189], v[24:27]
	v_mfma_f32_16x16x32_bf16 v[12:15], v[162:165], v[194:197], v[12:15]
	v_mfma_f32_16x16x32_bf16 v[8:11], v[170:173], v[194:197], v[8:11]
	v_mfma_f32_16x16x32_bf16 v[4:7], v[162:165], v[202:205], v[4:7]
	v_mfma_f32_16x16x32_bf16 v[0:3], v[170:173], v[202:205], v[0:3]
	s_setprio 0
	s_barrier
	v_add_u32_e32 v150, s74, v135
	v_add_u32_e32 v170, s73, v135
	ds_read_b128 v[138:141], v150
	ds_read_b128 v[142:145], v150 offset:1024
	ds_read_b128 v[146:149], v150 offset:2048
	ds_read_b128 v[150:153], v150 offset:3072
	ds_read_b128 v[154:157], v170
	ds_read_b128 v[162:165], v170 offset:1024
	ds_read_b128 v[166:169], v170 offset:2048
	ds_read_b128 v[170:173], v170 offset:3072
	s_mov_b32 m0, s60
	ds_read_b128 v[174:177], v137 offset:32768
	ds_read_b128 v[178:181], v137 offset:33792
	ds_read_b128 v[182:185], v137 offset:34816
	ds_read_b128 v[186:189], v137 offset:35840
	ds_read_b128 v[190:193], v137 offset:36864
	ds_read_b128 v[194:197], v137 offset:37888
	ds_read_b128 v[198:201], v137 offset:38912
	ds_read_b128 v[202:205], v137 offset:39936
	global_load_lds_dwordx4 v128, s[24:25]
	s_mov_b32 m0, s61
	s_nop 0
	global_load_lds_dwordx4 v130, s[24:25]
	s_waitcnt vmcnt(8) lgkmcnt(0)
	s_barrier
	s_setprio 1
	v_mfma_f32_16x16x32_bf16 v[124:127], v[138:141], v[174:177], v[124:127]
	v_mfma_f32_16x16x32_bf16 v[120:123], v[146:149], v[174:177], v[120:123]
	v_mfma_f32_16x16x32_bf16 v[116:119], v[138:141], v[182:185], v[116:119]
	v_mfma_f32_16x16x32_bf16 v[112:115], v[146:149], v[182:185], v[112:115]
	v_mfma_f32_16x16x32_bf16 v[100:103], v[138:141], v[190:193], v[100:103]
	v_mfma_f32_16x16x32_bf16 v[96:99], v[146:149], v[190:193], v[96:99]
	v_mfma_f32_16x16x32_bf16 v[84:87], v[138:141], v[198:201], v[84:87]
	v_mfma_f32_16x16x32_bf16 v[80:83], v[146:149], v[198:201], v[80:83]
	v_mfma_f32_16x16x32_bf16 v[124:127], v[142:145], v[178:181], v[124:127]
	v_mfma_f32_16x16x32_bf16 v[120:123], v[150:153], v[178:181], v[120:123]
	v_mfma_f32_16x16x32_bf16 v[116:119], v[142:145], v[186:189], v[116:119]
	v_mfma_f32_16x16x32_bf16 v[112:115], v[150:153], v[186:189], v[112:115]
	v_mfma_f32_16x16x32_bf16 v[100:103], v[142:145], v[194:197], v[100:103]
	v_mfma_f32_16x16x32_bf16 v[96:99], v[150:153], v[194:197], v[96:99]
	v_mfma_f32_16x16x32_bf16 v[84:87], v[142:145], v[202:205], v[84:87]
	v_mfma_f32_16x16x32_bf16 v[80:83], v[150:153], v[202:205], v[80:83]
	v_mfma_f32_16x16x32_bf16 v[108:111], v[154:157], v[174:177], v[108:111]
	v_mfma_f32_16x16x32_bf16 v[104:107], v[166:169], v[174:177], v[104:107]
	v_mfma_f32_16x16x32_bf16 v[92:95], v[154:157], v[182:185], v[92:95]
	v_mfma_f32_16x16x32_bf16 v[88:91], v[166:169], v[182:185], v[88:91]
	v_mfma_f32_16x16x32_bf16 v[76:79], v[154:157], v[190:193], v[76:79]
	v_mfma_f32_16x16x32_bf16 v[72:75], v[166:169], v[190:193], v[72:75]
	v_mfma_f32_16x16x32_bf16 v[68:71], v[154:157], v[198:201], v[68:71]
	v_mfma_f32_16x16x32_bf16 v[64:67], v[166:169], v[198:201], v[64:67]
	v_mfma_f32_16x16x32_bf16 v[108:111], v[162:165], v[178:181], v[108:111]
	v_mfma_f32_16x16x32_bf16 v[104:107], v[170:173], v[178:181], v[104:107]
	v_mfma_f32_16x16x32_bf16 v[92:95], v[162:165], v[186:189], v[92:95]
	v_mfma_f32_16x16x32_bf16 v[88:91], v[170:173], v[186:189], v[88:91]
	v_mfma_f32_16x16x32_bf16 v[76:79], v[162:165], v[194:197], v[76:79]
	v_mfma_f32_16x16x32_bf16 v[72:75], v[170:173], v[194:197], v[72:75]
	v_mfma_f32_16x16x32_bf16 v[68:71], v[162:165], v[202:205], v[68:71]
	v_mfma_f32_16x16x32_bf16 v[64:67], v[170:173], v[202:205], v[64:67]
	s_setprio 0
	s_barrier
; #define PG8_STAGE(bufoff, gbase, voff) do { _Pragma("unroll") for (int _i = 0; _i < 2; ++_i) \
;         __builtin_amdgcn_global_load_lds((const unsigned*)((const char*)(gbase) + (voff)[_i]), (LAS unsigned*)(lds + (bufoff) + ldsw + _i * 8192), 16, 0, 0); } while (0)
; #define PG8_LDA(dst, b, h) do { _Pragma("unroll") for (int m = 0; m < 4; ++m) _Pragma("unroll") for (int k = 0; k < 2; ++k) dst[m][k] = *(const LAS bf16x8*)(lds + PG8_SA(b, h) + aoff + m * 2048 + k * 1024); } while (0)
; #define PG8_MMA(ai, bj, At, Bt) do { __builtin_amdgcn_s_setprio(1); _Pragma("unroll") for (int m = 0; m < 4; ++m) _Pragma("unroll") for (int n = 0; n < 2; ++n) _Pragma("unroll") for (int k = 0; k < 2; ++k) \
;         acc[ai][bj][m][n] = __builtin_amdgcn_mfma_f32_16x16x32_bf16(Bt[n][k], At[m][k], acc[ai][bj][m][n], 0, 0, 0); __builtin_amdgcn_s_setprio(0); } while (0)
; #define PG8_WAIT_V(n) asm volatile("s_waitcnt vmcnt(" #n ")" ::: "memory")
; #define PG8_WAIT_L(n) asm volatile("s_waitcnt lgkmcnt(" #n ")" ::: "memory")
; #define PG8_BAR __builtin_amdgcn_s_barrier()
; #define PG8_SCHED __builtin_amdgcn_sched_barrier(0)
; template <class Epi, bool ALIGN_EPI = true>
; __device__ __forceinline__ void gemm_phase(LAS unsigned char* lds, const Gemm g, const StaticOrder& S, const Epi& E, int wave_k) {
;     ...
;             PG8_LDA(At, 1, 1); PG8_STAGE(PG8_SB(1, 0), b3, voffB); PG8_STAGE(PG8_SB(1, 1), b3 + hstepB, voffB); PG8_STAGE(PG8_SA(1, 0), a3, voffA);
;             PG8_WAIT_V(8); PG8_WAIT_L(0); PG8_BAR; PG8_MMA(1, 0, At, B0); PG8_MMA(1, 1, At, B1); PG8_BAR; PG8_SCHED;
;         }
;         if constexpr (ALIGN_EPI) { if (wr == 0) PG8_BAR; }
	s_mov_b32 m0, s72
	v_lshl_add_u64 v[158:159], v[158:159], 0, s[22:23]
	ds_read_b128 v[174:177], v137 offset:49152
	ds_read_b128 v[178:181], v137 offset:50176
	ds_read_b128 v[182:185], v137 offset:51200
	ds_read_b128 v[186:189], v137 offset:52224
	ds_read_b128 v[190:193], v137 offset:53248
	ds_read_b128 v[194:197], v137 offset:54272
	ds_read_b128 v[198:201], v137 offset:55296
	ds_read_b128 v[202:205], v137 offset:56320
	global_load_lds_dwordx4 v[158:159], off
	v_lshl_add_u64 v[158:159], v[206:207], 0, s[22:23]
	s_mov_b32 m0, s71
	s_nop 0
	global_load_lds_dwordx4 v[158:159], off
	s_mov_b32 m0, s80
	s_nop 0
	global_load_lds_dwordx4 v160, s[16:17]
	s_mov_b32 m0, s79
	s_nop 0
	global_load_lds_dwordx4 v132, s[16:17]
	v_lshl_add_u64 v[158:159], v[208:209], 0, s[22:23]
	s_mov_b32 m0, s62
	s_nop 0
	global_load_lds_dwordx4 v[158:159], off
	v_lshl_add_u64 v[158:159], v[210:211], 0, s[22:23]
	s_mov_b32 m0, s63
	s_nop 0
	global_load_lds_dwordx4 v[158:159], off
	s_waitcnt vmcnt(8) lgkmcnt(0)
	s_barrier
	s_setprio 1
	v_mfma_f32_16x16x32_bf16 v[60:63], v[138:141], v[174:177], v[60:63]
	v_mfma_f32_16x16x32_bf16 v[56:59], v[146:149], v[174:177], v[56:59]
	v_mfma_f32_16x16x32_bf16 v[52:55], v[138:141], v[182:185], v[52:55]
	v_mfma_f32_16x16x32_bf16 v[48:51], v[146:149], v[182:185], v[48:51]
	v_mfma_f32_16x16x32_bf16 v[36:39], v[138:141], v[190:193], v[36:39]
	v_mfma_f32_16x16x32_bf16 v[32:35], v[146:149], v[190:193], v[32:35]
	v_mfma_f32_16x16x32_bf16 v[20:23], v[138:141], v[198:201], v[20:23]
	v_mfma_f32_16x16x32_bf16 v[16:19], v[146:149], v[198:201], v[16:19]
	v_mfma_f32_16x16x32_bf16 v[60:63], v[142:145], v[178:181], v[60:63]
	v_mfma_f32_16x16x32_bf16 v[56:59], v[150:153], v[178:181], v[56:59]
	v_mfma_f32_16x16x32_bf16 v[52:55], v[142:145], v[186:189], v[52:55]
	v_mfma_f32_16x16x32_bf16 v[48:51], v[150:153], v[186:189], v[48:51]
	v_mfma_f32_16x16x32_bf16 v[36:39], v[142:145], v[194:197], v[36:39]
	v_mfma_f32_16x16x32_bf16 v[32:35], v[150:153], v[194:197], v[32:35]
	v_mfma_f32_16x16x32_bf16 v[20:23], v[142:145], v[202:205], v[20:23]
	v_mfma_f32_16x16x32_bf16 v[16:19], v[150:153], v[202:205], v[16:19]
	v_mfma_f32_16x16x32_bf16 v[44:47], v[154:157], v[174:177], v[44:47]
	v_mfma_f32_16x16x32_bf16 v[40:43], v[166:169], v[174:177], v[40:43]
	v_mfma_f32_16x16x32_bf16 v[28:31], v[154:157], v[182:185], v[28:31]
	v_mfma_f32_16x16x32_bf16 v[24:27], v[166:169], v[182:185], v[24:27]
	v_mfma_f32_16x16x32_bf16 v[12:15], v[154:157], v[190:193], v[12:15]
	v_mfma_f32_16x16x32_bf16 v[8:11], v[166:169], v[190:193], v[8:11]
	v_mfma_f32_16x16x32_bf16 v[4:7], v[154:157], v[198:201], v[4:7]
	v_mfma_f32_16x16x32_bf16 v[0:3], v[166:169], v[198:201], v[0:3]
	v_mfma_f32_16x16x32_bf16 v[44:47], v[162:165], v[178:181], v[44:47]
	v_mfma_f32_16x16x32_bf16 v[40:43], v[170:173], v[178:181], v[40:43]
	v_mfma_f32_16x16x32_bf16 v[28:31], v[162:165], v[186:189], v[28:31]
	v_mfma_f32_16x16x32_bf16 v[24:27], v[170:173], v[186:189], v[24:27]
	v_mfma_f32_16x16x32_bf16 v[12:15], v[162:165], v[194:197], v[12:15]
	v_mfma_f32_16x16x32_bf16 v[8:11], v[170:173], v[194:197], v[8:11]
	v_mfma_f32_16x16x32_bf16 v[4:7], v[162:165], v[202:205], v[4:7]
	v_mfma_f32_16x16x32_bf16 v[0:3], v[170:173], v[202:205], v[0:3]
	s_setprio 0
	s_barrier
	s_movk_i32 s24, 0x100
	s_andn2_b64 vcc, exec, s[44:45]
	s_mov_b64 s[16:17], -1
	s_mov_b64 s[44:45], 0
	s_cbranch_vccz .LBB0_800
	s_and_b64 vcc, exec, s[14:15]
	s_cbranch_vccz .LBB0_803
	s_barrier

; #define PG8_STAGE(bufoff, gbase, voff) do { _Pragma("unroll") for (int _i = 0; _i < 2; ++_i) \
;         __builtin_amdgcn_global_load_lds((const unsigned*)((const char*)(gbase) + (voff)[_i]), (LAS unsigned*)(lds + (bufoff) + ldsw + _i * 8192), 16, 0, 0); } while (0)
; #define PG8_LDA(dst, b, h) do { _Pragma("unroll") for (int m = 0; m < 4; ++m) _Pragma("unroll") for (int k = 0; k < 2; ++k) dst[m][k] = *(const LAS bf16x8*)(lds + PG8_SA(b, h) + aoff + m * 2048 + k * 1024); } while (0)
; #define PG8_LDB(dst, b, h) do { _Pragma("unroll") for (int n = 0; n < 2; ++n) _Pragma("unroll") for (int k = 0; k < 2; ++k) dst[n][k] = *(const LAS bf16x8*)(lds + PG8_SB(b, h) + boff + n * 2048 + k * 1024); } while (0)
; #define PG8_MMA(ai, bj, At, Bt) do { __builtin_amdgcn_s_setprio(1); _Pragma("unroll") for (int m = 0; m < 4; ++m) _Pragma("unroll") for (int n = 0; n < 2; ++n) _Pragma("unroll") for (int k = 0; k < 2; ++k) \
;         acc[ai][bj][m][n] = __builtin_amdgcn_mfma_f32_16x16x32_bf16(Bt[n][k], At[m][k], acc[ai][bj][m][n], 0, 0, 0); __builtin_amdgcn_s_setprio(0); } while (0)
; #define PG8_BAR __builtin_amdgcn_s_barrier()
; template <class Epi, bool ALIGN_EPI = true>
; __device__ __forceinline__ void gemm_phase(LAS unsigned char* lds, const Gemm g, const StaticOrder& S, const Epi& E, int wave_k) {
;     ...
;         const bool has_next = S.next(ui + 1, nxt);
;         const char* nA = has_next ? (const char*)g.A + (size_t)nxt.pm * tstepA : cA; const char* nB = has_next ? (const char*)g.Bt + (size_t)nxt.pn * tstepB : cB;
;         for (int t = 0; t < nt; t += 2) {
;             const bool last = (t == nt - 2);
;             const char* a1 = cA + (size_t)(t + 1) * kstep;
;             const char* a2 = last ? nA : cA + (size_t)(t + 2) * kstep; const char* b2 = last ? nB : cB + (size_t)(t + 2) * kstep;
;             const char* a3 = a2 + kstep; const char* b3 = b2 + kstep;
;             PG8_LDB(B0, 0, 0); PG8_LDB(B1, 0, 1); PG8_SCHED; PG8_LDA(At, 0, 0); PG8_STAGE(PG8_SA(1, 1), a1 + hstepA, voffA);
;             PG8_WAIT_V(8); PG8_WAIT_L(0); PG8_BAR; PG8_MMA(0, 0, At, B0); PG8_MMA(0, 1, At, B1); PG8_BAR; PG8_SCHED;
;             PG8_LDA(At, 0, 1); PG8_STAGE(PG8_SB(0, 0), b2, voffB); PG8_STAGE(PG8_SB(0, 1), b2 + hstepB, voffB); PG8_STAGE(PG8_SA(0, 0), a2, voffA);
;             PG8_WAIT_V(8); PG8_WAIT_L(0); PG8_BAR; PG8_MMA(1, 0, At, B0); PG8_MMA(1, 1, At, B1); PG8_BAR; PG8_SCHED;
.LBB0_886:
	s_add_u32 s16, s46, 0xfffe0080
	s_addc_u32 s17, s47, -1
	s_add_i32 s65, 0, 0x10000
	s_cmp_eq_u32 s64, 4
	s_cselect_b32 s25, s26, s17
	s_cselect_b32 s24, s27, s16
	s_cselect_b32 s17, s21, s63
	s_cselect_b32 s16, s35, s62
	s_add_i32 s68, 0, 0x14000
	v_add_u32_e32 v154, s65, v143
	v_add_u32_e32 v158, s68, v143
	ds_read_b128 v[138:141], v154
	ds_read_b128 v[146:149], v154 offset:1024
	ds_read_b128 v[150:153], v154 offset:2048
	ds_read_b128 v[154:157], v154 offset:3072
	ds_read_b128 v[162:165], v158
	ds_read_b128 v[166:169], v158 offset:1024
	ds_read_b128 v[170:173], v158 offset:2048
	ds_read_b128 v[174:177], v158 offset:3072
	s_add_i32 m0, s45, 0xc000
	ds_read_b128 v[178:181], v145
	ds_read_b128 v[182:185], v145 offset:1024
	ds_read_b128 v[186:189], v145 offset:2048
	ds_read_b128 v[190:193], v145 offset:3072
	ds_read_b128 v[194:197], v145 offset:4096
	ds_read_b128 v[198:201], v145 offset:5120
	ds_read_b128 v[202:205], v145 offset:6144
	ds_read_b128 v[206:209], v145 offset:7168
	global_load_lds_dwordx4 v134, s[46:47]
	s_add_i32 m0, s45, 0xe000
	s_nop 0
	global_load_lds_dwordx4 v136, s[46:47]
	s_waitcnt vmcnt(8) lgkmcnt(0)
	s_barrier
	s_setprio 1
	v_mfma_f32_16x16x32_bf16 v[124:127], v[138:141], v[178:181], v[124:127]
	v_mfma_f32_16x16x32_bf16 v[120:123], v[150:153], v[178:181], v[120:123]
	v_mfma_f32_16x16x32_bf16 v[108:111], v[138:141], v[186:189], v[108:111]
	v_mfma_f32_16x16x32_bf16 v[104:107], v[150:153], v[186:189], v[104:107]
	v_mfma_f32_16x16x32_bf16 v[92:95], v[138:141], v[194:197], v[92:95]
	v_mfma_f32_16x16x32_bf16 v[88:91], v[150:153], v[194:197], v[88:91]
	v_mfma_f32_16x16x32_bf16 v[76:79], v[138:141], v[202:205], v[76:79]
	v_mfma_f32_16x16x32_bf16 v[72:75], v[150:153], v[202:205], v[72:75]
	v_mfma_f32_16x16x32_bf16 v[124:127], v[146:149], v[182:185], v[124:127]
	v_mfma_f32_16x16x32_bf16 v[120:123], v[154:157], v[182:185], v[120:123]
	v_mfma_f32_16x16x32_bf16 v[108:111], v[146:149], v[190:193], v[108:111]
	v_mfma_f32_16x16x32_bf16 v[104:107], v[154:157], v[190:193], v[104:107]
	v_mfma_f32_16x16x32_bf16 v[92:95], v[146:149], v[198:201], v[92:95]
	v_mfma_f32_16x16x32_bf16 v[88:91], v[154:157], v[198:201], v[88:91]
	v_mfma_f32_16x16x32_bf16 v[76:79], v[146:149], v[206:209], v[76:79]
	v_mfma_f32_16x16x32_bf16 v[72:75], v[154:157], v[206:209], v[72:75]
	v_mfma_f32_16x16x32_bf16 v[116:119], v[162:165], v[178:181], v[116:119]
	v_mfma_f32_16x16x32_bf16 v[112:115], v[170:173], v[178:181], v[112:115]
	v_mfma_f32_16x16x32_bf16 v[100:103], v[162:165], v[186:189], v[100:103]
	v_mfma_f32_16x16x32_bf16 v[96:99], v[170:173], v[186:189], v[96:99]
	v_mfma_f32_16x16x32_bf16 v[84:87], v[162:165], v[194:197], v[84:87]
	v_mfma_f32_16x16x32_bf16 v[80:83], v[170:173], v[194:197], v[80:83]
	v_mfma_f32_16x16x32_bf16 v[68:71], v[162:165], v[202:205], v[68:71]
	v_mfma_f32_16x16x32_bf16 v[64:67], v[170:173], v[202:205], v[64:67]
	v_mfma_f32_16x16x32_bf16 v[116:119], v[166:169], v[182:185], v[116:119]
	v_mfma_f32_16x16x32_bf16 v[112:115], v[174:177], v[182:185], v[112:115]
	v_mfma_f32_16x16x32_bf16 v[100:103], v[166:169], v[190:193], v[100:103]
	v_mfma_f32_16x16x32_bf16 v[96:99], v[174:177], v[190:193], v[96:99]
	v_mfma_f32_16x16x32_bf16 v[84:87], v[166:169], v[198:201], v[84:87]
	v_mfma_f32_16x16x32_bf16 v[80:83], v[174:177], v[198:201], v[80:83]
	v_mfma_f32_16x16x32_bf16 v[68:71], v[166:169], v[206:209], v[68:71]
	v_mfma_f32_16x16x32_bf16 v[64:67], v[174:177], v[206:209], v[64:67]
	s_setprio 0
	s_barrier
	s_add_i32 s65, s65, s53
	v_lshl_add_u64 v[158:159], s[16:17], 0, v[160:161]
	s_mov_b32 m0, s65
	ds_read_b128 v[178:181], v145 offset:16384
	ds_read_b128 v[182:185], v145 offset:17408
	ds_read_b128 v[186:189], v145 offset:18432
	ds_read_b128 v[190:193], v145 offset:19456
	ds_read_b128 v[194:197], v145 offset:20480
	ds_read_b128 v[198:201], v145 offset:21504
	ds_read_b128 v[202:205], v145 offset:22528
	ds_read_b128 v[206:209], v145 offset:23552
	global_load_lds_dwordx4 v[158:159], off
	s_add_i32 m0, s65, 0x2000
	s_add_u32 s66, s16, 0x20000
	v_lshl_add_u64 v[210:211], s[16:17], 0, v[132:133]
	s_addc_u32 s67, s17, 0
	s_add_i32 s65, s68, s53
	global_load_lds_dwordx4 v[210:211], off
	s_mov_b32 m0, s65
	v_lshl_add_u64 v[218:219], s[24:25], 0, v[130:131]
	global_load_lds_dwordx4 v160, s[66:67]
	s_add_i32 m0, s65, 0x2000
	s_nop 0
	global_load_lds_dwordx4 v132, s[66:67]
	v_lshl_add_u64 v[212:213], s[24:25], 0, v[128:129]
	s_mov_b32 m0, s45
	s_nop 0
	global_load_lds_dwordx4 v[212:213], off
	s_mov_b32 m0, s54
	s_nop 0
	global_load_lds_dwordx4 v[218:219], off
	s_waitcnt vmcnt(8) lgkmcnt(0)
	s_barrier
; #define PG8_STAGE(bufoff, gbase, voff) do { _Pragma("unroll") for (int _i = 0; _i < 2; ++_i) \
;         __builtin_amdgcn_global_load_lds((const unsigned*)((const char*)(gbase) + (voff)[_i]), (LAS unsigned*)(lds + (bufoff) + ldsw + _i * 8192), 16, 0, 0); } while (0)
; #define PG8_LDA(dst, b, h) do { _Pragma("unroll") for (int m = 0; m < 4; ++m) _Pragma("unroll") for (int k = 0; k < 2; ++k) dst[m][k] = *(const LAS bf16x8*)(lds + PG8_SA(b, h) + aoff + m * 2048 + k * 1024); } while (0)
; #define PG8_LDB(dst, b, h) do { _Pragma("unroll") for (int n = 0; n < 2; ++n) _Pragma("unroll") for (int k = 0; k < 2; ++k) dst[n][k] = *(const LAS bf16x8*)(lds + PG8_SB(b, h) + boff + n * 2048 + k * 1024); } while (0)
; #define PG8_MMA(ai, bj, At, Bt) do { __builtin_amdgcn_s_setprio(1); _Pragma("unroll") for (int m = 0; m < 4; ++m) _Pragma("unroll") for (int n = 0; n < 2; ++n) _Pragma("unroll") for (int k = 0; k < 2; ++k) \
;         acc[ai][bj][m][n] = __builtin_amdgcn_mfma_f32_16x16x32_bf16(Bt[n][k], At[m][k], acc[ai][bj][m][n], 0, 0, 0); __builtin_amdgcn_s_setprio(0); } while (0)
; #define PG8_WAIT_V(n) asm volatile("s_waitcnt vmcnt(" #n ")" ::: "memory")
; #define PG8_WAIT_L(n) asm volatile("s_waitcnt lgkmcnt(" #n ")" ::: "memory")
; #define PG8_BAR __builtin_amdgcn_s_barrier()
; #define PG8_SCHED __builtin_amdgcn_sched_barrier(0)
; template <class Epi, bool ALIGN_EPI = true>
; __device__ __forceinline__ void gemm_phase(LAS unsigned char* lds, const Gemm g, const StaticOrder& S, const Epi& E, int wave_k) {
;     ...
;             PG8_WAIT_V(8); PG8_WAIT_L(0); PG8_BAR; PG8_MMA(1, 0, At, B0); PG8_MMA(1, 1, At, B1); PG8_BAR; PG8_SCHED;
;             PG8_LDB(B0, 1, 0); PG8_LDB(B1, 1, 1); PG8_SCHED; PG8_LDA(At, 1, 0); PG8_STAGE(PG8_SA(0, 1), a2 + hstepA, voffA);
;             PG8_WAIT_V(8); PG8_WAIT_L(0); PG8_BAR; PG8_MMA(0, 0, At, B0); PG8_MMA(0, 1, At, B1); PG8_BAR; PG8_SCHED;
	s_setprio 1
	v_mfma_f32_16x16x32_bf16 v[60:63], v[138:141], v[178:181], v[60:63]
	v_mfma_f32_16x16x32_bf16 v[56:59], v[150:153], v[178:181], v[56:59]
	v_mfma_f32_16x16x32_bf16 v[44:47], v[138:141], v[186:189], v[44:47]
	v_mfma_f32_16x16x32_bf16 v[40:43], v[150:153], v[186:189], v[40:43]
	v_mfma_f32_16x16x32_bf16 v[28:31], v[138:141], v[194:197], v[28:31]
	v_mfma_f32_16x16x32_bf16 v[24:27], v[150:153], v[194:197], v[24:27]
	v_mfma_f32_16x16x32_bf16 v[12:15], v[138:141], v[202:205], v[12:15]
	v_mfma_f32_16x16x32_bf16 v[8:11], v[150:153], v[202:205], v[8:11]
	v_mfma_f32_16x16x32_bf16 v[60:63], v[146:149], v[182:185], v[60:63]
	v_mfma_f32_16x16x32_bf16 v[56:59], v[154:157], v[182:185], v[56:59]
	v_mfma_f32_16x16x32_bf16 v[44:47], v[146:149], v[190:193], v[44:47]
	v_mfma_f32_16x16x32_bf16 v[40:43], v[154:157], v[190:193], v[40:43]
	v_mfma_f32_16x16x32_bf16 v[28:31], v[146:149], v[198:201], v[28:31]
	v_mfma_f32_16x16x32_bf16 v[24:27], v[154:157], v[198:201], v[24:27]
	v_mfma_f32_16x16x32_bf16 v[12:15], v[146:149], v[206:209], v[12:15]
	v_mfma_f32_16x16x32_bf16 v[8:11], v[154:157], v[206:209], v[8:11]
	v_mfma_f32_16x16x32_bf16 v[52:55], v[162:165], v[178:181], v[52:55]
	v_mfma_f32_16x16x32_bf16 v[48:51], v[170:173], v[178:181], v[48:51]
	v_mfma_f32_16x16x32_bf16 v[36:39], v[162:165], v[186:189], v[36:39]
	v_mfma_f32_16x16x32_bf16 v[32:35], v[170:173], v[186:189], v[32:35]
	v_mfma_f32_16x16x32_bf16 v[20:23], v[162:165], v[194:197], v[20:23]
	v_mfma_f32_16x16x32_bf16 v[16:19], v[170:173], v[194:197], v[16:19]
	v_mfma_f32_16x16x32_bf16 v[4:7], v[162:165], v[202:205], v[4:7]
	v_mfma_f32_16x16x32_bf16 v[0:3], v[170:173], v[202:205], v[0:3]
	v_mfma_f32_16x16x32_bf16 v[52:55], v[166:169], v[182:185], v[52:55]
	v_mfma_f32_16x16x32_bf16 v[48:51], v[174:177], v[182:185], v[48:51]
	v_mfma_f32_16x16x32_bf16 v[36:39], v[166:169], v[190:193], v[36:39]
	v_mfma_f32_16x16x32_bf16 v[32:35], v[174:177], v[190:193], v[32:35]
	v_mfma_f32_16x16x32_bf16 v[20:23], v[166:169], v[198:201], v[20:23]
	v_mfma_f32_16x16x32_bf16 v[16:19], v[174:177], v[198:201], v[16:19]
	v_mfma_f32_16x16x32_bf16 v[4:7], v[166:169], v[206:209], v[4:7]
	v_mfma_f32_16x16x32_bf16 v[0:3], v[174:177], v[206:209], v[0:3]
	s_setprio 0
	s_barrier
	s_add_i32 s65, 0, 0x18000
	s_add_i32 s66, 0, 0x1c000
	v_add_u32_e32 v154, s65, v143
	v_add_u32_e32 v174, s66, v143
	ds_read_b128 v[138:141], v154
	ds_read_b128 v[146:149], v154 offset:1024
	ds_read_b128 v[150:153], v154 offset:2048
	ds_read_b128 v[154:157], v154 offset:3072
	ds_read_b128 v[162:165], v174
	ds_read_b128 v[166:169], v174 offset:1024
	ds_read_b128 v[170:173], v174 offset:2048
	ds_read_b128 v[174:177], v174 offset:3072
	s_add_u32 s24, s24, 0x20000
	s_addc_u32 s25, s25, 0
	s_mov_b32 m0, s55
	ds_read_b128 v[178:181], v145 offset:32768
	ds_read_b128 v[182:185], v145 offset:33792
	ds_read_b128 v[186:189], v145 offset:34816
	ds_read_b128 v[190:193], v145 offset:35840
	ds_read_b128 v[194:197], v145 offset:36864
	ds_read_b128 v[198:201], v145 offset:37888
	ds_read_b128 v[202:205], v145 offset:38912
	ds_read_b128 v[206:209], v145 offset:39936
	global_load_lds_dwordx4 v128, s[24:25]
	s_mov_b32 m0, s56
	s_nop 0
	global_load_lds_dwordx4 v130, s[24:25]
	s_waitcnt vmcnt(8) lgkmcnt(0)
	s_barrier
	s_setprio 1
	v_mfma_f32_16x16x32_bf16 v[124:127], v[138:141], v[178:181], v[124:127]
	v_mfma_f32_16x16x32_bf16 v[120:123], v[150:153], v[178:181], v[120:123]
	v_mfma_f32_16x16x32_bf16 v[108:111], v[138:141], v[186:189], v[108:111]
	v_mfma_f32_16x16x32_bf16 v[104:107], v[150:153], v[186:189], v[104:107]
	v_mfma_f32_16x16x32_bf16 v[92:95], v[138:141], v[194:197], v[92:95]
	v_mfma_f32_16x16x32_bf16 v[88:91], v[150:153], v[194:197], v[88:91]
	v_mfma_f32_16x16x32_bf16 v[76:79], v[138:141], v[202:205], v[76:79]
	v_mfma_f32_16x16x32_bf16 v[72:75], v[150:153], v[202:205], v[72:75]
	v_mfma_f32_16x16x32_bf16 v[124:127], v[146:149], v[182:185], v[124:127]
	v_mfma_f32_16x16x32_bf16 v[120:123], v[154:157], v[182:185], v[120:123]
	v_mfma_f32_16x16x32_bf16 v[108:111], v[146:149], v[190:193], v[108:111]
	v_mfma_f32_16x16x32_bf16 v[104:107], v[154:157], v[190:193], v[104:107]
	v_mfma_f32_16x16x32_bf16 v[92:95], v[146:149], v[198:201], v[92:95]
	v_mfma_f32_16x16x32_bf16 v[88:91], v[154:157], v[198:201], v[88:91]
	v_mfma_f32_16x16x32_bf16 v[76:79], v[146:149], v[206:209], v[76:79]
	v_mfma_f32_16x16x32_bf16 v[72:75], v[154:157], v[206:209], v[72:75]
	v_mfma_f32_16x16x32_bf16 v[116:119], v[162:165], v[178:181], v[116:119]
	v_mfma_f32_16x16x32_bf16 v[112:115], v[170:173], v[178:181], v[112:115]
	v_mfma_f32_16x16x32_bf16 v[100:103], v[162:165], v[186:189], v[100:103]
	v_mfma_f32_16x16x32_bf16 v[96:99], v[170:173], v[186:189], v[96:99]
	v_mfma_f32_16x16x32_bf16 v[84:87], v[162:165], v[194:197], v[84:87]
	v_mfma_f32_16x16x32_bf16 v[80:83], v[170:173], v[194:197], v[80:83]
	v_mfma_f32_16x16x32_bf16 v[68:71], v[162:165], v[202:205], v[68:71]
	v_mfma_f32_16x16x32_bf16 v[64:67], v[170:173], v[202:205], v[64:67]
	v_mfma_f32_16x16x32_bf16 v[116:119], v[166:169], v[182:185], v[116:119]
	v_mfma_f32_16x16x32_bf16 v[112:115], v[174:177], v[182:185], v[112:115]
	v_mfma_f32_16x16x32_bf16 v[100:103], v[166:169], v[190:193], v[100:103]
	v_mfma_f32_16x16x32_bf16 v[96:99], v[174:177], v[190:193], v[96:99]
	v_mfma_f32_16x16x32_bf16 v[84:87], v[166:169], v[198:201], v[84:87]
	v_mfma_f32_16x16x32_bf16 v[80:83], v[174:177], v[198:201], v[80:83]
	v_mfma_f32_16x16x32_bf16 v[68:71], v[166:169], v[206:209], v[68:71]
	v_mfma_f32_16x16x32_bf16 v[64:67], v[174:177], v[206:209], v[64:67]
	s_setprio 0
	s_barrier
; #define PG8_STAGE(bufoff, gbase, voff) do { _Pragma("unroll") for (int _i = 0; _i < 2; ++_i) \
;         __builtin_amdgcn_global_load_lds((const unsigned*)((const char*)(gbase) + (voff)[_i]), (LAS unsigned*)(lds + (bufoff) + ldsw + _i * 8192), 16, 0, 0); } while (0)
; #define PG8_LDA(dst, b, h) do { _Pragma("unroll") for (int m = 0; m < 4; ++m) _Pragma("unroll") for (int k = 0; k < 2; ++k) dst[m][k] = *(const LAS bf16x8*)(lds + PG8_SA(b, h) + aoff + m * 2048 + k * 1024); } while (0)
; #define PG8_MMA(ai, bj, At, Bt) do { __builtin_amdgcn_s_setprio(1); _Pragma("unroll") for (int m = 0; m < 4; ++m) _Pragma("unroll") for (int n = 0; n < 2; ++n) _Pragma("unroll") for (int k = 0; k < 2; ++k) \
;         acc[ai][bj][m][n] = __builtin_amdgcn_mfma_f32_16x16x32_bf16(Bt[n][k], At[m][k], acc[ai][bj][m][n], 0, 0, 0); __builtin_amdgcn_s_setprio(0); } while (0)
; #define PG8_WAIT_V(n) asm volatile("s_waitcnt vmcnt(" #n ")" ::: "memory")
; #define PG8_WAIT_L(n) asm volatile("s_waitcnt lgkmcnt(" #n ")" ::: "memory")
; #define PG8_BAR __builtin_amdgcn_s_barrier()
; #define PG8_SCHED __builtin_amdgcn_sched_barrier(0)
; template <class Epi, bool ALIGN_EPI = true>
; __device__ __forceinline__ void gemm_phase(LAS unsigned char* lds, const Gemm g, const StaticOrder& S, const Epi& E, int wave_k) {
;     ...
;             PG8_LDA(At, 1, 1); PG8_STAGE(PG8_SB(1, 0), b3, voffB); PG8_STAGE(PG8_SB(1, 1), b3 + hstepB, voffB); PG8_STAGE(PG8_SA(1, 0), a3, voffA);
;             PG8_WAIT_V(8); PG8_WAIT_L(0); PG8_BAR; PG8_MMA(1, 0, At, B0); PG8_MMA(1, 1, At, B1); PG8_BAR; PG8_SCHED;
;         }
;         if constexpr (ALIGN_EPI) { if (wr == 0) PG8_BAR; }
	s_add_i32 s24, s65, s53
	v_lshl_add_u64 v[158:159], v[158:159], 0, s[22:23]
	s_mov_b32 m0, s24
	ds_read_b128 v[178:181], v145 offset:49152
	ds_read_b128 v[182:185], v145 offset:50176
	ds_read_b128 v[186:189], v145 offset:51200
	ds_read_b128 v[190:193], v145 offset:52224
	ds_read_b128 v[194:197], v145 offset:53248
	ds_read_b128 v[198:201], v145 offset:54272
	ds_read_b128 v[202:205], v145 offset:55296
	ds_read_b128 v[206:209], v145 offset:56320
	global_load_lds_dwordx4 v[158:159], off
	s_add_i32 m0, s24, 0x2000
	s_add_u32 s16, s16, 0x20080
	v_lshl_add_u64 v[158:159], v[210:211], 0, s[22:23]
	s_addc_u32 s17, s17, 0
	s_add_i32 s24, s66, s53
	global_load_lds_dwordx4 v[158:159], off
	s_mov_b32 m0, s24
	s_nop 0
	global_load_lds_dwordx4 v160, s[16:17]
	s_add_i32 m0, s24, 0x2000
	s_nop 0
	global_load_lds_dwordx4 v132, s[16:17]
	v_lshl_add_u64 v[158:159], v[212:213], 0, s[22:23]
	s_mov_b32 m0, s57
	s_nop 0
	global_load_lds_dwordx4 v[158:159], off
	v_lshl_add_u64 v[158:159], v[218:219], 0, s[22:23]
	s_mov_b32 m0, s58
	s_nop 0
	global_load_lds_dwordx4 v[158:159], off
	s_waitcnt vmcnt(8) lgkmcnt(0)
	s_barrier
	s_setprio 1
	v_mfma_f32_16x16x32_bf16 v[60:63], v[138:141], v[178:181], v[60:63]
	v_mfma_f32_16x16x32_bf16 v[56:59], v[150:153], v[178:181], v[56:59]
	v_mfma_f32_16x16x32_bf16 v[44:47], v[138:141], v[186:189], v[44:47]
	v_mfma_f32_16x16x32_bf16 v[40:43], v[150:153], v[186:189], v[40:43]
	v_mfma_f32_16x16x32_bf16 v[28:31], v[138:141], v[194:197], v[28:31]
	v_mfma_f32_16x16x32_bf16 v[24:27], v[150:153], v[194:197], v[24:27]
	v_mfma_f32_16x16x32_bf16 v[12:15], v[138:141], v[202:205], v[12:15]
	v_mfma_f32_16x16x32_bf16 v[8:11], v[150:153], v[202:205], v[8:11]
	v_mfma_f32_16x16x32_bf16 v[60:63], v[146:149], v[182:185], v[60:63]
	v_mfma_f32_16x16x32_bf16 v[56:59], v[154:157], v[182:185], v[56:59]
	v_mfma_f32_16x16x32_bf16 v[44:47], v[146:149], v[190:193], v[44:47]
	v_mfma_f32_16x16x32_bf16 v[40:43], v[154:157], v[190:193], v[40:43]
	v_mfma_f32_16x16x32_bf16 v[28:31], v[146:149], v[198:201], v[28:31]
	v_mfma_f32_16x16x32_bf16 v[24:27], v[154:157], v[198:201], v[24:27]
	v_mfma_f32_16x16x32_bf16 v[12:15], v[146:149], v[206:209], v[12:15]
	v_mfma_f32_16x16x32_bf16 v[8:11], v[154:157], v[206:209], v[8:11]
	v_mfma_f32_16x16x32_bf16 v[52:55], v[162:165], v[178:181], v[52:55]
	v_mfma_f32_16x16x32_bf16 v[48:51], v[170:173], v[178:181], v[48:51]
	v_mfma_f32_16x16x32_bf16 v[36:39], v[162:165], v[186:189], v[36:39]
	v_mfma_f32_16x16x32_bf16 v[32:35], v[170:173], v[186:189], v[32:35]
	v_mfma_f32_16x16x32_bf16 v[20:23], v[162:165], v[194:197], v[20:23]
	v_mfma_f32_16x16x32_bf16 v[16:19], v[170:173], v[194:197], v[16:19]
	v_mfma_f32_16x16x32_bf16 v[4:7], v[162:165], v[202:205], v[4:7]
	v_mfma_f32_16x16x32_bf16 v[0:3], v[170:173], v[202:205], v[0:3]
	v_mfma_f32_16x16x32_bf16 v[52:55], v[166:169], v[182:185], v[52:55]
	v_mfma_f32_16x16x32_bf16 v[48:51], v[174:177], v[182:185], v[48:51]
	v_mfma_f32_16x16x32_bf16 v[36:39], v[166:169], v[190:193], v[36:39]
	v_mfma_f32_16x16x32_bf16 v[32:35], v[174:177], v[190:193], v[32:35]
	v_mfma_f32_16x16x32_bf16 v[20:23], v[166:169], v[198:201], v[20:23]
	v_mfma_f32_16x16x32_bf16 v[16:19], v[174:177], v[198:201], v[16:19]
	v_mfma_f32_16x16x32_bf16 v[4:7], v[166:169], v[206:209], v[4:7]
	v_mfma_f32_16x16x32_bf16 v[0:3], v[174:177], v[206:209], v[0:3]
	s_setprio 0
	s_barrier
	s_add_i32 s64, s64, 2
	s_add_u32 s46, s46, 0x100
	s_addc_u32 s47, s47, 0
	s_add_u32 s62, s62, 0x100
	s_addc_u32 s63, s63, 0
	s_cmp_gt_u32 s64, 5
	s_cbranch_scc0 .LBB0_886
	s_and_b64 vcc, exec, s[18:19]
	s_cbranch_vccz .LBB0_889
	s_barrier

; #define PG8_STAGE(bufoff, gbase, voff) do { _Pragma("unroll") for (int _i = 0; _i < 2; ++_i) \
;         __builtin_amdgcn_global_load_lds((const unsigned*)((const char*)(gbase) + (voff)[_i]), (LAS unsigned*)(lds + (bufoff) + ldsw + _i * 8192), 16, 0, 0); } while (0)
; #define PG8_LDA(dst, b, h) do { _Pragma("unroll") for (int m = 0; m < 4; ++m) _Pragma("unroll") for (int k = 0; k < 2; ++k) dst[m][k] = *(const LAS bf16x8*)(lds + PG8_SA(b, h) + aoff + m * 2048 + k * 1024); } while (0)
; #define PG8_LDB(dst, b, h) do { _Pragma("unroll") for (int n = 0; n < 2; ++n) _Pragma("unroll") for (int k = 0; k < 2; ++k) dst[n][k] = *(const LAS bf16x8*)(lds + PG8_SB(b, h) + boff + n * 2048 + k * 1024); } while (0)
; #define PG8_MMA(ai, bj, At, Bt) do { __builtin_amdgcn_s_setprio(1); _Pragma("unroll") for (int m = 0; m < 4; ++m) _Pragma("unroll") for (int n = 0; n < 2; ++n) _Pragma("unroll") for (int k = 0; k < 2; ++k) \
;         acc[ai][bj][m][n] = __builtin_amdgcn_mfma_f32_16x16x32_bf16(Bt[n][k], At[m][k], acc[ai][bj][m][n], 0, 0, 0); __builtin_amdgcn_s_setprio(0); } while (0)
; #define PG8_BAR __builtin_amdgcn_s_barrier()
; template <class Epi, bool ALIGN_EPI = true>
; __device__ __forceinline__ void gemm_phase(LAS unsigned char* lds, const Gemm g, const StaticOrder& S, const Epi& E, int wave_k) {
;     ...
;         const bool has_next = S.next(ui + 1, nxt);
;         const char* nA = has_next ? (const char*)g.A + (size_t)nxt.pm * tstepA : cA; const char* nB = has_next ? (const char*)g.Bt + (size_t)nxt.pn * tstepB : cB;
;         for (int t = 0; t < nt; t += 2) {
;             const bool last = (t == nt - 2);
;             const char* a1 = cA + (size_t)(t + 1) * kstep;
;             const char* a2 = last ? nA : cA + (size_t)(t + 2) * kstep; const char* b2 = last ? nB : cB + (size_t)(t + 2) * kstep;
;             const char* a3 = a2 + kstep; const char* b3 = b2 + kstep;
;             PG8_LDB(B0, 0, 0); PG8_LDB(B1, 0, 1); PG8_SCHED; PG8_LDA(At, 0, 0); PG8_STAGE(PG8_SA(1, 1), a1 + hstepA, voffA);
;             PG8_WAIT_V(8); PG8_WAIT_L(0); PG8_BAR; PG8_MMA(0, 0, At, B0); PG8_MMA(0, 1, At, B1); PG8_BAR; PG8_SCHED;
;             PG8_LDA(At, 0, 1); PG8_STAGE(PG8_SB(0, 0), b2, voffB); PG8_STAGE(PG8_SB(0, 1), b2 + hstepB, voffB); PG8_STAGE(PG8_SA(0, 0), a2, voffA);
;             PG8_WAIT_V(8); PG8_WAIT_L(0); PG8_BAR; PG8_MMA(1, 0, At, B0); PG8_MMA(1, 1, At, B1); PG8_BAR; PG8_SCHED;
.LBB0_1057:
	s_add_u32 s16, s50, 0xfffc0080
	s_addc_u32 s17, s51, -1
	s_add_i32 s71, 0, 0x10000
	s_cmp_eq_u32 s70, 12
	s_cselect_b32 s25, s26, s17
	s_cselect_b32 s24, s27, s16
	s_cselect_b32 s17, s1, s67
	s_cselect_b32 s16, s35, s66
	s_add_i32 s74, 0, 0x14000
	v_add_u32_e32 v154, s71, v143
	v_add_u32_e32 v158, s74, v143
	ds_read_b128 v[138:141], v154
	ds_read_b128 v[146:149], v154 offset:1024
	ds_read_b128 v[150:153], v154 offset:2048
	ds_read_b128 v[154:157], v154 offset:3072
	ds_read_b128 v[162:165], v158
	ds_read_b128 v[166:169], v158 offset:1024
	ds_read_b128 v[170:173], v158 offset:2048
	ds_read_b128 v[174:177], v158 offset:3072
	s_add_i32 m0, s47, 0xc000
	ds_read_b128 v[178:181], v145
	ds_read_b128 v[182:185], v145 offset:1024
	ds_read_b128 v[186:189], v145 offset:2048
	ds_read_b128 v[190:193], v145 offset:3072
	ds_read_b128 v[194:197], v145 offset:4096
	ds_read_b128 v[198:201], v145 offset:5120
	ds_read_b128 v[202:205], v145 offset:6144
	ds_read_b128 v[206:209], v145 offset:7168
	global_load_lds_dwordx4 v134, s[50:51]
	s_add_i32 m0, s47, 0xe000
	s_nop 0
	global_load_lds_dwordx4 v136, s[50:51]
	s_waitcnt vmcnt(8) lgkmcnt(0)
	s_barrier
	s_setprio 1
	v_mfma_f32_16x16x32_bf16 v[124:127], v[138:141], v[178:181], v[124:127]
	v_mfma_f32_16x16x32_bf16 v[120:123], v[150:153], v[178:181], v[120:123]
	v_mfma_f32_16x16x32_bf16 v[108:111], v[138:141], v[186:189], v[108:111]
	v_mfma_f32_16x16x32_bf16 v[104:107], v[150:153], v[186:189], v[104:107]
	v_mfma_f32_16x16x32_bf16 v[92:95], v[138:141], v[194:197], v[92:95]
	v_mfma_f32_16x16x32_bf16 v[88:91], v[150:153], v[194:197], v[88:91]
	v_mfma_f32_16x16x32_bf16 v[76:79], v[138:141], v[202:205], v[76:79]
	v_mfma_f32_16x16x32_bf16 v[72:75], v[150:153], v[202:205], v[72:75]
	v_mfma_f32_16x16x32_bf16 v[124:127], v[146:149], v[182:185], v[124:127]
	v_mfma_f32_16x16x32_bf16 v[120:123], v[154:157], v[182:185], v[120:123]
	v_mfma_f32_16x16x32_bf16 v[108:111], v[146:149], v[190:193], v[108:111]
	v_mfma_f32_16x16x32_bf16 v[104:107], v[154:157], v[190:193], v[104:107]
	v_mfma_f32_16x16x32_bf16 v[92:95], v[146:149], v[198:201], v[92:95]
	v_mfma_f32_16x16x32_bf16 v[88:91], v[154:157], v[198:201], v[88:91]
	v_mfma_f32_16x16x32_bf16 v[76:79], v[146:149], v[206:209], v[76:79]
	v_mfma_f32_16x16x32_bf16 v[72:75], v[154:157], v[206:209], v[72:75]
	v_mfma_f32_16x16x32_bf16 v[116:119], v[162:165], v[178:181], v[116:119]
	v_mfma_f32_16x16x32_bf16 v[112:115], v[170:173], v[178:181], v[112:115]
	v_mfma_f32_16x16x32_bf16 v[100:103], v[162:165], v[186:189], v[100:103]
	v_mfma_f32_16x16x32_bf16 v[96:99], v[170:173], v[186:189], v[96:99]
	v_mfma_f32_16x16x32_bf16 v[84:87], v[162:165], v[194:197], v[84:87]
	v_mfma_f32_16x16x32_bf16 v[80:83], v[170:173], v[194:197], v[80:83]
	v_mfma_f32_16x16x32_bf16 v[68:71], v[162:165], v[202:205], v[68:71]
	v_mfma_f32_16x16x32_bf16 v[64:67], v[170:173], v[202:205], v[64:67]
	v_mfma_f32_16x16x32_bf16 v[116:119], v[166:169], v[182:185], v[116:119]
	v_mfma_f32_16x16x32_bf16 v[112:115], v[174:177], v[182:185], v[112:115]
	v_mfma_f32_16x16x32_bf16 v[100:103], v[166:169], v[190:193], v[100:103]
	v_mfma_f32_16x16x32_bf16 v[96:99], v[174:177], v[190:193], v[96:99]
	v_mfma_f32_16x16x32_bf16 v[84:87], v[166:169], v[198:201], v[84:87]
	v_mfma_f32_16x16x32_bf16 v[80:83], v[174:177], v[198:201], v[80:83]
	v_mfma_f32_16x16x32_bf16 v[68:71], v[166:169], v[206:209], v[68:71]
	v_mfma_f32_16x16x32_bf16 v[64:67], v[174:177], v[206:209], v[64:67]
	s_setprio 0
	s_barrier
	s_add_i32 s71, s71, s58
	v_lshl_add_u64 v[158:159], s[16:17], 0, v[160:161]
	s_mov_b32 m0, s71
	ds_read_b128 v[178:181], v145 offset:16384
	ds_read_b128 v[182:185], v145 offset:17408
	ds_read_b128 v[186:189], v145 offset:18432
	ds_read_b128 v[190:193], v145 offset:19456
	ds_read_b128 v[194:197], v145 offset:20480
	ds_read_b128 v[198:201], v145 offset:21504
	ds_read_b128 v[202:205], v145 offset:22528
	ds_read_b128 v[206:209], v145 offset:23552
	global_load_lds_dwordx4 v[158:159], off
	s_add_i32 m0, s71, 0x2000
	s_add_u32 s72, s16, 0x40000
	v_lshl_add_u64 v[210:211], s[16:17], 0, v[132:133]
	s_addc_u32 s73, s17, 0
	s_add_i32 s71, s74, s58
	global_load_lds_dwordx4 v[210:211], off
	s_mov_b32 m0, s71
	v_lshl_add_u64 v[218:219], s[24:25], 0, v[130:131]
	global_load_lds_dwordx4 v160, s[72:73]
	s_add_i32 m0, s71, 0x2000
	s_nop 0
	global_load_lds_dwordx4 v132, s[72:73]
	v_lshl_add_u64 v[212:213], s[24:25], 0, v[128:129]
	s_mov_b32 m0, s47
	s_nop 0
	global_load_lds_dwordx4 v[212:213], off
	s_mov_b32 m0, s53
	s_nop 0
	global_load_lds_dwordx4 v[218:219], off
	s_waitcnt vmcnt(8) lgkmcnt(0)
	s_barrier
; #define PG8_STAGE(bufoff, gbase, voff) do { _Pragma("unroll") for (int _i = 0; _i < 2; ++_i) \
;         __builtin_amdgcn_global_load_lds((const unsigned*)((const char*)(gbase) + (voff)[_i]), (LAS unsigned*)(lds + (bufoff) + ldsw + _i * 8192), 16, 0, 0); } while (0)
; #define PG8_LDA(dst, b, h) do { _Pragma("unroll") for (int m = 0; m < 4; ++m) _Pragma("unroll") for (int k = 0; k < 2; ++k) dst[m][k] = *(const LAS bf16x8*)(lds + PG8_SA(b, h) + aoff + m * 2048 + k * 1024); } while (0)
; #define PG8_LDB(dst, b, h) do { _Pragma("unroll") for (int n = 0; n < 2; ++n) _Pragma("unroll") for (int k = 0; k < 2; ++k) dst[n][k] = *(const LAS bf16x8*)(lds + PG8_SB(b, h) + boff + n * 2048 + k * 1024); } while (0)
; #define PG8_MMA(ai, bj, At, Bt) do { __builtin_amdgcn_s_setprio(1); _Pragma("unroll") for (int m = 0; m < 4; ++m) _Pragma("unroll") for (int n = 0; n < 2; ++n) _Pragma("unroll") for (int k = 0; k < 2; ++k) \
;         acc[ai][bj][m][n] = __builtin_amdgcn_mfma_f32_16x16x32_bf16(Bt[n][k], At[m][k], acc[ai][bj][m][n], 0, 0, 0); __builtin_amdgcn_s_setprio(0); } while (0)
; #define PG8_WAIT_V(n) asm volatile("s_waitcnt vmcnt(" #n ")" ::: "memory")
; #define PG8_WAIT_L(n) asm volatile("s_waitcnt lgkmcnt(" #n ")" ::: "memory")
; #define PG8_BAR __builtin_amdgcn_s_barrier()
; #define PG8_SCHED __builtin_amdgcn_sched_barrier(0)
; template <class Epi, bool ALIGN_EPI = true>
; __device__ __forceinline__ void gemm_phase(LAS unsigned char* lds, const Gemm g, const StaticOrder& S, const Epi& E, int wave_k) {
;     ...
;             PG8_WAIT_V(8); PG8_WAIT_L(0); PG8_BAR; PG8_MMA(1, 0, At, B0); PG8_MMA(1, 1, At, B1); PG8_BAR; PG8_SCHED;
;             PG8_LDB(B0, 1, 0); PG8_LDB(B1, 1, 1); PG8_SCHED; PG8_LDA(At, 1, 0); PG8_STAGE(PG8_SA(0, 1), a2 + hstepA, voffA);
;             PG8_WAIT_V(8); PG8_WAIT_L(0); PG8_BAR; PG8_MMA(0, 0, At, B0); PG8_MMA(0, 1, At, B1); PG8_BAR; PG8_SCHED;
	s_setprio 1
	v_mfma_f32_16x16x32_bf16 v[60:63], v[138:141], v[178:181], v[60:63]
	v_mfma_f32_16x16x32_bf16 v[56:59], v[150:153], v[178:181], v[56:59]
	v_mfma_f32_16x16x32_bf16 v[44:47], v[138:141], v[186:189], v[44:47]
	v_mfma_f32_16x16x32_bf16 v[40:43], v[150:153], v[186:189], v[40:43]
	v_mfma_f32_16x16x32_bf16 v[28:31], v[138:141], v[194:197], v[28:31]
	v_mfma_f32_16x16x32_bf16 v[24:27], v[150:153], v[194:197], v[24:27]
	v_mfma_f32_16x16x32_bf16 v[12:15], v[138:141], v[202:205], v[12:15]
	v_mfma_f32_16x16x32_bf16 v[8:11], v[150:153], v[202:205], v[8:11]
	v_mfma_f32_16x16x32_bf16 v[60:63], v[146:149], v[182:185], v[60:63]
	v_mfma_f32_16x16x32_bf16 v[56:59], v[154:157], v[182:185], v[56:59]
	v_mfma_f32_16x16x32_bf16 v[44:47], v[146:149], v[190:193], v[44:47]
	v_mfma_f32_16x16x32_bf16 v[40:43], v[154:157], v[190:193], v[40:43]
	v_mfma_f32_16x16x32_bf16 v[28:31], v[146:149], v[198:201], v[28:31]
	v_mfma_f32_16x16x32_bf16 v[24:27], v[154:157], v[198:201], v[24:27]
	v_mfma_f32_16x16x32_bf16 v[12:15], v[146:149], v[206:209], v[12:15]
	v_mfma_f32_16x16x32_bf16 v[8:11], v[154:157], v[206:209], v[8:11]
	v_mfma_f32_16x16x32_bf16 v[52:55], v[162:165], v[178:181], v[52:55]
	v_mfma_f32_16x16x32_bf16 v[48:51], v[170:173], v[178:181], v[48:51]
	v_mfma_f32_16x16x32_bf16 v[36:39], v[162:165], v[186:189], v[36:39]
	v_mfma_f32_16x16x32_bf16 v[32:35], v[170:173], v[186:189], v[32:35]
	v_mfma_f32_16x16x32_bf16 v[20:23], v[162:165], v[194:197], v[20:23]
	v_mfma_f32_16x16x32_bf16 v[16:19], v[170:173], v[194:197], v[16:19]
	v_mfma_f32_16x16x32_bf16 v[4:7], v[162:165], v[202:205], v[4:7]
	v_mfma_f32_16x16x32_bf16 v[0:3], v[170:173], v[202:205], v[0:3]
	v_mfma_f32_16x16x32_bf16 v[52:55], v[166:169], v[182:185], v[52:55]
	v_mfma_f32_16x16x32_bf16 v[48:51], v[174:177], v[182:185], v[48:51]
	v_mfma_f32_16x16x32_bf16 v[36:39], v[166:169], v[190:193], v[36:39]
	v_mfma_f32_16x16x32_bf16 v[32:35], v[174:177], v[190:193], v[32:35]
	v_mfma_f32_16x16x32_bf16 v[20:23], v[166:169], v[198:201], v[20:23]
	v_mfma_f32_16x16x32_bf16 v[16:19], v[174:177], v[198:201], v[16:19]
	v_mfma_f32_16x16x32_bf16 v[4:7], v[166:169], v[206:209], v[4:7]
	v_mfma_f32_16x16x32_bf16 v[0:3], v[174:177], v[206:209], v[0:3]
	s_setprio 0
	s_barrier
	s_add_i32 s71, 0, 0x18000
	s_add_i32 s72, 0, 0x1c000
	v_add_u32_e32 v154, s71, v143
	v_add_u32_e32 v174, s72, v143
	ds_read_b128 v[138:141], v154
	ds_read_b128 v[146:149], v154 offset:1024
	ds_read_b128 v[150:153], v154 offset:2048
	ds_read_b128 v[154:157], v154 offset:3072
	ds_read_b128 v[162:165], v174
	ds_read_b128 v[166:169], v174 offset:1024
	ds_read_b128 v[170:173], v174 offset:2048
	ds_read_b128 v[174:177], v174 offset:3072
	s_add_u32 s24, s24, 0x40000
	s_addc_u32 s25, s25, 0
	s_mov_b32 m0, s59
	ds_read_b128 v[178:181], v145 offset:32768
	ds_read_b128 v[182:185], v145 offset:33792
	ds_read_b128 v[186:189], v145 offset:34816
	ds_read_b128 v[190:193], v145 offset:35840
	ds_read_b128 v[194:197], v145 offset:36864
	ds_read_b128 v[198:201], v145 offset:37888
	ds_read_b128 v[202:205], v145 offset:38912
	ds_read_b128 v[206:209], v145 offset:39936
	global_load_lds_dwordx4 v128, s[24:25]
	s_mov_b32 m0, s60
	s_nop 0
	global_load_lds_dwordx4 v130, s[24:25]
	s_waitcnt vmcnt(8) lgkmcnt(0)
	s_barrier
	s_setprio 1
	v_mfma_f32_16x16x32_bf16 v[124:127], v[138:141], v[178:181], v[124:127]
	v_mfma_f32_16x16x32_bf16 v[120:123], v[150:153], v[178:181], v[120:123]
	v_mfma_f32_16x16x32_bf16 v[108:111], v[138:141], v[186:189], v[108:111]
	v_mfma_f32_16x16x32_bf16 v[104:107], v[150:153], v[186:189], v[104:107]
	v_mfma_f32_16x16x32_bf16 v[92:95], v[138:141], v[194:197], v[92:95]
	v_mfma_f32_16x16x32_bf16 v[88:91], v[150:153], v[194:197], v[88:91]
	v_mfma_f32_16x16x32_bf16 v[76:79], v[138:141], v[202:205], v[76:79]
	v_mfma_f32_16x16x32_bf16 v[72:75], v[150:153], v[202:205], v[72:75]
	v_mfma_f32_16x16x32_bf16 v[124:127], v[146:149], v[182:185], v[124:127]
	v_mfma_f32_16x16x32_bf16 v[120:123], v[154:157], v[182:185], v[120:123]
	v_mfma_f32_16x16x32_bf16 v[108:111], v[146:149], v[190:193], v[108:111]
	v_mfma_f32_16x16x32_bf16 v[104:107], v[154:157], v[190:193], v[104:107]
	v_mfma_f32_16x16x32_bf16 v[92:95], v[146:149], v[198:201], v[92:95]
	v_mfma_f32_16x16x32_bf16 v[88:91], v[154:157], v[198:201], v[88:91]
	v_mfma_f32_16x16x32_bf16 v[76:79], v[146:149], v[206:209], v[76:79]
	v_mfma_f32_16x16x32_bf16 v[72:75], v[154:157], v[206:209], v[72:75]
	v_mfma_f32_16x16x32_bf16 v[116:119], v[162:165], v[178:181], v[116:119]
	v_mfma_f32_16x16x32_bf16 v[112:115], v[170:173], v[178:181], v[112:115]
	v_mfma_f32_16x16x32_bf16 v[100:103], v[162:165], v[186:189], v[100:103]
	v_mfma_f32_16x16x32_bf16 v[96:99], v[170:173], v[186:189], v[96:99]
	v_mfma_f32_16x16x32_bf16 v[84:87], v[162:165], v[194:197], v[84:87]
	v_mfma_f32_16x16x32_bf16 v[80:83], v[170:173], v[194:197], v[80:83]
	v_mfma_f32_16x16x32_bf16 v[68:71], v[162:165], v[202:205], v[68:71]
	v_mfma_f32_16x16x32_bf16 v[64:67], v[170:173], v[202:205], v[64:67]
	v_mfma_f32_16x16x32_bf16 v[116:119], v[166:169], v[182:185], v[116:119]
	v_mfma_f32_16x16x32_bf16 v[112:115], v[174:177], v[182:185], v[112:115]
	v_mfma_f32_16x16x32_bf16 v[100:103], v[166:169], v[190:193], v[100:103]
	v_mfma_f32_16x16x32_bf16 v[96:99], v[174:177], v[190:193], v[96:99]
	v_mfma_f32_16x16x32_bf16 v[84:87], v[166:169], v[198:201], v[84:87]
	v_mfma_f32_16x16x32_bf16 v[80:83], v[174:177], v[198:201], v[80:83]
	v_mfma_f32_16x16x32_bf16 v[68:71], v[166:169], v[206:209], v[68:71]
	v_mfma_f32_16x16x32_bf16 v[64:67], v[174:177], v[206:209], v[64:67]
	s_setprio 0
	s_barrier
; #define PG8_STAGE(bufoff, gbase, voff) do { _Pragma("unroll") for (int _i = 0; _i < 2; ++_i) \
;         __builtin_amdgcn_global_load_lds((const unsigned*)((const char*)(gbase) + (voff)[_i]), (LAS unsigned*)(lds + (bufoff) + ldsw + _i * 8192), 16, 0, 0); } while (0)
; #define PG8_LDA(dst, b, h) do { _Pragma("unroll") for (int m = 0; m < 4; ++m) _Pragma("unroll") for (int k = 0; k < 2; ++k) dst[m][k] = *(const LAS bf16x8*)(lds + PG8_SA(b, h) + aoff + m * 2048 + k * 1024); } while (0)
; #define PG8_MMA(ai, bj, At, Bt) do { __builtin_amdgcn_s_setprio(1); _Pragma("unroll") for (int m = 0; m < 4; ++m) _Pragma("unroll") for (int n = 0; n < 2; ++n) _Pragma("unroll") for (int k = 0; k < 2; ++k) \
;         acc[ai][bj][m][n] = __builtin_amdgcn_mfma_f32_16x16x32_bf16(Bt[n][k], At[m][k], acc[ai][bj][m][n], 0, 0, 0); __builtin_amdgcn_s_setprio(0); } while (0)
; #define PG8_WAIT_V(n) asm volatile("s_waitcnt vmcnt(" #n ")" ::: "memory")
; #define PG8_WAIT_L(n) asm volatile("s_waitcnt lgkmcnt(" #n ")" ::: "memory")
; #define PG8_BAR __builtin_amdgcn_s_barrier()
; #define PG8_SCHED __builtin_amdgcn_sched_barrier(0)
; template <class Epi, bool ALIGN_EPI = true>
; __device__ __forceinline__ void gemm_phase(LAS unsigned char* lds, const Gemm g, const StaticOrder& S, const Epi& E, int wave_k) {
;     ...
;             PG8_LDA(At, 1, 1); PG8_STAGE(PG8_SB(1, 0), b3, voffB); PG8_STAGE(PG8_SB(1, 1), b3 + hstepB, voffB); PG8_STAGE(PG8_SA(1, 0), a3, voffA);
;             PG8_WAIT_V(8); PG8_WAIT_L(0); PG8_BAR; PG8_MMA(1, 0, At, B0); PG8_MMA(1, 1, At, B1); PG8_BAR; PG8_SCHED;
;         }
;         if constexpr (ALIGN_EPI) { if (wr == 0) PG8_BAR; }
	s_add_i32 s24, s71, s58
	v_lshl_add_u64 v[158:159], v[158:159], 0, s[22:23]
	s_mov_b32 m0, s24
	ds_read_b128 v[178:181], v145 offset:49152
	ds_read_b128 v[182:185], v145 offset:50176
	ds_read_b128 v[186:189], v145 offset:51200
	ds_read_b128 v[190:193], v145 offset:52224
	ds_read_b128 v[194:197], v145 offset:53248
	ds_read_b128 v[198:201], v145 offset:54272
	ds_read_b128 v[202:205], v145 offset:55296
	ds_read_b128 v[206:209], v145 offset:56320
	global_load_lds_dwordx4 v[158:159], off
	s_add_i32 m0, s24, 0x2000
	s_add_u32 s16, s16, 0x40080
	v_lshl_add_u64 v[158:159], v[210:211], 0, s[22:23]
	s_addc_u32 s17, s17, 0
	s_add_i32 s24, s72, s58
	global_load_lds_dwordx4 v[158:159], off
	s_mov_b32 m0, s24
	s_nop 0
	global_load_lds_dwordx4 v160, s[16:17]
	s_add_i32 m0, s24, 0x2000
	s_nop 0
	global_load_lds_dwordx4 v132, s[16:17]
	v_lshl_add_u64 v[158:159], v[212:213], 0, s[22:23]
	s_mov_b32 m0, s61
	s_nop 0
	global_load_lds_dwordx4 v[158:159], off
	v_lshl_add_u64 v[158:159], v[218:219], 0, s[22:23]
	s_mov_b32 m0, s62
	s_nop 0
	global_load_lds_dwordx4 v[158:159], off
	s_waitcnt vmcnt(8) lgkmcnt(0)
	s_barrier
	s_setprio 1
	v_mfma_f32_16x16x32_bf16 v[60:63], v[138:141], v[178:181], v[60:63]
	v_mfma_f32_16x16x32_bf16 v[56:59], v[150:153], v[178:181], v[56:59]
	v_mfma_f32_16x16x32_bf16 v[44:47], v[138:141], v[186:189], v[44:47]
	v_mfma_f32_16x16x32_bf16 v[40:43], v[150:153], v[186:189], v[40:43]
	v_mfma_f32_16x16x32_bf16 v[28:31], v[138:141], v[194:197], v[28:31]
	v_mfma_f32_16x16x32_bf16 v[24:27], v[150:153], v[194:197], v[24:27]
	v_mfma_f32_16x16x32_bf16 v[12:15], v[138:141], v[202:205], v[12:15]
	v_mfma_f32_16x16x32_bf16 v[8:11], v[150:153], v[202:205], v[8:11]
	v_mfma_f32_16x16x32_bf16 v[60:63], v[146:149], v[182:185], v[60:63]
	v_mfma_f32_16x16x32_bf16 v[56:59], v[154:157], v[182:185], v[56:59]
	v_mfma_f32_16x16x32_bf16 v[44:47], v[146:149], v[190:193], v[44:47]
	v_mfma_f32_16x16x32_bf16 v[40:43], v[154:157], v[190:193], v[40:43]
	v_mfma_f32_16x16x32_bf16 v[28:31], v[146:149], v[198:201], v[28:31]
	v_mfma_f32_16x16x32_bf16 v[24:27], v[154:157], v[198:201], v[24:27]
	v_mfma_f32_16x16x32_bf16 v[12:15], v[146:149], v[206:209], v[12:15]
	v_mfma_f32_16x16x32_bf16 v[8:11], v[154:157], v[206:209], v[8:11]
	v_mfma_f32_16x16x32_bf16 v[52:55], v[162:165], v[178:181], v[52:55]
	v_mfma_f32_16x16x32_bf16 v[48:51], v[170:173], v[178:181], v[48:51]
	v_mfma_f32_16x16x32_bf16 v[36:39], v[162:165], v[186:189], v[36:39]
	v_mfma_f32_16x16x32_bf16 v[32:35], v[170:173], v[186:189], v[32:35]
	v_mfma_f32_16x16x32_bf16 v[20:23], v[162:165], v[194:197], v[20:23]
	v_mfma_f32_16x16x32_bf16 v[16:19], v[170:173], v[194:197], v[16:19]
	v_mfma_f32_16x16x32_bf16 v[4:7], v[162:165], v[202:205], v[4:7]
	v_mfma_f32_16x16x32_bf16 v[0:3], v[170:173], v[202:205], v[0:3]
	v_mfma_f32_16x16x32_bf16 v[52:55], v[166:169], v[182:185], v[52:55]
	v_mfma_f32_16x16x32_bf16 v[48:51], v[174:177], v[182:185], v[48:51]
	v_mfma_f32_16x16x32_bf16 v[36:39], v[166:169], v[190:193], v[36:39]
	v_mfma_f32_16x16x32_bf16 v[32:35], v[174:177], v[190:193], v[32:35]
	v_mfma_f32_16x16x32_bf16 v[20:23], v[166:169], v[198:201], v[20:23]
	v_mfma_f32_16x16x32_bf16 v[16:19], v[174:177], v[198:201], v[16:19]
	v_mfma_f32_16x16x32_bf16 v[4:7], v[166:169], v[206:209], v[4:7]
	v_mfma_f32_16x16x32_bf16 v[0:3], v[174:177], v[206:209], v[0:3]
	s_setprio 0
	s_barrier
	s_add_i32 s70, s70, 2
	s_add_u32 s50, s50, 0x100
	s_addc_u32 s51, s51, 0
	s_add_u32 s66, s66, 0x100
	s_addc_u32 s67, s67, 0
	s_cmp_gt_u32 s70, 13
	s_cbranch_scc0 .LBB0_1057
	s_and_b64 vcc, exec, s[20:21]
	s_cbranch_vccz .LBB0_1060
	s_barrier

; #define PG8_STAGE(bufoff, gbase, voff) do { _Pragma("unroll") for (int _i = 0; _i < 2; ++_i) \
;         __builtin_amdgcn_global_load_lds((const unsigned*)((const char*)(gbase) + (voff)[_i]), (LAS unsigned*)(lds + (bufoff) + ldsw + _i * 8192), 16, 0, 0); } while (0)
; #define PG8_LDA(dst, b, h) do { _Pragma("unroll") for (int m = 0; m < 4; ++m) _Pragma("unroll") for (int k = 0; k < 2; ++k) dst[m][k] = *(const LAS bf16x8*)(lds + PG8_SA(b, h) + aoff + m * 2048 + k * 1024); } while (0)
; #define PG8_LDB(dst, b, h) do { _Pragma("unroll") for (int n = 0; n < 2; ++n) _Pragma("unroll") for (int k = 0; k < 2; ++k) dst[n][k] = *(const LAS bf16x8*)(lds + PG8_SB(b, h) + boff + n * 2048 + k * 1024); } while (0)
; #define PG8_MMA(ai, bj, At, Bt) do { __builtin_amdgcn_s_setprio(1); _Pragma("unroll") for (int m = 0; m < 4; ++m) _Pragma("unroll") for (int n = 0; n < 2; ++n) _Pragma("unroll") for (int k = 0; k < 2; ++k) \
;         acc[ai][bj][m][n] = __builtin_amdgcn_mfma_f32_16x16x32_bf16(Bt[n][k], At[m][k], acc[ai][bj][m][n], 0, 0, 0); __builtin_amdgcn_s_setprio(0); } while (0)
; #define PG8_BAR __builtin_amdgcn_s_barrier()
; template <class Epi, bool ALIGN_EPI = true>
; __device__ __forceinline__ void gemm_phase(LAS unsigned char* lds, const Gemm g, const StaticOrder& S, const Epi& E, int wave_k) {
;     ...
;         const bool has_next = S.next(ui + 1, nxt);
;         const char* nA = has_next ? (const char*)g.A + (size_t)nxt.pm * tstepA : cA; const char* nB = has_next ? (const char*)g.Bt + (size_t)nxt.pn * tstepB : cB;
;         for (int t = 0; t < nt; t += 2) {
;             const bool last = (t == nt - 2);
;             const char* a1 = cA + (size_t)(t + 1) * kstep;
;             const char* a2 = last ? nA : cA + (size_t)(t + 2) * kstep; const char* b2 = last ? nB : cB + (size_t)(t + 2) * kstep;
;             const char* a3 = a2 + kstep; const char* b3 = b2 + kstep;
;             PG8_LDB(B0, 0, 0); PG8_LDB(B1, 0, 1); PG8_SCHED; PG8_LDA(At, 0, 0); PG8_STAGE(PG8_SA(1, 1), a1 + hstepA, voffA);
;             PG8_WAIT_V(8); PG8_WAIT_L(0); PG8_BAR; PG8_MMA(0, 0, At, B0); PG8_MMA(0, 1, At, B1); PG8_BAR; PG8_SCHED;
;             PG8_LDA(At, 0, 1); PG8_STAGE(PG8_SB(0, 0), b2, voffB); PG8_STAGE(PG8_SB(0, 1), b2 + hstepB, voffB); PG8_STAGE(PG8_SA(0, 0), a2, voffA);
;             PG8_WAIT_V(8); PG8_WAIT_L(0); PG8_BAR; PG8_MMA(1, 0, At, B0); PG8_MMA(1, 1, At, B1); PG8_BAR; PG8_SCHED;
.LBB0_1141:
	s_add_u32 s16, s2, 0xfffc0080
	s_addc_u32 s17, s3, -1
	s_add_i32 s65, 0, 0x10000
	s_cmp_eq_u32 s64, 12
	s_cselect_b32 s19, s44, s17
	s_cselect_b32 s18, s45, s16
	s_cselect_b32 s17, s47, s63
	s_cselect_b32 s16, s49, s62
	s_add_i32 s68, 0, 0x14000
	v_add_u32_e32 v150, s65, v157
	v_add_u32_e32 v154, s68, v157
	ds_read_b128 v[138:141], v150
	ds_read_b128 v[142:145], v150 offset:1024
	ds_read_b128 v[146:149], v150 offset:2048
	ds_read_b128 v[150:153], v150 offset:3072
	ds_read_b128 v[162:165], v154
	ds_read_b128 v[166:169], v154 offset:1024
	ds_read_b128 v[170:173], v154 offset:2048
	ds_read_b128 v[174:177], v154 offset:3072
	s_add_i32 m0, s55, 0xc000
	ds_read_b128 v[178:181], v159
	ds_read_b128 v[182:185], v159 offset:1024
	ds_read_b128 v[186:189], v159 offset:2048
	ds_read_b128 v[190:193], v159 offset:3072
	ds_read_b128 v[194:197], v159 offset:4096
	ds_read_b128 v[198:201], v159 offset:5120
	ds_read_b128 v[202:205], v159 offset:6144
	ds_read_b128 v[206:209], v159 offset:7168
	global_load_lds_dwordx4 v134, s[2:3]
	s_add_i32 m0, s55, 0xe000
	s_nop 0
	global_load_lds_dwordx4 v136, s[2:3]
	s_waitcnt vmcnt(8) lgkmcnt(0)
	s_barrier
	s_setprio 1
	v_mfma_f32_16x16x32_bf16 v[124:127], v[138:141], v[178:181], v[124:127]
	v_mfma_f32_16x16x32_bf16 v[120:123], v[146:149], v[178:181], v[120:123]
	v_mfma_f32_16x16x32_bf16 v[108:111], v[138:141], v[186:189], v[108:111]
	v_mfma_f32_16x16x32_bf16 v[100:103], v[146:149], v[186:189], v[100:103]
	v_mfma_f32_16x16x32_bf16 v[92:95], v[138:141], v[194:197], v[92:95]
	v_mfma_f32_16x16x32_bf16 v[84:87], v[146:149], v[194:197], v[84:87]
	v_mfma_f32_16x16x32_bf16 v[76:79], v[138:141], v[202:205], v[76:79]
	v_mfma_f32_16x16x32_bf16 v[68:71], v[146:149], v[202:205], v[68:71]
	v_mfma_f32_16x16x32_bf16 v[124:127], v[142:145], v[182:185], v[124:127]
	v_mfma_f32_16x16x32_bf16 v[120:123], v[150:153], v[182:185], v[120:123]
	v_mfma_f32_16x16x32_bf16 v[108:111], v[142:145], v[190:193], v[108:111]
	v_mfma_f32_16x16x32_bf16 v[100:103], v[150:153], v[190:193], v[100:103]
	v_mfma_f32_16x16x32_bf16 v[92:95], v[142:145], v[198:201], v[92:95]
	v_mfma_f32_16x16x32_bf16 v[84:87], v[150:153], v[198:201], v[84:87]
	v_mfma_f32_16x16x32_bf16 v[76:79], v[142:145], v[206:209], v[76:79]
	v_mfma_f32_16x16x32_bf16 v[68:71], v[150:153], v[206:209], v[68:71]
	v_mfma_f32_16x16x32_bf16 v[116:119], v[162:165], v[178:181], v[116:119]
	v_mfma_f32_16x16x32_bf16 v[112:115], v[170:173], v[178:181], v[112:115]
	v_mfma_f32_16x16x32_bf16 v[104:107], v[162:165], v[186:189], v[104:107]
	v_mfma_f32_16x16x32_bf16 v[96:99], v[170:173], v[186:189], v[96:99]
	v_mfma_f32_16x16x32_bf16 v[88:91], v[162:165], v[194:197], v[88:91]
	v_mfma_f32_16x16x32_bf16 v[80:83], v[170:173], v[194:197], v[80:83]
	v_mfma_f32_16x16x32_bf16 v[72:75], v[162:165], v[202:205], v[72:75]
	v_mfma_f32_16x16x32_bf16 v[64:67], v[170:173], v[202:205], v[64:67]
	v_mfma_f32_16x16x32_bf16 v[116:119], v[166:169], v[182:185], v[116:119]
	v_mfma_f32_16x16x32_bf16 v[112:115], v[174:177], v[182:185], v[112:115]
	v_mfma_f32_16x16x32_bf16 v[104:107], v[166:169], v[190:193], v[104:107]
	v_mfma_f32_16x16x32_bf16 v[96:99], v[174:177], v[190:193], v[96:99]
	v_mfma_f32_16x16x32_bf16 v[88:91], v[166:169], v[198:201], v[88:91]
	v_mfma_f32_16x16x32_bf16 v[80:83], v[174:177], v[198:201], v[80:83]
	v_mfma_f32_16x16x32_bf16 v[72:75], v[166:169], v[206:209], v[72:75]
	v_mfma_f32_16x16x32_bf16 v[64:67], v[174:177], v[206:209], v[64:67]
	s_setprio 0
	s_barrier
	s_add_i32 s65, s65, s29
	v_lshl_add_u64 v[154:155], s[16:17], 0, v[160:161]
	s_mov_b32 m0, s65
	ds_read_b128 v[178:181], v159 offset:16384
	ds_read_b128 v[182:185], v159 offset:17408
	ds_read_b128 v[186:189], v159 offset:18432
	ds_read_b128 v[190:193], v159 offset:19456
	ds_read_b128 v[194:197], v159 offset:20480
	ds_read_b128 v[198:201], v159 offset:21504
	ds_read_b128 v[202:205], v159 offset:22528
	ds_read_b128 v[206:209], v159 offset:23552
	global_load_lds_dwordx4 v[154:155], off
	s_add_i32 m0, s65, 0x2000
	s_add_u32 s66, s16, 0x40000
	v_lshl_add_u64 v[210:211], s[16:17], 0, v[128:129]
	s_addc_u32 s67, s17, 0
	s_add_i32 s65, s68, s29
	global_load_lds_dwordx4 v[210:211], off
	s_mov_b32 m0, s65
	v_lshl_add_u64 v[218:219], s[18:19], 0, v[130:131]
	global_load_lds_dwordx4 v160, s[66:67]
	s_add_i32 m0, s65, 0x2000
	s_nop 0
	global_load_lds_dwordx4 v128, s[66:67]
	v_lshl_add_u64 v[212:213], s[18:19], 0, v[132:133]
	s_mov_b32 m0, s55
	s_nop 0
	global_load_lds_dwordx4 v[212:213], off
	s_mov_b32 m0, s56
	s_nop 0
	global_load_lds_dwordx4 v[218:219], off
	s_waitcnt vmcnt(8) lgkmcnt(0)
	s_barrier
; #define PG8_STAGE(bufoff, gbase, voff) do { _Pragma("unroll") for (int _i = 0; _i < 2; ++_i) \
;         __builtin_amdgcn_global_load_lds((const unsigned*)((const char*)(gbase) + (voff)[_i]), (LAS unsigned*)(lds + (bufoff) + ldsw + _i * 8192), 16, 0, 0); } while (0)
; #define PG8_LDA(dst, b, h) do { _Pragma("unroll") for (int m = 0; m < 4; ++m) _Pragma("unroll") for (int k = 0; k < 2; ++k) dst[m][k] = *(const LAS bf16x8*)(lds + PG8_SA(b, h) + aoff + m * 2048 + k * 1024); } while (0)
; #define PG8_LDB(dst, b, h) do { _Pragma("unroll") for (int n = 0; n < 2; ++n) _Pragma("unroll") for (int k = 0; k < 2; ++k) dst[n][k] = *(const LAS bf16x8*)(lds + PG8_SB(b, h) + boff + n * 2048 + k * 1024); } while (0)
; #define PG8_MMA(ai, bj, At, Bt) do { __builtin_amdgcn_s_setprio(1); _Pragma("unroll") for (int m = 0; m < 4; ++m) _Pragma("unroll") for (int n = 0; n < 2; ++n) _Pragma("unroll") for (int k = 0; k < 2; ++k) \
;         acc[ai][bj][m][n] = __builtin_amdgcn_mfma_f32_16x16x32_bf16(Bt[n][k], At[m][k], acc[ai][bj][m][n], 0, 0, 0); __builtin_amdgcn_s_setprio(0); } while (0)
; #define PG8_WAIT_V(n) asm volatile("s_waitcnt vmcnt(" #n ")" ::: "memory")
; #define PG8_WAIT_L(n) asm volatile("s_waitcnt lgkmcnt(" #n ")" ::: "memory")
; #define PG8_BAR __builtin_amdgcn_s_barrier()
; #define PG8_SCHED __builtin_amdgcn_sched_barrier(0)
; template <class Epi, bool ALIGN_EPI = true>
; __device__ __forceinline__ void gemm_phase(LAS unsigned char* lds, const Gemm g, const StaticOrder& S, const Epi& E, int wave_k) {
;     ...
;             PG8_WAIT_V(8); PG8_WAIT_L(0); PG8_BAR; PG8_MMA(1, 0, At, B0); PG8_MMA(1, 1, At, B1); PG8_BAR; PG8_SCHED;
;             PG8_LDB(B0, 1, 0); PG8_LDB(B1, 1, 1); PG8_SCHED; PG8_LDA(At, 1, 0); PG8_STAGE(PG8_SA(0, 1), a2 + hstepA, voffA);
;             PG8_WAIT_V(8); PG8_WAIT_L(0); PG8_BAR; PG8_MMA(0, 0, At, B0); PG8_MMA(0, 1, At, B1); PG8_BAR; PG8_SCHED;
	s_setprio 1
	v_mfma_f32_16x16x32_bf16 v[60:63], v[138:141], v[178:181], v[60:63]
	v_mfma_f32_16x16x32_bf16 v[52:55], v[146:149], v[178:181], v[52:55]
	v_mfma_f32_16x16x32_bf16 v[44:47], v[138:141], v[186:189], v[44:47]
	v_mfma_f32_16x16x32_bf16 v[36:39], v[146:149], v[186:189], v[36:39]
	v_mfma_f32_16x16x32_bf16 v[28:31], v[138:141], v[194:197], v[28:31]
	v_mfma_f32_16x16x32_bf16 v[20:23], v[146:149], v[194:197], v[20:23]
	v_mfma_f32_16x16x32_bf16 v[12:15], v[138:141], v[202:205], v[12:15]
	v_mfma_f32_16x16x32_bf16 v[4:7], v[146:149], v[202:205], v[4:7]
	v_mfma_f32_16x16x32_bf16 v[60:63], v[142:145], v[182:185], v[60:63]
	v_mfma_f32_16x16x32_bf16 v[52:55], v[150:153], v[182:185], v[52:55]
	v_mfma_f32_16x16x32_bf16 v[44:47], v[142:145], v[190:193], v[44:47]
	v_mfma_f32_16x16x32_bf16 v[36:39], v[150:153], v[190:193], v[36:39]
	v_mfma_f32_16x16x32_bf16 v[28:31], v[142:145], v[198:201], v[28:31]
	v_mfma_f32_16x16x32_bf16 v[20:23], v[150:153], v[198:201], v[20:23]
	v_mfma_f32_16x16x32_bf16 v[12:15], v[142:145], v[206:209], v[12:15]
	v_mfma_f32_16x16x32_bf16 v[4:7], v[150:153], v[206:209], v[4:7]
	v_mfma_f32_16x16x32_bf16 v[56:59], v[162:165], v[178:181], v[56:59]
	v_mfma_f32_16x16x32_bf16 v[48:51], v[170:173], v[178:181], v[48:51]
	v_mfma_f32_16x16x32_bf16 v[40:43], v[162:165], v[186:189], v[40:43]
	v_mfma_f32_16x16x32_bf16 v[32:35], v[170:173], v[186:189], v[32:35]
	v_mfma_f32_16x16x32_bf16 v[24:27], v[162:165], v[194:197], v[24:27]
	v_mfma_f32_16x16x32_bf16 v[16:19], v[170:173], v[194:197], v[16:19]
	v_mfma_f32_16x16x32_bf16 v[8:11], v[162:165], v[202:205], v[8:11]
	v_mfma_f32_16x16x32_bf16 v[0:3], v[170:173], v[202:205], v[0:3]
	v_mfma_f32_16x16x32_bf16 v[56:59], v[166:169], v[182:185], v[56:59]
	v_mfma_f32_16x16x32_bf16 v[48:51], v[174:177], v[182:185], v[48:51]
	v_mfma_f32_16x16x32_bf16 v[40:43], v[166:169], v[190:193], v[40:43]
	v_mfma_f32_16x16x32_bf16 v[32:35], v[174:177], v[190:193], v[32:35]
	v_mfma_f32_16x16x32_bf16 v[24:27], v[166:169], v[198:201], v[24:27]
	v_mfma_f32_16x16x32_bf16 v[16:19], v[174:177], v[198:201], v[16:19]
	v_mfma_f32_16x16x32_bf16 v[8:11], v[166:169], v[206:209], v[8:11]
	v_mfma_f32_16x16x32_bf16 v[0:3], v[174:177], v[206:209], v[0:3]
	s_setprio 0
	s_barrier
	s_add_i32 s65, 0, 0x18000
	s_add_i32 s66, 0, 0x1c000
	v_add_u32_e32 v150, s65, v157
	v_add_u32_e32 v174, s66, v157
	ds_read_b128 v[138:141], v150
	ds_read_b128 v[142:145], v150 offset:1024
	ds_read_b128 v[146:149], v150 offset:2048
	ds_read_b128 v[150:153], v150 offset:3072
	ds_read_b128 v[162:165], v174
	ds_read_b128 v[166:169], v174 offset:1024
	ds_read_b128 v[170:173], v174 offset:2048
	ds_read_b128 v[174:177], v174 offset:3072
	s_add_u32 s18, s18, 0x40000
	s_addc_u32 s19, s19, 0
	s_mov_b32 m0, s57
	ds_read_b128 v[178:181], v159 offset:32768
	ds_read_b128 v[182:185], v159 offset:33792
	ds_read_b128 v[186:189], v159 offset:34816
	ds_read_b128 v[190:193], v159 offset:35840
	ds_read_b128 v[194:197], v159 offset:36864
	ds_read_b128 v[198:201], v159 offset:37888
	ds_read_b128 v[202:205], v159 offset:38912
	ds_read_b128 v[206:209], v159 offset:39936
	global_load_lds_dwordx4 v132, s[18:19]
	s_mov_b32 m0, s58
	s_nop 0
	global_load_lds_dwordx4 v130, s[18:19]
	s_waitcnt vmcnt(8) lgkmcnt(0)
	s_barrier
	s_setprio 1
	v_mfma_f32_16x16x32_bf16 v[124:127], v[138:141], v[178:181], v[124:127]
	v_mfma_f32_16x16x32_bf16 v[120:123], v[146:149], v[178:181], v[120:123]
	v_mfma_f32_16x16x32_bf16 v[108:111], v[138:141], v[186:189], v[108:111]
	v_mfma_f32_16x16x32_bf16 v[100:103], v[146:149], v[186:189], v[100:103]
	v_mfma_f32_16x16x32_bf16 v[92:95], v[138:141], v[194:197], v[92:95]
	v_mfma_f32_16x16x32_bf16 v[84:87], v[146:149], v[194:197], v[84:87]
	v_mfma_f32_16x16x32_bf16 v[76:79], v[138:141], v[202:205], v[76:79]
	v_mfma_f32_16x16x32_bf16 v[68:71], v[146:149], v[202:205], v[68:71]
	v_mfma_f32_16x16x32_bf16 v[124:127], v[142:145], v[182:185], v[124:127]
	v_mfma_f32_16x16x32_bf16 v[120:123], v[150:153], v[182:185], v[120:123]
	v_mfma_f32_16x16x32_bf16 v[108:111], v[142:145], v[190:193], v[108:111]
	v_mfma_f32_16x16x32_bf16 v[100:103], v[150:153], v[190:193], v[100:103]
	v_mfma_f32_16x16x32_bf16 v[92:95], v[142:145], v[198:201], v[92:95]
	v_mfma_f32_16x16x32_bf16 v[84:87], v[150:153], v[198:201], v[84:87]
	v_mfma_f32_16x16x32_bf16 v[76:79], v[142:145], v[206:209], v[76:79]
	v_mfma_f32_16x16x32_bf16 v[68:71], v[150:153], v[206:209], v[68:71]
	v_mfma_f32_16x16x32_bf16 v[116:119], v[162:165], v[178:181], v[116:119]
	v_mfma_f32_16x16x32_bf16 v[112:115], v[170:173], v[178:181], v[112:115]
	v_mfma_f32_16x16x32_bf16 v[104:107], v[162:165], v[186:189], v[104:107]
	v_mfma_f32_16x16x32_bf16 v[96:99], v[170:173], v[186:189], v[96:99]
	v_mfma_f32_16x16x32_bf16 v[88:91], v[162:165], v[194:197], v[88:91]
	v_mfma_f32_16x16x32_bf16 v[80:83], v[170:173], v[194:197], v[80:83]
	v_mfma_f32_16x16x32_bf16 v[72:75], v[162:165], v[202:205], v[72:75]
	v_mfma_f32_16x16x32_bf16 v[64:67], v[170:173], v[202:205], v[64:67]
	v_mfma_f32_16x16x32_bf16 v[116:119], v[166:169], v[182:185], v[116:119]
	v_mfma_f32_16x16x32_bf16 v[112:115], v[174:177], v[182:185], v[112:115]
	v_mfma_f32_16x16x32_bf16 v[104:107], v[166:169], v[190:193], v[104:107]
	v_mfma_f32_16x16x32_bf16 v[96:99], v[174:177], v[190:193], v[96:99]
	v_mfma_f32_16x16x32_bf16 v[88:91], v[166:169], v[198:201], v[88:91]
	v_mfma_f32_16x16x32_bf16 v[80:83], v[174:177], v[198:201], v[80:83]
	v_mfma_f32_16x16x32_bf16 v[72:75], v[166:169], v[206:209], v[72:75]
	v_mfma_f32_16x16x32_bf16 v[64:67], v[174:177], v[206:209], v[64:67]
	s_setprio 0
	s_barrier
; #define PG8_STAGE(bufoff, gbase, voff) do { _Pragma("unroll") for (int _i = 0; _i < 2; ++_i) \
;         __builtin_amdgcn_global_load_lds((const unsigned*)((const char*)(gbase) + (voff)[_i]), (LAS unsigned*)(lds + (bufoff) + ldsw + _i * 8192), 16, 0, 0); } while (0)
; #define PG8_LDA(dst, b, h) do { _Pragma("unroll") for (int m = 0; m < 4; ++m) _Pragma("unroll") for (int k = 0; k < 2; ++k) dst[m][k] = *(const LAS bf16x8*)(lds + PG8_SA(b, h) + aoff + m * 2048 + k * 1024); } while (0)
; #define PG8_MMA(ai, bj, At, Bt) do { __builtin_amdgcn_s_setprio(1); _Pragma("unroll") for (int m = 0; m < 4; ++m) _Pragma("unroll") for (int n = 0; n < 2; ++n) _Pragma("unroll") for (int k = 0; k < 2; ++k) \
;         acc[ai][bj][m][n] = __builtin_amdgcn_mfma_f32_16x16x32_bf16(Bt[n][k], At[m][k], acc[ai][bj][m][n], 0, 0, 0); __builtin_amdgcn_s_setprio(0); } while (0)
; #define PG8_WAIT_V(n) asm volatile("s_waitcnt vmcnt(" #n ")" ::: "memory")
; #define PG8_WAIT_L(n) asm volatile("s_waitcnt lgkmcnt(" #n ")" ::: "memory")
; #define PG8_BAR __builtin_amdgcn_s_barrier()
; #define PG8_SCHED __builtin_amdgcn_sched_barrier(0)
; template <class Epi, bool ALIGN_EPI = true>
; __device__ __forceinline__ void gemm_phase(LAS unsigned char* lds, const Gemm g, const StaticOrder& S, const Epi& E, int wave_k) {
;     ...
;             PG8_LDA(At, 1, 1); PG8_STAGE(PG8_SB(1, 0), b3, voffB); PG8_STAGE(PG8_SB(1, 1), b3 + hstepB, voffB); PG8_STAGE(PG8_SA(1, 0), a3, voffA);
;             PG8_WAIT_V(8); PG8_WAIT_L(0); PG8_BAR; PG8_MMA(1, 0, At, B0); PG8_MMA(1, 1, At, B1); PG8_BAR; PG8_SCHED;
;         }
;         if constexpr (ALIGN_EPI) { if (wr == 0) PG8_BAR; }
	s_add_i32 s18, s65, s29
	v_lshl_add_u64 v[154:155], v[154:155], 0, s[22:23]
	s_mov_b32 m0, s18
	ds_read_b128 v[178:181], v159 offset:49152
	ds_read_b128 v[182:185], v159 offset:50176
	ds_read_b128 v[186:189], v159 offset:51200
	ds_read_b128 v[190:193], v159 offset:52224
	ds_read_b128 v[194:197], v159 offset:53248
	ds_read_b128 v[198:201], v159 offset:54272
	ds_read_b128 v[202:205], v159 offset:55296
	ds_read_b128 v[206:209], v159 offset:56320
	global_load_lds_dwordx4 v[154:155], off
	s_add_i32 m0, s18, 0x2000
	s_add_u32 s16, s16, 0x40080
	v_lshl_add_u64 v[154:155], v[210:211], 0, s[22:23]
	s_addc_u32 s17, s17, 0
	s_add_i32 s18, s66, s29
	global_load_lds_dwordx4 v[154:155], off
	s_mov_b32 m0, s18
	s_nop 0
	global_load_lds_dwordx4 v160, s[16:17]
	s_add_i32 m0, s18, 0x2000
	s_nop 0
	global_load_lds_dwordx4 v128, s[16:17]
	v_lshl_add_u64 v[154:155], v[212:213], 0, s[22:23]
	s_mov_b32 m0, s20
	s_nop 0
	global_load_lds_dwordx4 v[154:155], off
	v_lshl_add_u64 v[154:155], v[218:219], 0, s[22:23]
	s_mov_b32 m0, s59
	s_nop 0
	global_load_lds_dwordx4 v[154:155], off
	s_waitcnt vmcnt(8) lgkmcnt(0)
	s_barrier
	s_setprio 1
	v_mfma_f32_16x16x32_bf16 v[60:63], v[138:141], v[178:181], v[60:63]
	v_mfma_f32_16x16x32_bf16 v[52:55], v[146:149], v[178:181], v[52:55]
	v_mfma_f32_16x16x32_bf16 v[44:47], v[138:141], v[186:189], v[44:47]
	v_mfma_f32_16x16x32_bf16 v[36:39], v[146:149], v[186:189], v[36:39]
	v_mfma_f32_16x16x32_bf16 v[28:31], v[138:141], v[194:197], v[28:31]
	v_mfma_f32_16x16x32_bf16 v[20:23], v[146:149], v[194:197], v[20:23]
	v_mfma_f32_16x16x32_bf16 v[12:15], v[138:141], v[202:205], v[12:15]
	v_mfma_f32_16x16x32_bf16 v[4:7], v[146:149], v[202:205], v[4:7]
	v_mfma_f32_16x16x32_bf16 v[60:63], v[142:145], v[182:185], v[60:63]
	v_mfma_f32_16x16x32_bf16 v[52:55], v[150:153], v[182:185], v[52:55]
	v_mfma_f32_16x16x32_bf16 v[44:47], v[142:145], v[190:193], v[44:47]
	v_mfma_f32_16x16x32_bf16 v[36:39], v[150:153], v[190:193], v[36:39]
	v_mfma_f32_16x16x32_bf16 v[28:31], v[142:145], v[198:201], v[28:31]
	v_mfma_f32_16x16x32_bf16 v[20:23], v[150:153], v[198:201], v[20:23]
	v_mfma_f32_16x16x32_bf16 v[12:15], v[142:145], v[206:209], v[12:15]
	v_mfma_f32_16x16x32_bf16 v[4:7], v[150:153], v[206:209], v[4:7]
	v_mfma_f32_16x16x32_bf16 v[56:59], v[162:165], v[178:181], v[56:59]
	v_mfma_f32_16x16x32_bf16 v[48:51], v[170:173], v[178:181], v[48:51]
	v_mfma_f32_16x16x32_bf16 v[40:43], v[162:165], v[186:189], v[40:43]
	v_mfma_f32_16x16x32_bf16 v[32:35], v[170:173], v[186:189], v[32:35]
	v_mfma_f32_16x16x32_bf16 v[24:27], v[162:165], v[194:197], v[24:27]
	v_mfma_f32_16x16x32_bf16 v[16:19], v[170:173], v[194:197], v[16:19]
	v_mfma_f32_16x16x32_bf16 v[8:11], v[162:165], v[202:205], v[8:11]
	v_mfma_f32_16x16x32_bf16 v[0:3], v[170:173], v[202:205], v[0:3]
	v_mfma_f32_16x16x32_bf16 v[56:59], v[166:169], v[182:185], v[56:59]
	v_mfma_f32_16x16x32_bf16 v[48:51], v[174:177], v[182:185], v[48:51]
	v_mfma_f32_16x16x32_bf16 v[40:43], v[166:169], v[190:193], v[40:43]
	v_mfma_f32_16x16x32_bf16 v[32:35], v[174:177], v[190:193], v[32:35]
	v_mfma_f32_16x16x32_bf16 v[24:27], v[166:169], v[198:201], v[24:27]
	v_mfma_f32_16x16x32_bf16 v[16:19], v[174:177], v[198:201], v[16:19]
	v_mfma_f32_16x16x32_bf16 v[8:11], v[166:169], v[206:209], v[8:11]
	v_mfma_f32_16x16x32_bf16 v[0:3], v[174:177], v[206:209], v[0:3]
	s_setprio 0
	s_barrier
	s_add_i32 s64, s64, 2
	s_add_u32 s2, s2, 0x100
	s_addc_u32 s3, s3, 0
	s_add_u32 s62, s62, 0x100
	s_addc_u32 s63, s63, 0
	s_cmp_gt_u32 s64, 13
	s_cbranch_scc0 .LBB0_1141
	s_and_b64 vcc, exec, s[40:41]
	s_cbranch_vccz .LBB0_1144
	s_barrier

; #define PG8_STAGE(bufoff, gbase, voff) do { _Pragma("unroll") for (int _i = 0; _i < 2; ++_i) \
;         __builtin_amdgcn_global_load_lds((const unsigned*)((const char*)(gbase) + (voff)[_i]), (LAS unsigned*)(lds + (bufoff) + ldsw + _i * 8192), 16, 0, 0); } while (0)
; #define PG8_LDA(dst, b, h) do { _Pragma("unroll") for (int m = 0; m < 4; ++m) _Pragma("unroll") for (int k = 0; k < 2; ++k) dst[m][k] = *(const LAS bf16x8*)(lds + PG8_SA(b, h) + aoff + m * 2048 + k * 1024); } while (0)
; #define PG8_LDB(dst, b, h) do { _Pragma("unroll") for (int n = 0; n < 2; ++n) _Pragma("unroll") for (int k = 0; k < 2; ++k) dst[n][k] = *(const LAS bf16x8*)(lds + PG8_SB(b, h) + boff + n * 2048 + k * 1024); } while (0)
; #define PG8_MMA(ai, bj, At, Bt) do { __builtin_amdgcn_s_setprio(1); _Pragma("unroll") for (int m = 0; m < 4; ++m) _Pragma("unroll") for (int n = 0; n < 2; ++n) _Pragma("unroll") for (int k = 0; k < 2; ++k) \
;         acc[ai][bj][m][n] = __builtin_amdgcn_mfma_f32_16x16x32_bf16(Bt[n][k], At[m][k], acc[ai][bj][m][n], 0, 0, 0); __builtin_amdgcn_s_setprio(0); } while (0)
; #define PG8_BAR __builtin_amdgcn_s_barrier()
; template <class Epi, bool ALIGN_EPI = true>
; __device__ __forceinline__ void gemm_phase(LAS unsigned char* lds, const Gemm g, const StaticOrder& S, const Epi& E, int wave_k) {
;     ...
;         const bool has_next = S.next(ui + 1, nxt);
;         const char* nA = has_next ? (const char*)g.A + (size_t)nxt.pm * tstepA : cA; const char* nB = has_next ? (const char*)g.Bt + (size_t)nxt.pn * tstepB : cB;
;         for (int t = 0; t < nt; t += 2) {
;             const bool last = (t == nt - 2);
;             const char* a1 = cA + (size_t)(t + 1) * kstep;
;             const char* a2 = last ? nA : cA + (size_t)(t + 2) * kstep; const char* b2 = last ? nB : cB + (size_t)(t + 2) * kstep;
;             const char* a3 = a2 + kstep; const char* b3 = b2 + kstep;
;             PG8_LDB(B0, 0, 0); PG8_LDB(B1, 0, 1); PG8_SCHED; PG8_LDA(At, 0, 0); PG8_STAGE(PG8_SA(1, 1), a1 + hstepA, voffA);
;             PG8_WAIT_V(8); PG8_WAIT_L(0); PG8_BAR; PG8_MMA(0, 0, At, B0); PG8_MMA(0, 1, At, B1); PG8_BAR; PG8_SCHED;
;             PG8_LDA(At, 0, 1); PG8_STAGE(PG8_SB(0, 0), b2, voffB); PG8_STAGE(PG8_SB(0, 1), b2 + hstepB, voffB); PG8_STAGE(PG8_SA(0, 0), a2, voffA);
;             PG8_WAIT_V(8); PG8_WAIT_L(0); PG8_BAR; PG8_MMA(1, 0, At, B0); PG8_MMA(1, 1, At, B1); PG8_BAR; PG8_SCHED;
.LBB0_1257:
	s_add_u32 s16, s24, 0x100
	s_addc_u32 s17, s25, 0
	s_add_i32 s67, 0, 0x10000
	s_cmp_eq_u32 s66, 40
	s_cselect_b32 s29, s1, s17
	s_cselect_b32 s28, s0, s16
	s_cselect_b32 s27, s35, s45
	s_cselect_b32 s26, s34, s44
	s_add_i32 s68, 0, 0x14000
	v_add_u32_e32 v154, s67, v143
	v_add_u32_e32 v158, s68, v143
	ds_read_b128 v[138:141], v154
	ds_read_b128 v[146:149], v154 offset:1024
	ds_read_b128 v[150:153], v154 offset:2048
	ds_read_b128 v[154:157], v154 offset:3072
	ds_read_b128 v[162:165], v158
	ds_read_b128 v[166:169], v158 offset:1024
	ds_read_b128 v[170:173], v158 offset:2048
	ds_read_b128 v[174:177], v158 offset:3072
	v_lshl_add_u64 v[158:159], s[24:25], 0, v[134:135]
	s_add_i32 m0, s55, 0xc000
	ds_read_b128 v[178:181], v145
	ds_read_b128 v[182:185], v145 offset:1024
	ds_read_b128 v[186:189], v145 offset:2048
	ds_read_b128 v[190:193], v145 offset:3072
	ds_read_b128 v[194:197], v145 offset:4096
	ds_read_b128 v[198:201], v145 offset:5120
	ds_read_b128 v[202:205], v145 offset:6144
	ds_read_b128 v[206:209], v145 offset:7168
	global_load_lds_dwordx4 v[158:159], off
	v_lshl_add_u64 v[158:159], s[24:25], 0, v[136:137]
	s_add_i32 m0, s55, 0xe000
	s_nop 0
	global_load_lds_dwordx4 v[158:159], off
	s_waitcnt vmcnt(8) lgkmcnt(0)
	s_barrier
	s_setprio 1
	v_mfma_f32_16x16x32_bf16 v[124:127], v[138:141], v[178:181], v[124:127]
	v_mfma_f32_16x16x32_bf16 v[120:123], v[150:153], v[178:181], v[120:123]
	v_mfma_f32_16x16x32_bf16 v[108:111], v[138:141], v[186:189], v[108:111]
	v_mfma_f32_16x16x32_bf16 v[104:107], v[150:153], v[186:189], v[104:107]
	v_mfma_f32_16x16x32_bf16 v[92:95], v[138:141], v[194:197], v[92:95]
	v_mfma_f32_16x16x32_bf16 v[88:91], v[150:153], v[194:197], v[88:91]
	v_mfma_f32_16x16x32_bf16 v[76:79], v[138:141], v[202:205], v[76:79]
	v_mfma_f32_16x16x32_bf16 v[72:75], v[150:153], v[202:205], v[72:75]
	v_mfma_f32_16x16x32_bf16 v[124:127], v[146:149], v[182:185], v[124:127]
	v_mfma_f32_16x16x32_bf16 v[120:123], v[154:157], v[182:185], v[120:123]
	v_mfma_f32_16x16x32_bf16 v[108:111], v[146:149], v[190:193], v[108:111]
	v_mfma_f32_16x16x32_bf16 v[104:107], v[154:157], v[190:193], v[104:107]
	v_mfma_f32_16x16x32_bf16 v[92:95], v[146:149], v[198:201], v[92:95]
	v_mfma_f32_16x16x32_bf16 v[88:91], v[154:157], v[198:201], v[88:91]
	v_mfma_f32_16x16x32_bf16 v[76:79], v[146:149], v[206:209], v[76:79]
	v_mfma_f32_16x16x32_bf16 v[72:75], v[154:157], v[206:209], v[72:75]
	v_mfma_f32_16x16x32_bf16 v[116:119], v[162:165], v[178:181], v[116:119]
	v_mfma_f32_16x16x32_bf16 v[112:115], v[170:173], v[178:181], v[112:115]
	v_mfma_f32_16x16x32_bf16 v[100:103], v[162:165], v[186:189], v[100:103]
	v_mfma_f32_16x16x32_bf16 v[96:99], v[170:173], v[186:189], v[96:99]
	v_mfma_f32_16x16x32_bf16 v[84:87], v[162:165], v[194:197], v[84:87]
	v_mfma_f32_16x16x32_bf16 v[80:83], v[170:173], v[194:197], v[80:83]
	v_mfma_f32_16x16x32_bf16 v[68:71], v[162:165], v[202:205], v[68:71]
	v_mfma_f32_16x16x32_bf16 v[64:67], v[170:173], v[202:205], v[64:67]
	v_mfma_f32_16x16x32_bf16 v[116:119], v[166:169], v[182:185], v[116:119]
	v_mfma_f32_16x16x32_bf16 v[112:115], v[174:177], v[182:185], v[112:115]
	v_mfma_f32_16x16x32_bf16 v[100:103], v[166:169], v[190:193], v[100:103]
	v_mfma_f32_16x16x32_bf16 v[96:99], v[174:177], v[190:193], v[96:99]
	v_mfma_f32_16x16x32_bf16 v[84:87], v[166:169], v[198:201], v[84:87]
	v_mfma_f32_16x16x32_bf16 v[80:83], v[174:177], v[198:201], v[80:83]
	v_mfma_f32_16x16x32_bf16 v[68:71], v[166:169], v[206:209], v[68:71]
	v_mfma_f32_16x16x32_bf16 v[64:67], v[174:177], v[206:209], v[64:67]
	s_setprio 0
	s_barrier
	s_add_i32 s24, s67, s54
	v_lshl_add_u64 v[158:159], s[26:27], 0, v[160:161]
	s_mov_b32 m0, s24
	ds_read_b128 v[178:181], v145 offset:16384
	ds_read_b128 v[182:185], v145 offset:17408
	ds_read_b128 v[186:189], v145 offset:18432
	ds_read_b128 v[190:193], v145 offset:19456
	ds_read_b128 v[194:197], v145 offset:20480
	ds_read_b128 v[198:201], v145 offset:21504
	ds_read_b128 v[202:205], v145 offset:22528
	ds_read_b128 v[206:209], v145 offset:23552
	global_load_lds_dwordx4 v[158:159], off
	s_add_i32 m0, s24, 0x2000
	s_add_u32 s24, s26, 0xb0000
	v_lshl_add_u64 v[210:211], s[26:27], 0, v[132:133]
	s_addc_u32 s25, s27, 0
	s_add_i32 s67, s68, s54
	global_load_lds_dwordx4 v[210:211], off
	s_mov_b32 m0, s67
	v_lshl_add_u64 v[218:219], s[28:29], 0, v[130:131]
	global_load_lds_dwordx4 v160, s[24:25]
	s_add_i32 m0, s67, 0x2000
	s_nop 0
	global_load_lds_dwordx4 v132, s[24:25]
	v_lshl_add_u64 v[212:213], s[28:29], 0, v[128:129]
	s_mov_b32 m0, s55
	s_nop 0
	global_load_lds_dwordx4 v[212:213], off
	s_mov_b32 m0, s56
	s_nop 0
	global_load_lds_dwordx4 v[218:219], off
	s_waitcnt vmcnt(8) lgkmcnt(0)
	s_barrier
; #define PG8_STAGE(bufoff, gbase, voff) do { _Pragma("unroll") for (int _i = 0; _i < 2; ++_i) \
;         __builtin_amdgcn_global_load_lds((const unsigned*)((const char*)(gbase) + (voff)[_i]), (LAS unsigned*)(lds + (bufoff) + ldsw + _i * 8192), 16, 0, 0); } while (0)
; #define PG8_LDA(dst, b, h) do { _Pragma("unroll") for (int m = 0; m < 4; ++m) _Pragma("unroll") for (int k = 0; k < 2; ++k) dst[m][k] = *(const LAS bf16x8*)(lds + PG8_SA(b, h) + aoff + m * 2048 + k * 1024); } while (0)
; #define PG8_LDB(dst, b, h) do { _Pragma("unroll") for (int n = 0; n < 2; ++n) _Pragma("unroll") for (int k = 0; k < 2; ++k) dst[n][k] = *(const LAS bf16x8*)(lds + PG8_SB(b, h) + boff + n * 2048 + k * 1024); } while (0)
; #define PG8_MMA(ai, bj, At, Bt) do { __builtin_amdgcn_s_setprio(1); _Pragma("unroll") for (int m = 0; m < 4; ++m) _Pragma("unroll") for (int n = 0; n < 2; ++n) _Pragma("unroll") for (int k = 0; k < 2; ++k) \
;         acc[ai][bj][m][n] = __builtin_amdgcn_mfma_f32_16x16x32_bf16(Bt[n][k], At[m][k], acc[ai][bj][m][n], 0, 0, 0); __builtin_amdgcn_s_setprio(0); } while (0)
; #define PG8_WAIT_V(n) asm volatile("s_waitcnt vmcnt(" #n ")" ::: "memory")
; #define PG8_WAIT_L(n) asm volatile("s_waitcnt lgkmcnt(" #n ")" ::: "memory")
; #define PG8_BAR __builtin_amdgcn_s_barrier()
; #define PG8_SCHED __builtin_amdgcn_sched_barrier(0)
; template <class Epi, bool ALIGN_EPI = true>
; __device__ __forceinline__ void gemm_phase(LAS unsigned char* lds, const Gemm g, const StaticOrder& S, const Epi& E, int wave_k) {
;     ...
;             PG8_WAIT_V(8); PG8_WAIT_L(0); PG8_BAR; PG8_MMA(1, 0, At, B0); PG8_MMA(1, 1, At, B1); PG8_BAR; PG8_SCHED;
;             PG8_LDB(B0, 1, 0); PG8_LDB(B1, 1, 1); PG8_SCHED; PG8_LDA(At, 1, 0); PG8_STAGE(PG8_SA(0, 1), a2 + hstepA, voffA);
;             PG8_WAIT_V(8); PG8_WAIT_L(0); PG8_BAR; PG8_MMA(0, 0, At, B0); PG8_MMA(0, 1, At, B1); PG8_BAR; PG8_SCHED;
	s_setprio 1
	v_mfma_f32_16x16x32_bf16 v[60:63], v[138:141], v[178:181], v[60:63]
	v_mfma_f32_16x16x32_bf16 v[56:59], v[150:153], v[178:181], v[56:59]
	v_mfma_f32_16x16x32_bf16 v[44:47], v[138:141], v[186:189], v[44:47]
	v_mfma_f32_16x16x32_bf16 v[40:43], v[150:153], v[186:189], v[40:43]
	v_mfma_f32_16x16x32_bf16 v[28:31], v[138:141], v[194:197], v[28:31]
	v_mfma_f32_16x16x32_bf16 v[24:27], v[150:153], v[194:197], v[24:27]
	v_mfma_f32_16x16x32_bf16 v[12:15], v[138:141], v[202:205], v[12:15]
	v_mfma_f32_16x16x32_bf16 v[8:11], v[150:153], v[202:205], v[8:11]
	v_mfma_f32_16x16x32_bf16 v[60:63], v[146:149], v[182:185], v[60:63]
	v_mfma_f32_16x16x32_bf16 v[56:59], v[154:157], v[182:185], v[56:59]
	v_mfma_f32_16x16x32_bf16 v[44:47], v[146:149], v[190:193], v[44:47]
	v_mfma_f32_16x16x32_bf16 v[40:43], v[154:157], v[190:193], v[40:43]
	v_mfma_f32_16x16x32_bf16 v[28:31], v[146:149], v[198:201], v[28:31]
	v_mfma_f32_16x16x32_bf16 v[24:27], v[154:157], v[198:201], v[24:27]
	v_mfma_f32_16x16x32_bf16 v[12:15], v[146:149], v[206:209], v[12:15]
	v_mfma_f32_16x16x32_bf16 v[8:11], v[154:157], v[206:209], v[8:11]
	v_mfma_f32_16x16x32_bf16 v[52:55], v[162:165], v[178:181], v[52:55]
	v_mfma_f32_16x16x32_bf16 v[48:51], v[170:173], v[178:181], v[48:51]
	v_mfma_f32_16x16x32_bf16 v[36:39], v[162:165], v[186:189], v[36:39]
	v_mfma_f32_16x16x32_bf16 v[32:35], v[170:173], v[186:189], v[32:35]
	v_mfma_f32_16x16x32_bf16 v[20:23], v[162:165], v[194:197], v[20:23]
	v_mfma_f32_16x16x32_bf16 v[16:19], v[170:173], v[194:197], v[16:19]
	v_mfma_f32_16x16x32_bf16 v[4:7], v[162:165], v[202:205], v[4:7]
	v_mfma_f32_16x16x32_bf16 v[0:3], v[170:173], v[202:205], v[0:3]
	v_mfma_f32_16x16x32_bf16 v[52:55], v[166:169], v[182:185], v[52:55]
	v_mfma_f32_16x16x32_bf16 v[48:51], v[174:177], v[182:185], v[48:51]
	v_mfma_f32_16x16x32_bf16 v[36:39], v[166:169], v[190:193], v[36:39]
	v_mfma_f32_16x16x32_bf16 v[32:35], v[174:177], v[190:193], v[32:35]
	v_mfma_f32_16x16x32_bf16 v[20:23], v[166:169], v[198:201], v[20:23]
	v_mfma_f32_16x16x32_bf16 v[16:19], v[174:177], v[198:201], v[16:19]
	v_mfma_f32_16x16x32_bf16 v[4:7], v[166:169], v[206:209], v[4:7]
	v_mfma_f32_16x16x32_bf16 v[0:3], v[174:177], v[206:209], v[0:3]
	s_setprio 0
	s_barrier
	s_add_i32 s67, 0, 0x18000
	s_add_i32 s68, 0, 0x1c000
	v_add_u32_e32 v154, s67, v143
	v_add_u32_e32 v174, s68, v143
	ds_read_b128 v[138:141], v154
	ds_read_b128 v[146:149], v154 offset:1024
	ds_read_b128 v[150:153], v154 offset:2048
	ds_read_b128 v[154:157], v154 offset:3072
	ds_read_b128 v[162:165], v174
	ds_read_b128 v[166:169], v174 offset:1024
	ds_read_b128 v[170:173], v174 offset:2048
	ds_read_b128 v[174:177], v174 offset:3072
	s_add_u32 s24, s28, 0xb0000
	s_addc_u32 s25, s29, 0
	s_mov_b32 m0, s57
	ds_read_b128 v[178:181], v145 offset:32768
	ds_read_b128 v[182:185], v145 offset:33792
	ds_read_b128 v[186:189], v145 offset:34816
	ds_read_b128 v[190:193], v145 offset:35840
	ds_read_b128 v[194:197], v145 offset:36864
	ds_read_b128 v[198:201], v145 offset:37888
	ds_read_b128 v[202:205], v145 offset:38912
	ds_read_b128 v[206:209], v145 offset:39936
	global_load_lds_dwordx4 v128, s[24:25]
	s_mov_b32 m0, s58
	s_nop 0
	global_load_lds_dwordx4 v130, s[24:25]
	s_waitcnt vmcnt(8) lgkmcnt(0)
	s_barrier
	s_setprio 1
	v_mfma_f32_16x16x32_bf16 v[124:127], v[138:141], v[178:181], v[124:127]
	v_mfma_f32_16x16x32_bf16 v[120:123], v[150:153], v[178:181], v[120:123]
	v_mfma_f32_16x16x32_bf16 v[108:111], v[138:141], v[186:189], v[108:111]
	v_mfma_f32_16x16x32_bf16 v[104:107], v[150:153], v[186:189], v[104:107]
	v_mfma_f32_16x16x32_bf16 v[92:95], v[138:141], v[194:197], v[92:95]
	v_mfma_f32_16x16x32_bf16 v[88:91], v[150:153], v[194:197], v[88:91]
	v_mfma_f32_16x16x32_bf16 v[76:79], v[138:141], v[202:205], v[76:79]
	v_mfma_f32_16x16x32_bf16 v[72:75], v[150:153], v[202:205], v[72:75]
	v_mfma_f32_16x16x32_bf16 v[124:127], v[146:149], v[182:185], v[124:127]
	v_mfma_f32_16x16x32_bf16 v[120:123], v[154:157], v[182:185], v[120:123]
	v_mfma_f32_16x16x32_bf16 v[108:111], v[146:149], v[190:193], v[108:111]
	v_mfma_f32_16x16x32_bf16 v[104:107], v[154:157], v[190:193], v[104:107]
	v_mfma_f32_16x16x32_bf16 v[92:95], v[146:149], v[198:201], v[92:95]
	v_mfma_f32_16x16x32_bf16 v[88:91], v[154:157], v[198:201], v[88:91]
	v_mfma_f32_16x16x32_bf16 v[76:79], v[146:149], v[206:209], v[76:79]
	v_mfma_f32_16x16x32_bf16 v[72:75], v[154:157], v[206:209], v[72:75]
	v_mfma_f32_16x16x32_bf16 v[116:119], v[162:165], v[178:181], v[116:119]
	v_mfma_f32_16x16x32_bf16 v[112:115], v[170:173], v[178:181], v[112:115]
	v_mfma_f32_16x16x32_bf16 v[100:103], v[162:165], v[186:189], v[100:103]
	v_mfma_f32_16x16x32_bf16 v[96:99], v[170:173], v[186:189], v[96:99]
	v_mfma_f32_16x16x32_bf16 v[84:87], v[162:165], v[194:197], v[84:87]
	v_mfma_f32_16x16x32_bf16 v[80:83], v[170:173], v[194:197], v[80:83]
	v_mfma_f32_16x16x32_bf16 v[68:71], v[162:165], v[202:205], v[68:71]
	v_mfma_f32_16x16x32_bf16 v[64:67], v[170:173], v[202:205], v[64:67]
	v_mfma_f32_16x16x32_bf16 v[116:119], v[166:169], v[182:185], v[116:119]
	v_mfma_f32_16x16x32_bf16 v[112:115], v[174:177], v[182:185], v[112:115]
	v_mfma_f32_16x16x32_bf16 v[100:103], v[166:169], v[190:193], v[100:103]
	v_mfma_f32_16x16x32_bf16 v[96:99], v[174:177], v[190:193], v[96:99]
	v_mfma_f32_16x16x32_bf16 v[84:87], v[166:169], v[198:201], v[84:87]
	v_mfma_f32_16x16x32_bf16 v[80:83], v[174:177], v[198:201], v[80:83]
	v_mfma_f32_16x16x32_bf16 v[68:71], v[166:169], v[206:209], v[68:71]
	v_mfma_f32_16x16x32_bf16 v[64:67], v[174:177], v[206:209], v[64:67]
	s_setprio 0
	s_barrier
; #define PG8_STAGE(bufoff, gbase, voff) do { _Pragma("unroll") for (int _i = 0; _i < 2; ++_i) \
;         __builtin_amdgcn_global_load_lds((const unsigned*)((const char*)(gbase) + (voff)[_i]), (LAS unsigned*)(lds + (bufoff) + ldsw + _i * 8192), 16, 0, 0); } while (0)
; #define PG8_LDA(dst, b, h) do { _Pragma("unroll") for (int m = 0; m < 4; ++m) _Pragma("unroll") for (int k = 0; k < 2; ++k) dst[m][k] = *(const LAS bf16x8*)(lds + PG8_SA(b, h) + aoff + m * 2048 + k * 1024); } while (0)
; #define PG8_MMA(ai, bj, At, Bt) do { __builtin_amdgcn_s_setprio(1); _Pragma("unroll") for (int m = 0; m < 4; ++m) _Pragma("unroll") for (int n = 0; n < 2; ++n) _Pragma("unroll") for (int k = 0; k < 2; ++k) \
;         acc[ai][bj][m][n] = __builtin_amdgcn_mfma_f32_16x16x32_bf16(Bt[n][k], At[m][k], acc[ai][bj][m][n], 0, 0, 0); __builtin_amdgcn_s_setprio(0); } while (0)
; #define PG8_WAIT_V(n) asm volatile("s_waitcnt vmcnt(" #n ")" ::: "memory")
; #define PG8_WAIT_L(n) asm volatile("s_waitcnt lgkmcnt(" #n ")" ::: "memory")
; #define PG8_BAR __builtin_amdgcn_s_barrier()
; #define PG8_SCHED __builtin_amdgcn_sched_barrier(0)
; template <class Epi, bool ALIGN_EPI = true>
; __device__ __forceinline__ void gemm_phase(LAS unsigned char* lds, const Gemm g, const StaticOrder& S, const Epi& E, int wave_k) {
;     ...
;             PG8_LDA(At, 1, 1); PG8_STAGE(PG8_SB(1, 0), b3, voffB); PG8_STAGE(PG8_SB(1, 1), b3 + hstepB, voffB); PG8_STAGE(PG8_SA(1, 0), a3, voffA);
;             PG8_WAIT_V(8); PG8_WAIT_L(0); PG8_BAR; PG8_MMA(1, 0, At, B0); PG8_MMA(1, 1, At, B1); PG8_BAR; PG8_SCHED;
;         }
;         if constexpr (ALIGN_EPI) { if (wr == 0) PG8_BAR; }
	s_add_i32 s24, s67, s54
	v_lshl_add_u64 v[158:159], v[158:159], 0, s[22:23]
	s_mov_b32 m0, s24
	ds_read_b128 v[178:181], v145 offset:49152
	ds_read_b128 v[182:185], v145 offset:50176
	ds_read_b128 v[186:189], v145 offset:51200
	ds_read_b128 v[190:193], v145 offset:52224
	ds_read_b128 v[194:197], v145 offset:53248
	ds_read_b128 v[198:201], v145 offset:54272
	ds_read_b128 v[202:205], v145 offset:55296
	ds_read_b128 v[206:209], v145 offset:56320
	global_load_lds_dwordx4 v[158:159], off
	s_add_i32 m0, s24, 0x2000
	s_add_u32 s24, s26, 0xb0080
	v_lshl_add_u64 v[158:159], v[210:211], 0, s[22:23]
	s_addc_u32 s25, s27, 0
	s_add_i32 s26, s68, s54
	global_load_lds_dwordx4 v[158:159], off
	s_mov_b32 m0, s26
	s_nop 0
	global_load_lds_dwordx4 v160, s[24:25]
	s_add_i32 m0, s26, 0x2000
	s_nop 0
	global_load_lds_dwordx4 v132, s[24:25]
	v_lshl_add_u64 v[158:159], v[212:213], 0, s[22:23]
	s_mov_b32 m0, s50
	s_nop 0
	global_load_lds_dwordx4 v[158:159], off
	v_lshl_add_u64 v[158:159], v[218:219], 0, s[22:23]
	s_mov_b32 m0, s51
	s_nop 0
	global_load_lds_dwordx4 v[158:159], off
	s_waitcnt vmcnt(8) lgkmcnt(0)
	s_barrier
	s_setprio 1
	v_mfma_f32_16x16x32_bf16 v[60:63], v[138:141], v[178:181], v[60:63]
	v_mfma_f32_16x16x32_bf16 v[56:59], v[150:153], v[178:181], v[56:59]
	v_mfma_f32_16x16x32_bf16 v[44:47], v[138:141], v[186:189], v[44:47]
	v_mfma_f32_16x16x32_bf16 v[40:43], v[150:153], v[186:189], v[40:43]
	v_mfma_f32_16x16x32_bf16 v[28:31], v[138:141], v[194:197], v[28:31]
	v_mfma_f32_16x16x32_bf16 v[24:27], v[150:153], v[194:197], v[24:27]
	v_mfma_f32_16x16x32_bf16 v[12:15], v[138:141], v[202:205], v[12:15]
	v_mfma_f32_16x16x32_bf16 v[8:11], v[150:153], v[202:205], v[8:11]
	v_mfma_f32_16x16x32_bf16 v[60:63], v[146:149], v[182:185], v[60:63]
	v_mfma_f32_16x16x32_bf16 v[56:59], v[154:157], v[182:185], v[56:59]
	v_mfma_f32_16x16x32_bf16 v[44:47], v[146:149], v[190:193], v[44:47]
	v_mfma_f32_16x16x32_bf16 v[40:43], v[154:157], v[190:193], v[40:43]
	v_mfma_f32_16x16x32_bf16 v[28:31], v[146:149], v[198:201], v[28:31]
	v_mfma_f32_16x16x32_bf16 v[24:27], v[154:157], v[198:201], v[24:27]
	v_mfma_f32_16x16x32_bf16 v[12:15], v[146:149], v[206:209], v[12:15]
	v_mfma_f32_16x16x32_bf16 v[8:11], v[154:157], v[206:209], v[8:11]
	v_mfma_f32_16x16x32_bf16 v[52:55], v[162:165], v[178:181], v[52:55]
	v_mfma_f32_16x16x32_bf16 v[48:51], v[170:173], v[178:181], v[48:51]
	v_mfma_f32_16x16x32_bf16 v[36:39], v[162:165], v[186:189], v[36:39]
	v_mfma_f32_16x16x32_bf16 v[32:35], v[170:173], v[186:189], v[32:35]
	v_mfma_f32_16x16x32_bf16 v[20:23], v[162:165], v[194:197], v[20:23]
	v_mfma_f32_16x16x32_bf16 v[16:19], v[170:173], v[194:197], v[16:19]
	v_mfma_f32_16x16x32_bf16 v[4:7], v[162:165], v[202:205], v[4:7]
	v_mfma_f32_16x16x32_bf16 v[0:3], v[170:173], v[202:205], v[0:3]
	v_mfma_f32_16x16x32_bf16 v[52:55], v[166:169], v[182:185], v[52:55]
	v_mfma_f32_16x16x32_bf16 v[48:51], v[174:177], v[182:185], v[48:51]
	v_mfma_f32_16x16x32_bf16 v[36:39], v[166:169], v[190:193], v[36:39]
	v_mfma_f32_16x16x32_bf16 v[32:35], v[174:177], v[190:193], v[32:35]
	v_mfma_f32_16x16x32_bf16 v[20:23], v[166:169], v[198:201], v[20:23]
	v_mfma_f32_16x16x32_bf16 v[16:19], v[174:177], v[198:201], v[16:19]
	v_mfma_f32_16x16x32_bf16 v[4:7], v[166:169], v[206:209], v[4:7]
	v_mfma_f32_16x16x32_bf16 v[0:3], v[174:177], v[206:209], v[0:3]
	s_setprio 0
	s_barrier
	s_add_i32 s66, s66, 2
	s_add_u32 s44, s44, 0x100
	s_addc_u32 s45, s45, 0
	s_cmp_gt_u32 s66, 41
	s_mov_b64 s[24:25], s[16:17]
	s_cbranch_scc0 .LBB0_1257
	s_and_b64 vcc, exec, s[20:21]
	s_cbranch_vccz .LBB0_1260
	s_barrier
